# code placement: MFMA segment heads of all GEMM K-loops padded to an 8-byte phase (16 s_nop pads placed at the start of load segments)
# speedup vs baseline: 1.0015x; 1.0015x over previous
.LBB0_200:
	s_ashr_i32 s23, s22, 31
	s_lshl_b64 s[6:7], s[22:23], 20
	s_add_u32 s6, s29, s6
	s_addc_u32 s7, s34, s7
	s_ashr_i32 s25, s24, 31
	s_lshl_b64 s[36:37], s[24:25], 1
	s_add_u32 s6, s6, s36
	s_addc_u32 s7, s7, s37
	s_and_b64 s[44:45], s[52:53], exec
	s_cselect_b32 s23, s7, s43
	s_cselect_b32 s25, s6, s42
	s_ashr_i32 s27, s26, 31
	s_lshl_b64 s[44:45], s[26:27], 20
	s_add_u32 s27, s35, s44
	s_addc_u32 s41, s54, s45
	s_add_u32 s36, s27, s36
	s_addc_u32 s37, s41, s37
	s_and_b64 s[44:45], s[52:53], exec
	s_cselect_b32 s27, s37, s51
	s_cselect_b32 s41, s36, s50
	s_add_i32 s44, s33, -2
	s_add_u32 s42, s42, 0x80080
	s_addc_u32 s43, s43, 0
	s_add_u32 s45, s50, 0x100
	s_addc_u32 s58, s51, 0
	s_mov_b32 s50, 0
	v_add_u32_e32 v253, 0x10000, v147
	s_add_i32 s59, s50, 2
	s_add_u32 s51, s42, 0xfff80080
	s_addc_u32 s52, s43, -1
	s_add_i32 s70, 0, 0x10000
	s_cmp_eq_u32 s44, s50
	s_cselect_b32 s53, s23, s52
	s_cselect_b32 s52, s25, s51
	s_cselect_b32 s51, s27, s58
	s_cselect_b32 s50, s41, s45
	s_add_i32 s74, 0, 0x14000
	ds_read_b128 v[150:153], v253
	ds_read_b128 v[154:157], v253 offset:1024
	ds_read_b128 v[158:161], v253 offset:2048
	ds_read_b128 v[162:165], v253 offset:3072
	ds_read_b128 v[166:169], v253 offset:16384
	ds_read_b128 v[170:173], v253 offset:17408
	ds_read_b128 v[174:177], v253 offset:18432
	ds_read_b128 v[178:181], v253 offset:19456
	s_add_i32 m0, s31, 0xc000
	ds_read_b128 v[182:185], v149
	ds_read_b128 v[186:189], v149 offset:1024
	ds_read_b128 v[190:193], v149 offset:2048
	ds_read_b128 v[204:207], v149 offset:3072
	ds_read_b128 v[208:211], v149 offset:4096
	ds_read_b128 v[212:215], v149 offset:5120
	ds_read_b128 v[216:219], v149 offset:6144
	ds_read_b128 v[220:223], v149 offset:7168
	global_load_lds_dwordx4 v140, s[42:43]
	s_add_i32 m0, s31, 0xe000
	s_nop 0
	global_load_lds_dwordx4 v142, s[42:43]
	s_waitcnt vmcnt(8)
	s_waitcnt lgkmcnt(0)
	s_barrier
	s_setprio 1
	s_waitcnt lgkmcnt(0)
	v_mfma_f32_16x16x32_bf16 v[126:129], v[150:153], v[182:185], 0
	v_mfma_f32_16x16x32_bf16 v[122:125], v[158:161], v[182:185], 0
	v_mfma_f32_16x16x32_bf16 v[114:117], v[150:153], v[190:193], 0
	v_mfma_f32_16x16x32_bf16 v[106:109], v[158:161], v[190:193], 0
	v_mfma_f32_16x16x32_bf16 v[98:101], v[150:153], v[208:211], 0
	v_mfma_f32_16x16x32_bf16 v[90:93], v[158:161], v[208:211], 0
	v_mfma_f32_16x16x32_bf16 v[82:85], v[150:153], v[216:219], 0
	v_mfma_f32_16x16x32_bf16 v[74:77], v[158:161], v[216:219], 0
	v_mfma_f32_16x16x32_bf16 v[126:129], v[154:157], v[186:189], v[126:129]
	v_mfma_f32_16x16x32_bf16 v[122:125], v[162:165], v[186:189], v[122:125]
	v_mfma_f32_16x16x32_bf16 v[114:117], v[154:157], v[204:207], v[114:117]
	v_mfma_f32_16x16x32_bf16 v[106:109], v[162:165], v[204:207], v[106:109]
	v_mfma_f32_16x16x32_bf16 v[98:101], v[154:157], v[212:215], v[98:101]
	v_mfma_f32_16x16x32_bf16 v[90:93], v[162:165], v[212:215], v[90:93]
	v_mfma_f32_16x16x32_bf16 v[82:85], v[154:157], v[220:223], v[82:85]
	v_mfma_f32_16x16x32_bf16 v[74:77], v[162:165], v[220:223], v[74:77]
	s_setprio 0
	s_setprio 1
	v_mfma_f32_16x16x32_bf16 v[118:121], v[166:169], v[182:185], 0
	v_mfma_f32_16x16x32_bf16 v[110:113], v[174:177], v[182:185], 0
	v_mfma_f32_16x16x32_bf16 v[102:105], v[166:169], v[190:193], 0
	v_mfma_f32_16x16x32_bf16 v[94:97], v[174:177], v[190:193], 0
	v_mfma_f32_16x16x32_bf16 v[86:89], v[166:169], v[208:211], 0
	v_mfma_f32_16x16x32_bf16 v[78:81], v[174:177], v[208:211], 0
	v_mfma_f32_16x16x32_bf16 v[70:73], v[166:169], v[216:219], 0
	v_mfma_f32_16x16x32_bf16 v[66:69], v[174:177], v[216:219], 0
	v_mfma_f32_16x16x32_bf16 v[118:121], v[170:173], v[186:189], v[118:121]
	v_mfma_f32_16x16x32_bf16 v[110:113], v[178:181], v[186:189], v[110:113]
	v_mfma_f32_16x16x32_bf16 v[102:105], v[170:173], v[204:207], v[102:105]
	v_mfma_f32_16x16x32_bf16 v[94:97], v[178:181], v[204:207], v[94:97]
	v_mfma_f32_16x16x32_bf16 v[86:89], v[170:173], v[212:215], v[86:89]
	v_mfma_f32_16x16x32_bf16 v[78:81], v[178:181], v[212:215], v[78:81]
	v_mfma_f32_16x16x32_bf16 v[70:73], v[170:173], v[220:223], v[70:73]
	v_mfma_f32_16x16x32_bf16 v[66:69], v[178:181], v[220:223], v[66:69]
	s_setprio 0
	s_barrier
	s_add_i32 s70, s70, s55
	s_mov_b32 m0, s70
	ds_read_b128 v[182:185], v149 offset:16384
	ds_read_b128 v[186:189], v149 offset:17408
	ds_read_b128 v[190:193], v149 offset:18432
	ds_read_b128 v[204:207], v149 offset:19456
	ds_read_b128 v[208:211], v149 offset:20480
	ds_read_b128 v[212:215], v149 offset:21504
	ds_read_b128 v[216:219], v149 offset:22528
	ds_read_b128 v[220:223], v149 offset:23552
	global_load_lds_dwordx4 v0, s[50:51]
	s_add_i32 m0, s70, 0x2000
	s_add_u32 s70, s50, 0x80000
	s_addc_u32 s71, s51, 0
	s_add_i32 s74, s74, s55
	global_load_lds_dwordx4 v134, s[50:51]
	s_mov_b32 m0, s74
	s_nop 0
	global_load_lds_dwordx4 v0, s[70:71]
	s_add_i32 m0, s74, 0x2000
	s_nop 0
	global_load_lds_dwordx4 v134, s[70:71]
	s_mov_b32 m0, s31
	s_nop 0
	global_load_lds_dwordx4 v130, s[52:53]
	s_mov_b32 m0, s39
	s_nop 0
	global_load_lds_dwordx4 v132, s[52:53]
	s_waitcnt vmcnt(8)
	s_waitcnt lgkmcnt(0)
	s_barrier
	s_setprio 1
	s_waitcnt lgkmcnt(0)
	v_mfma_f32_16x16x32_bf16 v[62:65], v[150:153], v[182:185], 0
	v_mfma_f32_16x16x32_bf16 v[58:61], v[158:161], v[182:185], 0
	v_mfma_f32_16x16x32_bf16 v[50:53], v[150:153], v[190:193], 0
	v_mfma_f32_16x16x32_bf16 v[42:45], v[158:161], v[190:193], 0
	v_mfma_f32_16x16x32_bf16 v[34:37], v[150:153], v[208:211], 0
	v_mfma_f32_16x16x32_bf16 v[26:29], v[158:161], v[208:211], 0
	v_mfma_f32_16x16x32_bf16 v[18:21], v[150:153], v[216:219], 0
	v_mfma_f32_16x16x32_bf16 v[10:13], v[158:161], v[216:219], 0
	v_mfma_f32_16x16x32_bf16 v[62:65], v[154:157], v[186:189], v[62:65]
	v_mfma_f32_16x16x32_bf16 v[58:61], v[162:165], v[186:189], v[58:61]
	v_mfma_f32_16x16x32_bf16 v[50:53], v[154:157], v[204:207], v[50:53]
	v_mfma_f32_16x16x32_bf16 v[42:45], v[162:165], v[204:207], v[42:45]
	v_mfma_f32_16x16x32_bf16 v[34:37], v[154:157], v[212:215], v[34:37]
	v_mfma_f32_16x16x32_bf16 v[26:29], v[162:165], v[212:215], v[26:29]
	v_mfma_f32_16x16x32_bf16 v[18:21], v[154:157], v[220:223], v[18:21]
	v_mfma_f32_16x16x32_bf16 v[10:13], v[162:165], v[220:223], v[10:13]
	s_setprio 0
	s_setprio 1
	v_mfma_f32_16x16x32_bf16 v[54:57], v[166:169], v[182:185], 0
	v_mfma_f32_16x16x32_bf16 v[46:49], v[174:177], v[182:185], 0
	v_mfma_f32_16x16x32_bf16 v[38:41], v[166:169], v[190:193], 0
	v_mfma_f32_16x16x32_bf16 v[30:33], v[174:177], v[190:193], 0
	v_mfma_f32_16x16x32_bf16 v[22:25], v[166:169], v[208:211], 0
	v_mfma_f32_16x16x32_bf16 v[14:17], v[174:177], v[208:211], 0
	v_mfma_f32_16x16x32_bf16 v[6:9], v[166:169], v[216:219], 0
	v_mfma_f32_16x16x32_bf16 v[2:5], v[174:177], v[216:219], 0
	v_mfma_f32_16x16x32_bf16 v[54:57], v[170:173], v[186:189], v[54:57]
	v_mfma_f32_16x16x32_bf16 v[46:49], v[178:181], v[186:189], v[46:49]
	v_mfma_f32_16x16x32_bf16 v[38:41], v[170:173], v[204:207], v[38:41]
	v_mfma_f32_16x16x32_bf16 v[30:33], v[178:181], v[204:207], v[30:33]
	v_mfma_f32_16x16x32_bf16 v[22:25], v[170:173], v[212:215], v[22:25]
	v_mfma_f32_16x16x32_bf16 v[14:17], v[178:181], v[212:215], v[14:17]
	v_mfma_f32_16x16x32_bf16 v[6:9], v[170:173], v[220:223], v[6:9]
	v_mfma_f32_16x16x32_bf16 v[2:5], v[178:181], v[220:223], v[2:5]
	s_setprio 0
	s_barrier
	s_nop 0
	s_add_i32 s70, 0, 0x18000
	s_add_i32 s71, 0, 0x1c000
	ds_read_b128 v[150:153], v253 offset:32768
	ds_read_b128 v[154:157], v253 offset:33792
	ds_read_b128 v[158:161], v253 offset:34816
	ds_read_b128 v[162:165], v253 offset:35840
	ds_read_b128 v[166:169], v253 offset:49152
	ds_read_b128 v[170:173], v253 offset:50176
	ds_read_b128 v[174:177], v253 offset:51200
	ds_read_b128 v[178:181], v253 offset:52224
	s_add_u32 s52, s52, 0x80000
	s_addc_u32 s53, s53, 0
	s_mov_b32 m0, s56
	ds_read_b128 v[182:185], v149 offset:32768
	ds_read_b128 v[186:189], v149 offset:33792
	ds_read_b128 v[190:193], v149 offset:34816
	ds_read_b128 v[204:207], v149 offset:35840
	ds_read_b128 v[208:211], v149 offset:36864
	ds_read_b128 v[212:215], v149 offset:37888
	ds_read_b128 v[216:219], v149 offset:38912
	ds_read_b128 v[220:223], v149 offset:39936
	global_load_lds_dwordx4 v130, s[52:53]
	s_mov_b32 m0, s57
	s_nop 0
	global_load_lds_dwordx4 v132, s[52:53]
	s_waitcnt vmcnt(8)
	s_waitcnt lgkmcnt(0)
	s_barrier
	s_setprio 1
	s_waitcnt lgkmcnt(0)
	v_mfma_f32_16x16x32_bf16 v[126:129], v[150:153], v[182:185], v[126:129]
	v_mfma_f32_16x16x32_bf16 v[122:125], v[158:161], v[182:185], v[122:125]
	v_mfma_f32_16x16x32_bf16 v[114:117], v[150:153], v[190:193], v[114:117]
	v_mfma_f32_16x16x32_bf16 v[106:109], v[158:161], v[190:193], v[106:109]
	v_mfma_f32_16x16x32_bf16 v[98:101], v[150:153], v[208:211], v[98:101]
	v_mfma_f32_16x16x32_bf16 v[90:93], v[158:161], v[208:211], v[90:93]
	v_mfma_f32_16x16x32_bf16 v[82:85], v[150:153], v[216:219], v[82:85]
	v_mfma_f32_16x16x32_bf16 v[74:77], v[158:161], v[216:219], v[74:77]
	v_mfma_f32_16x16x32_bf16 v[126:129], v[154:157], v[186:189], v[126:129]
	v_mfma_f32_16x16x32_bf16 v[122:125], v[162:165], v[186:189], v[122:125]
	v_mfma_f32_16x16x32_bf16 v[114:117], v[154:157], v[204:207], v[114:117]
	v_mfma_f32_16x16x32_bf16 v[106:109], v[162:165], v[204:207], v[106:109]
	v_mfma_f32_16x16x32_bf16 v[98:101], v[154:157], v[212:215], v[98:101]
	v_mfma_f32_16x16x32_bf16 v[90:93], v[162:165], v[212:215], v[90:93]
	v_mfma_f32_16x16x32_bf16 v[82:85], v[154:157], v[220:223], v[82:85]
	v_mfma_f32_16x16x32_bf16 v[74:77], v[162:165], v[220:223], v[74:77]
	s_setprio 0
	s_setprio 1
	v_mfma_f32_16x16x32_bf16 v[118:121], v[166:169], v[182:185], v[118:121]
	v_mfma_f32_16x16x32_bf16 v[110:113], v[174:177], v[182:185], v[110:113]
	v_mfma_f32_16x16x32_bf16 v[102:105], v[166:169], v[190:193], v[102:105]
	v_mfma_f32_16x16x32_bf16 v[94:97], v[174:177], v[190:193], v[94:97]
	v_mfma_f32_16x16x32_bf16 v[86:89], v[166:169], v[208:211], v[86:89]
	v_mfma_f32_16x16x32_bf16 v[78:81], v[174:177], v[208:211], v[78:81]
	v_mfma_f32_16x16x32_bf16 v[70:73], v[166:169], v[216:219], v[70:73]
	v_mfma_f32_16x16x32_bf16 v[66:69], v[174:177], v[216:219], v[66:69]
	v_mfma_f32_16x16x32_bf16 v[118:121], v[170:173], v[186:189], v[118:121]
	v_mfma_f32_16x16x32_bf16 v[110:113], v[178:181], v[186:189], v[110:113]
	v_mfma_f32_16x16x32_bf16 v[102:105], v[170:173], v[204:207], v[102:105]
	v_mfma_f32_16x16x32_bf16 v[94:97], v[178:181], v[204:207], v[94:97]
	v_mfma_f32_16x16x32_bf16 v[86:89], v[170:173], v[212:215], v[86:89]
	v_mfma_f32_16x16x32_bf16 v[78:81], v[178:181], v[212:215], v[78:81]
	v_mfma_f32_16x16x32_bf16 v[70:73], v[170:173], v[220:223], v[70:73]
	v_mfma_f32_16x16x32_bf16 v[66:69], v[178:181], v[220:223], v[66:69]
	s_setprio 0
	s_barrier
	s_add_u32 s100, s52, 0xfff80080
	s_addc_u32 s101, s53, -1
	s_add_u32 s98, s50, 0x80
	s_addc_u32 s99, s51, 0
	s_add_i32 s52, s70, s55
	s_mov_b32 m0, s52
	ds_read_b128 v[182:185], v149 offset:49152
	ds_read_b128 v[186:189], v149 offset:50176
	ds_read_b128 v[190:193], v149 offset:51200
	ds_read_b128 v[204:207], v149 offset:52224
	ds_read_b128 v[208:211], v149 offset:53248
	ds_read_b128 v[212:215], v149 offset:54272
	ds_read_b128 v[216:219], v149 offset:55296
	ds_read_b128 v[220:223], v149 offset:56320
	global_load_lds_dwordx4 v0, s[98:99]
	s_add_i32 m0, s52, 0x2000
	s_add_u32 s50, s50, 0x80080
	s_addc_u32 s51, s51, 0
	s_add_i32 s52, s71, s55
	global_load_lds_dwordx4 v134, s[98:99]
	s_mov_b32 m0, s52
	s_nop 0
	global_load_lds_dwordx4 v0, s[50:51]
	s_add_i32 m0, s52, 0x2000
	s_nop 0
	global_load_lds_dwordx4 v134, s[50:51]
	s_mov_b32 m0, s61
	s_nop 0
	global_load_lds_dwordx4 v130, s[100:101]
	s_mov_b32 m0, s62
	s_nop 0
	global_load_lds_dwordx4 v132, s[100:101]
	s_waitcnt vmcnt(8)
	s_waitcnt lgkmcnt(0)
	s_barrier
	s_setprio 1
	s_waitcnt lgkmcnt(0)
	v_mfma_f32_16x16x32_bf16 v[62:65], v[150:153], v[182:185], v[62:65]
	v_mfma_f32_16x16x32_bf16 v[58:61], v[158:161], v[182:185], v[58:61]
	v_mfma_f32_16x16x32_bf16 v[50:53], v[150:153], v[190:193], v[50:53]
	v_mfma_f32_16x16x32_bf16 v[42:45], v[158:161], v[190:193], v[42:45]
	v_mfma_f32_16x16x32_bf16 v[34:37], v[150:153], v[208:211], v[34:37]
	v_mfma_f32_16x16x32_bf16 v[26:29], v[158:161], v[208:211], v[26:29]
	v_mfma_f32_16x16x32_bf16 v[18:21], v[150:153], v[216:219], v[18:21]
	v_mfma_f32_16x16x32_bf16 v[10:13], v[158:161], v[216:219], v[10:13]
	v_mfma_f32_16x16x32_bf16 v[62:65], v[154:157], v[186:189], v[62:65]
	v_mfma_f32_16x16x32_bf16 v[58:61], v[162:165], v[186:189], v[58:61]
	v_mfma_f32_16x16x32_bf16 v[50:53], v[154:157], v[204:207], v[50:53]
	v_mfma_f32_16x16x32_bf16 v[42:45], v[162:165], v[204:207], v[42:45]
	v_mfma_f32_16x16x32_bf16 v[34:37], v[154:157], v[212:215], v[34:37]
	v_mfma_f32_16x16x32_bf16 v[26:29], v[162:165], v[212:215], v[26:29]
	v_mfma_f32_16x16x32_bf16 v[18:21], v[154:157], v[220:223], v[18:21]
	v_mfma_f32_16x16x32_bf16 v[10:13], v[162:165], v[220:223], v[10:13]
	s_setprio 0
	s_setprio 1
	v_mfma_f32_16x16x32_bf16 v[54:57], v[166:169], v[182:185], v[54:57]
	v_mfma_f32_16x16x32_bf16 v[46:49], v[174:177], v[182:185], v[46:49]
	v_mfma_f32_16x16x32_bf16 v[38:41], v[166:169], v[190:193], v[38:41]
	v_mfma_f32_16x16x32_bf16 v[30:33], v[174:177], v[190:193], v[30:33]
	v_mfma_f32_16x16x32_bf16 v[22:25], v[166:169], v[208:211], v[22:25]
	v_mfma_f32_16x16x32_bf16 v[14:17], v[174:177], v[208:211], v[14:17]
	v_mfma_f32_16x16x32_bf16 v[6:9], v[166:169], v[216:219], v[6:9]
	v_mfma_f32_16x16x32_bf16 v[2:5], v[174:177], v[216:219], v[2:5]
	v_mfma_f32_16x16x32_bf16 v[54:57], v[170:173], v[186:189], v[54:57]
	v_mfma_f32_16x16x32_bf16 v[46:49], v[178:181], v[186:189], v[46:49]
	v_mfma_f32_16x16x32_bf16 v[38:41], v[170:173], v[204:207], v[38:41]
	v_mfma_f32_16x16x32_bf16 v[30:33], v[178:181], v[204:207], v[30:33]
	v_mfma_f32_16x16x32_bf16 v[22:25], v[170:173], v[212:215], v[22:25]
	v_mfma_f32_16x16x32_bf16 v[14:17], v[178:181], v[212:215], v[14:17]
	v_mfma_f32_16x16x32_bf16 v[6:9], v[170:173], v[220:223], v[6:9]
	v_mfma_f32_16x16x32_bf16 v[2:5], v[178:181], v[220:223], v[2:5]
	s_setprio 0
	s_barrier
	s_add_u32 s42, s42, 0x100
	s_addc_u32 s43, s43, 0
	s_add_u32 s45, s45, 0x100
	s_addc_u32 s58, s58, 0
	s_cmp_ge_u32 s59, s33
	s_mov_b32 s50, s59
	s_cbranch_scc0 .LBB0_201
	s_branch .Lpeel_exit_0
.LBB0_201:
	s_nop 0
	s_add_i32 s59, s50, 2
	s_add_u32 s51, s42, 0xfff80080
	s_addc_u32 s52, s43, -1
	s_add_i32 s70, 0, 0x10000
	s_cmp_eq_u32 s44, s50
	s_cselect_b32 s53, s23, s52
	s_cselect_b32 s52, s25, s51
	s_cselect_b32 s51, s27, s58
	s_cselect_b32 s50, s41, s45
	s_add_i32 s74, 0, 0x14000
	ds_read_b128 v[150:153], v253
	ds_read_b128 v[154:157], v253 offset:1024
	ds_read_b128 v[158:161], v253 offset:2048
	ds_read_b128 v[162:165], v253 offset:3072
	ds_read_b128 v[166:169], v253 offset:16384
	ds_read_b128 v[170:173], v253 offset:17408
	ds_read_b128 v[174:177], v253 offset:18432
	ds_read_b128 v[178:181], v253 offset:19456
	s_add_i32 m0, s31, 0xc000
	ds_read_b128 v[182:185], v149
	ds_read_b128 v[186:189], v149 offset:1024
	ds_read_b128 v[190:193], v149 offset:2048
	ds_read_b128 v[204:207], v149 offset:3072
	ds_read_b128 v[208:211], v149 offset:4096
	ds_read_b128 v[212:215], v149 offset:5120
	ds_read_b128 v[216:219], v149 offset:6144
	ds_read_b128 v[220:223], v149 offset:7168
	global_load_lds_dwordx4 v140, s[42:43]
	s_add_i32 m0, s31, 0xe000
	s_nop 0
	global_load_lds_dwordx4 v142, s[42:43]
	s_waitcnt vmcnt(8)
	s_waitcnt lgkmcnt(0)
	s_barrier
	s_setprio 1
	s_waitcnt lgkmcnt(0)
	v_mfma_f32_16x16x32_bf16 v[126:129], v[150:153], v[182:185], v[126:129]
	v_mfma_f32_16x16x32_bf16 v[122:125], v[158:161], v[182:185], v[122:125]
	v_mfma_f32_16x16x32_bf16 v[114:117], v[150:153], v[190:193], v[114:117]
	v_mfma_f32_16x16x32_bf16 v[106:109], v[158:161], v[190:193], v[106:109]
	v_mfma_f32_16x16x32_bf16 v[98:101], v[150:153], v[208:211], v[98:101]
	v_mfma_f32_16x16x32_bf16 v[90:93], v[158:161], v[208:211], v[90:93]
	v_mfma_f32_16x16x32_bf16 v[82:85], v[150:153], v[216:219], v[82:85]
	v_mfma_f32_16x16x32_bf16 v[74:77], v[158:161], v[216:219], v[74:77]
	v_mfma_f32_16x16x32_bf16 v[126:129], v[154:157], v[186:189], v[126:129]
	v_mfma_f32_16x16x32_bf16 v[122:125], v[162:165], v[186:189], v[122:125]
	v_mfma_f32_16x16x32_bf16 v[114:117], v[154:157], v[204:207], v[114:117]
	v_mfma_f32_16x16x32_bf16 v[106:109], v[162:165], v[204:207], v[106:109]
	v_mfma_f32_16x16x32_bf16 v[98:101], v[154:157], v[212:215], v[98:101]
	v_mfma_f32_16x16x32_bf16 v[90:93], v[162:165], v[212:215], v[90:93]
	v_mfma_f32_16x16x32_bf16 v[82:85], v[154:157], v[220:223], v[82:85]
	v_mfma_f32_16x16x32_bf16 v[74:77], v[162:165], v[220:223], v[74:77]
	s_setprio 0
	s_setprio 1
	v_mfma_f32_16x16x32_bf16 v[118:121], v[166:169], v[182:185], v[118:121]
	v_mfma_f32_16x16x32_bf16 v[110:113], v[174:177], v[182:185], v[110:113]
	v_mfma_f32_16x16x32_bf16 v[102:105], v[166:169], v[190:193], v[102:105]
	v_mfma_f32_16x16x32_bf16 v[94:97], v[174:177], v[190:193], v[94:97]
	v_mfma_f32_16x16x32_bf16 v[86:89], v[166:169], v[208:211], v[86:89]
	v_mfma_f32_16x16x32_bf16 v[78:81], v[174:177], v[208:211], v[78:81]
	v_mfma_f32_16x16x32_bf16 v[70:73], v[166:169], v[216:219], v[70:73]
	v_mfma_f32_16x16x32_bf16 v[66:69], v[174:177], v[216:219], v[66:69]
	v_mfma_f32_16x16x32_bf16 v[118:121], v[170:173], v[186:189], v[118:121]
	v_mfma_f32_16x16x32_bf16 v[110:113], v[178:181], v[186:189], v[110:113]
	v_mfma_f32_16x16x32_bf16 v[102:105], v[170:173], v[204:207], v[102:105]
	v_mfma_f32_16x16x32_bf16 v[94:97], v[178:181], v[204:207], v[94:97]
	v_mfma_f32_16x16x32_bf16 v[86:89], v[170:173], v[212:215], v[86:89]
	v_mfma_f32_16x16x32_bf16 v[78:81], v[178:181], v[212:215], v[78:81]
	v_mfma_f32_16x16x32_bf16 v[70:73], v[170:173], v[220:223], v[70:73]
	v_mfma_f32_16x16x32_bf16 v[66:69], v[178:181], v[220:223], v[66:69]
	s_setprio 0
	s_barrier
	s_add_i32 s70, s70, s55
	s_mov_b32 m0, s70
	ds_read_b128 v[182:185], v149 offset:16384
	ds_read_b128 v[186:189], v149 offset:17408
	ds_read_b128 v[190:193], v149 offset:18432
	ds_read_b128 v[204:207], v149 offset:19456
	ds_read_b128 v[208:211], v149 offset:20480
	ds_read_b128 v[212:215], v149 offset:21504
	ds_read_b128 v[216:219], v149 offset:22528
	ds_read_b128 v[220:223], v149 offset:23552
	global_load_lds_dwordx4 v0, s[50:51]
	s_add_i32 m0, s70, 0x2000
	s_add_u32 s70, s50, 0x80000
	s_addc_u32 s71, s51, 0
	s_add_i32 s74, s74, s55
	global_load_lds_dwordx4 v134, s[50:51]
	s_mov_b32 m0, s74
	s_nop 0
	global_load_lds_dwordx4 v0, s[70:71]
	s_add_i32 m0, s74, 0x2000
	s_nop 0
	global_load_lds_dwordx4 v134, s[70:71]
	s_mov_b32 m0, s31
	s_nop 0
	global_load_lds_dwordx4 v130, s[52:53]
	s_mov_b32 m0, s39
	s_nop 0
	global_load_lds_dwordx4 v132, s[52:53]
	s_waitcnt vmcnt(8)
	s_waitcnt lgkmcnt(0)
	s_barrier
	s_setprio 1
	s_waitcnt lgkmcnt(0)
	v_mfma_f32_16x16x32_bf16 v[62:65], v[150:153], v[182:185], v[62:65]
	v_mfma_f32_16x16x32_bf16 v[58:61], v[158:161], v[182:185], v[58:61]
	v_mfma_f32_16x16x32_bf16 v[50:53], v[150:153], v[190:193], v[50:53]
	v_mfma_f32_16x16x32_bf16 v[42:45], v[158:161], v[190:193], v[42:45]
	v_mfma_f32_16x16x32_bf16 v[34:37], v[150:153], v[208:211], v[34:37]
	v_mfma_f32_16x16x32_bf16 v[26:29], v[158:161], v[208:211], v[26:29]
	v_mfma_f32_16x16x32_bf16 v[18:21], v[150:153], v[216:219], v[18:21]
	v_mfma_f32_16x16x32_bf16 v[10:13], v[158:161], v[216:219], v[10:13]
	v_mfma_f32_16x16x32_bf16 v[62:65], v[154:157], v[186:189], v[62:65]
	v_mfma_f32_16x16x32_bf16 v[58:61], v[162:165], v[186:189], v[58:61]
	v_mfma_f32_16x16x32_bf16 v[50:53], v[154:157], v[204:207], v[50:53]
	v_mfma_f32_16x16x32_bf16 v[42:45], v[162:165], v[204:207], v[42:45]
	v_mfma_f32_16x16x32_bf16 v[34:37], v[154:157], v[212:215], v[34:37]
	v_mfma_f32_16x16x32_bf16 v[26:29], v[162:165], v[212:215], v[26:29]
	v_mfma_f32_16x16x32_bf16 v[18:21], v[154:157], v[220:223], v[18:21]
	v_mfma_f32_16x16x32_bf16 v[10:13], v[162:165], v[220:223], v[10:13]
	s_setprio 0
	s_setprio 1
	v_mfma_f32_16x16x32_bf16 v[54:57], v[166:169], v[182:185], v[54:57]
	v_mfma_f32_16x16x32_bf16 v[46:49], v[174:177], v[182:185], v[46:49]
	v_mfma_f32_16x16x32_bf16 v[38:41], v[166:169], v[190:193], v[38:41]
	v_mfma_f32_16x16x32_bf16 v[30:33], v[174:177], v[190:193], v[30:33]
	v_mfma_f32_16x16x32_bf16 v[22:25], v[166:169], v[208:211], v[22:25]
	v_mfma_f32_16x16x32_bf16 v[14:17], v[174:177], v[208:211], v[14:17]
	v_mfma_f32_16x16x32_bf16 v[6:9], v[166:169], v[216:219], v[6:9]
	v_mfma_f32_16x16x32_bf16 v[2:5], v[174:177], v[216:219], v[2:5]
	v_mfma_f32_16x16x32_bf16 v[54:57], v[170:173], v[186:189], v[54:57]
	v_mfma_f32_16x16x32_bf16 v[46:49], v[178:181], v[186:189], v[46:49]
	v_mfma_f32_16x16x32_bf16 v[38:41], v[170:173], v[204:207], v[38:41]
	v_mfma_f32_16x16x32_bf16 v[30:33], v[178:181], v[204:207], v[30:33]
	v_mfma_f32_16x16x32_bf16 v[22:25], v[170:173], v[212:215], v[22:25]
	v_mfma_f32_16x16x32_bf16 v[14:17], v[178:181], v[212:215], v[14:17]
	v_mfma_f32_16x16x32_bf16 v[6:9], v[170:173], v[220:223], v[6:9]
	v_mfma_f32_16x16x32_bf16 v[2:5], v[178:181], v[220:223], v[2:5]
	s_setprio 0
	s_barrier
	s_nop 0
	s_add_i32 s70, 0, 0x18000
	s_add_i32 s71, 0, 0x1c000
	ds_read_b128 v[150:153], v253 offset:32768
	ds_read_b128 v[154:157], v253 offset:33792
	ds_read_b128 v[158:161], v253 offset:34816
	ds_read_b128 v[162:165], v253 offset:35840
	ds_read_b128 v[166:169], v253 offset:49152
	ds_read_b128 v[170:173], v253 offset:50176
	ds_read_b128 v[174:177], v253 offset:51200
	ds_read_b128 v[178:181], v253 offset:52224
	s_add_u32 s52, s52, 0x80000
	s_addc_u32 s53, s53, 0
	s_mov_b32 m0, s56
	ds_read_b128 v[182:185], v149 offset:32768
	ds_read_b128 v[186:189], v149 offset:33792
	ds_read_b128 v[190:193], v149 offset:34816
	ds_read_b128 v[204:207], v149 offset:35840
	ds_read_b128 v[208:211], v149 offset:36864
	ds_read_b128 v[212:215], v149 offset:37888
	ds_read_b128 v[216:219], v149 offset:38912
	ds_read_b128 v[220:223], v149 offset:39936
	global_load_lds_dwordx4 v130, s[52:53]
	s_mov_b32 m0, s57
	s_nop 0
	global_load_lds_dwordx4 v132, s[52:53]
	s_waitcnt vmcnt(8)
	s_waitcnt lgkmcnt(0)
	s_barrier
	s_setprio 1
	s_waitcnt lgkmcnt(0)
	v_mfma_f32_16x16x32_bf16 v[126:129], v[150:153], v[182:185], v[126:129]
	v_mfma_f32_16x16x32_bf16 v[122:125], v[158:161], v[182:185], v[122:125]
	v_mfma_f32_16x16x32_bf16 v[114:117], v[150:153], v[190:193], v[114:117]
	v_mfma_f32_16x16x32_bf16 v[106:109], v[158:161], v[190:193], v[106:109]
	v_mfma_f32_16x16x32_bf16 v[98:101], v[150:153], v[208:211], v[98:101]
	v_mfma_f32_16x16x32_bf16 v[90:93], v[158:161], v[208:211], v[90:93]
	v_mfma_f32_16x16x32_bf16 v[82:85], v[150:153], v[216:219], v[82:85]
	v_mfma_f32_16x16x32_bf16 v[74:77], v[158:161], v[216:219], v[74:77]
	v_mfma_f32_16x16x32_bf16 v[126:129], v[154:157], v[186:189], v[126:129]
	v_mfma_f32_16x16x32_bf16 v[122:125], v[162:165], v[186:189], v[122:125]
	v_mfma_f32_16x16x32_bf16 v[114:117], v[154:157], v[204:207], v[114:117]
	v_mfma_f32_16x16x32_bf16 v[106:109], v[162:165], v[204:207], v[106:109]
	v_mfma_f32_16x16x32_bf16 v[98:101], v[154:157], v[212:215], v[98:101]
	v_mfma_f32_16x16x32_bf16 v[90:93], v[162:165], v[212:215], v[90:93]
	v_mfma_f32_16x16x32_bf16 v[82:85], v[154:157], v[220:223], v[82:85]
	v_mfma_f32_16x16x32_bf16 v[74:77], v[162:165], v[220:223], v[74:77]
	s_setprio 0
	s_setprio 1
	v_mfma_f32_16x16x32_bf16 v[118:121], v[166:169], v[182:185], v[118:121]
	v_mfma_f32_16x16x32_bf16 v[110:113], v[174:177], v[182:185], v[110:113]
	v_mfma_f32_16x16x32_bf16 v[102:105], v[166:169], v[190:193], v[102:105]
	v_mfma_f32_16x16x32_bf16 v[94:97], v[174:177], v[190:193], v[94:97]
	v_mfma_f32_16x16x32_bf16 v[86:89], v[166:169], v[208:211], v[86:89]
	v_mfma_f32_16x16x32_bf16 v[78:81], v[174:177], v[208:211], v[78:81]
	v_mfma_f32_16x16x32_bf16 v[70:73], v[166:169], v[216:219], v[70:73]
	v_mfma_f32_16x16x32_bf16 v[66:69], v[174:177], v[216:219], v[66:69]
	v_mfma_f32_16x16x32_bf16 v[118:121], v[170:173], v[186:189], v[118:121]
	v_mfma_f32_16x16x32_bf16 v[110:113], v[178:181], v[186:189], v[110:113]
	v_mfma_f32_16x16x32_bf16 v[102:105], v[170:173], v[204:207], v[102:105]
	v_mfma_f32_16x16x32_bf16 v[94:97], v[178:181], v[204:207], v[94:97]
	v_mfma_f32_16x16x32_bf16 v[86:89], v[170:173], v[212:215], v[86:89]
	v_mfma_f32_16x16x32_bf16 v[78:81], v[178:181], v[212:215], v[78:81]
	v_mfma_f32_16x16x32_bf16 v[70:73], v[170:173], v[220:223], v[70:73]
	v_mfma_f32_16x16x32_bf16 v[66:69], v[178:181], v[220:223], v[66:69]
	s_setprio 0
	s_barrier
	s_add_u32 s100, s52, 0xfff80080
	s_addc_u32 s101, s53, -1
	s_add_u32 s98, s50, 0x80
	s_addc_u32 s99, s51, 0
	s_add_i32 s52, s70, s55
	s_mov_b32 m0, s52
	ds_read_b128 v[182:185], v149 offset:49152
	ds_read_b128 v[186:189], v149 offset:50176
	ds_read_b128 v[190:193], v149 offset:51200
	ds_read_b128 v[204:207], v149 offset:52224
	ds_read_b128 v[208:211], v149 offset:53248
	ds_read_b128 v[212:215], v149 offset:54272
	ds_read_b128 v[216:219], v149 offset:55296
	ds_read_b128 v[220:223], v149 offset:56320
	global_load_lds_dwordx4 v0, s[98:99]
	s_add_i32 m0, s52, 0x2000
	s_add_u32 s50, s50, 0x80080
	s_addc_u32 s51, s51, 0
	s_add_i32 s52, s71, s55
	global_load_lds_dwordx4 v134, s[98:99]
	s_mov_b32 m0, s52
	s_nop 0
	global_load_lds_dwordx4 v0, s[50:51]
	s_add_i32 m0, s52, 0x2000
	s_nop 0
	global_load_lds_dwordx4 v134, s[50:51]
	s_mov_b32 m0, s61
	s_nop 0
	global_load_lds_dwordx4 v130, s[100:101]
	s_mov_b32 m0, s62
	s_nop 0
	global_load_lds_dwordx4 v132, s[100:101]
	s_waitcnt vmcnt(8)
	s_waitcnt lgkmcnt(0)
	s_barrier
	s_setprio 1
	s_waitcnt lgkmcnt(0)
	v_mfma_f32_16x16x32_bf16 v[62:65], v[150:153], v[182:185], v[62:65]
	v_mfma_f32_16x16x32_bf16 v[58:61], v[158:161], v[182:185], v[58:61]
	v_mfma_f32_16x16x32_bf16 v[50:53], v[150:153], v[190:193], v[50:53]
	v_mfma_f32_16x16x32_bf16 v[42:45], v[158:161], v[190:193], v[42:45]
	v_mfma_f32_16x16x32_bf16 v[34:37], v[150:153], v[208:211], v[34:37]
	v_mfma_f32_16x16x32_bf16 v[26:29], v[158:161], v[208:211], v[26:29]
	v_mfma_f32_16x16x32_bf16 v[18:21], v[150:153], v[216:219], v[18:21]
	v_mfma_f32_16x16x32_bf16 v[10:13], v[158:161], v[216:219], v[10:13]
	v_mfma_f32_16x16x32_bf16 v[62:65], v[154:157], v[186:189], v[62:65]
	v_mfma_f32_16x16x32_bf16 v[58:61], v[162:165], v[186:189], v[58:61]
	v_mfma_f32_16x16x32_bf16 v[50:53], v[154:157], v[204:207], v[50:53]
	v_mfma_f32_16x16x32_bf16 v[42:45], v[162:165], v[204:207], v[42:45]
	v_mfma_f32_16x16x32_bf16 v[34:37], v[154:157], v[212:215], v[34:37]
	v_mfma_f32_16x16x32_bf16 v[26:29], v[162:165], v[212:215], v[26:29]
	v_mfma_f32_16x16x32_bf16 v[18:21], v[154:157], v[220:223], v[18:21]
	v_mfma_f32_16x16x32_bf16 v[10:13], v[162:165], v[220:223], v[10:13]
	s_setprio 0
	s_setprio 1
	v_mfma_f32_16x16x32_bf16 v[54:57], v[166:169], v[182:185], v[54:57]
	v_mfma_f32_16x16x32_bf16 v[46:49], v[174:177], v[182:185], v[46:49]
	v_mfma_f32_16x16x32_bf16 v[38:41], v[166:169], v[190:193], v[38:41]
	v_mfma_f32_16x16x32_bf16 v[30:33], v[174:177], v[190:193], v[30:33]
	v_mfma_f32_16x16x32_bf16 v[22:25], v[166:169], v[208:211], v[22:25]
	v_mfma_f32_16x16x32_bf16 v[14:17], v[174:177], v[208:211], v[14:17]
	v_mfma_f32_16x16x32_bf16 v[6:9], v[166:169], v[216:219], v[6:9]
	v_mfma_f32_16x16x32_bf16 v[2:5], v[174:177], v[216:219], v[2:5]
	v_mfma_f32_16x16x32_bf16 v[54:57], v[170:173], v[186:189], v[54:57]
	v_mfma_f32_16x16x32_bf16 v[46:49], v[178:181], v[186:189], v[46:49]
	v_mfma_f32_16x16x32_bf16 v[38:41], v[170:173], v[204:207], v[38:41]
	v_mfma_f32_16x16x32_bf16 v[30:33], v[178:181], v[204:207], v[30:33]
	v_mfma_f32_16x16x32_bf16 v[22:25], v[170:173], v[212:215], v[22:25]
	v_mfma_f32_16x16x32_bf16 v[14:17], v[178:181], v[212:215], v[14:17]
	v_mfma_f32_16x16x32_bf16 v[6:9], v[170:173], v[220:223], v[6:9]
	v_mfma_f32_16x16x32_bf16 v[2:5], v[178:181], v[220:223], v[2:5]
	s_setprio 0
	s_barrier
	s_add_u32 s42, s42, 0x100
	s_addc_u32 s43, s43, 0
	s_add_u32 s45, s45, 0x100
	s_addc_u32 s58, s58, 0
	s_cmp_ge_u32 s59, s33
	s_mov_b32 s50, s59
	s_cbranch_scc0 .LBB0_201

.LBB0_344:
	s_nop 0
	s_ashr_i32 s13, s12, 31
	s_lshl_b64 s[14:15], s[12:13], 18
	s_add_u32 s14, s17, s14
	s_addc_u32 s15, s18, s15
	s_and_b64 s[20:21], s[4:5], exec
	s_cselect_b32 s13, s15, s25
	s_cselect_b32 s40, s14, s24
	s_ashr_i32 s11, s10, 31
	s_lshl_b64 s[20:21], s[10:11], 18
	s_add_u32 s20, s19, s20
	s_addc_u32 s21, s28, s21
	s_and_b64 s[30:31], s[4:5], exec
	s_cselect_b32 s11, s21, s27
	s_cselect_b32 s41, s20, s26
	s_add_u32 s24, s24, 0x20080
	s_addc_u32 s25, s25, 0
	s_add_u32 s43, s26, 0x100
	s_addc_u32 s44, s27, 0
	s_mov_b32 s45, -2
	v_add_u32_e32 v253, 0x10000, v154
	s_add_u32 s26, s24, 0xfffe0080
	s_addc_u32 s27, s25, -1
	s_add_i32 s46, 0, 0x10000
	s_cmp_eq_u32 s45, 4
	s_cselect_b32 s31, s13, s27
	s_cselect_b32 s30, s40, s26
	s_cselect_b32 s27, s11, s44
	s_cselect_b32 s26, s41, s43
	s_add_i32 s52, 0, 0x14000
	ds_read_b128 v[158:161], v253
	ds_read_b128 v[162:165], v253 offset:1024
	ds_read_b128 v[166:169], v253 offset:2048
	ds_read_b128 v[170:173], v253 offset:3072
	ds_read_b128 v[174:177], v253 offset:16384
	ds_read_b128 v[178:181], v253 offset:17408
	ds_read_b128 v[182:185], v253 offset:18432
	ds_read_b128 v[186:189], v253 offset:19456
	s_add_i32 m0, s23, 0xc000
	ds_read_b128 v[190:193], v156
	ds_read_b128 v[204:207], v156 offset:1024
	ds_read_b128 v[208:211], v156 offset:2048
	ds_read_b128 v[212:215], v156 offset:3072
	ds_read_b128 v[216:219], v156 offset:4096
	ds_read_b128 v[220:223], v156 offset:5120
	ds_read_b128 v[224:227], v156 offset:6144
	ds_read_b128 v[228:231], v156 offset:7168
	global_load_lds_dwordx4 v136, s[24:25]
	s_add_i32 m0, s23, 0xe000
	s_nop 0
	global_load_lds_dwordx4 v138, s[24:25]
	s_waitcnt vmcnt(8)
	s_waitcnt lgkmcnt(0)
	s_barrier
	s_setprio 1
	s_waitcnt lgkmcnt(0)
	v_mfma_f32_16x16x32_bf16 v[126:129], v[158:161], v[190:193], 0
	v_mfma_f32_16x16x32_bf16 v[122:125], v[166:169], v[190:193], 0
	v_mfma_f32_16x16x32_bf16 v[114:117], v[158:161], v[208:211], 0
	v_mfma_f32_16x16x32_bf16 v[106:109], v[166:169], v[208:211], 0
	v_mfma_f32_16x16x32_bf16 v[98:101], v[158:161], v[216:219], 0
	v_mfma_f32_16x16x32_bf16 v[90:93], v[166:169], v[216:219], 0
	v_mfma_f32_16x16x32_bf16 v[82:85], v[158:161], v[224:227], 0
	v_mfma_f32_16x16x32_bf16 v[74:77], v[166:169], v[224:227], 0
	v_mfma_f32_16x16x32_bf16 v[126:129], v[162:165], v[204:207], v[126:129]
	v_mfma_f32_16x16x32_bf16 v[122:125], v[170:173], v[204:207], v[122:125]
	v_mfma_f32_16x16x32_bf16 v[114:117], v[162:165], v[212:215], v[114:117]
	v_mfma_f32_16x16x32_bf16 v[106:109], v[170:173], v[212:215], v[106:109]
	v_mfma_f32_16x16x32_bf16 v[98:101], v[162:165], v[220:223], v[98:101]
	v_mfma_f32_16x16x32_bf16 v[90:93], v[170:173], v[220:223], v[90:93]
	v_mfma_f32_16x16x32_bf16 v[82:85], v[162:165], v[228:231], v[82:85]
	v_mfma_f32_16x16x32_bf16 v[74:77], v[170:173], v[228:231], v[74:77]
	s_setprio 0
	s_setprio 1
	v_mfma_f32_16x16x32_bf16 v[118:121], v[174:177], v[190:193], 0
	v_mfma_f32_16x16x32_bf16 v[110:113], v[182:185], v[190:193], 0
	v_mfma_f32_16x16x32_bf16 v[102:105], v[174:177], v[208:211], 0
	v_mfma_f32_16x16x32_bf16 v[94:97], v[182:185], v[208:211], 0
	v_mfma_f32_16x16x32_bf16 v[86:89], v[174:177], v[216:219], 0
	v_mfma_f32_16x16x32_bf16 v[78:81], v[182:185], v[216:219], 0
	v_mfma_f32_16x16x32_bf16 v[70:73], v[174:177], v[224:227], 0
	v_mfma_f32_16x16x32_bf16 v[66:69], v[182:185], v[224:227], 0
	v_mfma_f32_16x16x32_bf16 v[118:121], v[178:181], v[204:207], v[118:121]
	v_mfma_f32_16x16x32_bf16 v[110:113], v[186:189], v[204:207], v[110:113]
	v_mfma_f32_16x16x32_bf16 v[102:105], v[178:181], v[212:215], v[102:105]
	v_mfma_f32_16x16x32_bf16 v[94:97], v[186:189], v[212:215], v[94:97]
	v_mfma_f32_16x16x32_bf16 v[86:89], v[178:181], v[220:223], v[86:89]
	v_mfma_f32_16x16x32_bf16 v[78:81], v[186:189], v[220:223], v[78:81]
	v_mfma_f32_16x16x32_bf16 v[70:73], v[178:181], v[228:231], v[70:73]
	v_mfma_f32_16x16x32_bf16 v[66:69], v[186:189], v[228:231], v[66:69]
	s_setprio 0
	s_barrier
	s_add_i32 s46, s46, s29
	s_mov_b32 m0, s46
	ds_read_b128 v[190:193], v156 offset:16384
	ds_read_b128 v[204:207], v156 offset:17408
	ds_read_b128 v[208:211], v156 offset:18432
	ds_read_b128 v[212:215], v156 offset:19456
	ds_read_b128 v[216:219], v156 offset:20480
	ds_read_b128 v[220:223], v156 offset:21504
	ds_read_b128 v[224:227], v156 offset:22528
	ds_read_b128 v[228:231], v156 offset:23552
	global_load_lds_dwordx4 v0, s[26:27]
	s_add_i32 m0, s46, 0x2000
	s_add_u32 s50, s26, 0x20000
	s_addc_u32 s51, s27, 0
	s_add_i32 s46, s52, s29
	global_load_lds_dwordx4 v130, s[26:27]
	s_mov_b32 m0, s46
	s_nop 0
	global_load_lds_dwordx4 v0, s[50:51]
	s_add_i32 m0, s46, 0x2000
	s_nop 0
	global_load_lds_dwordx4 v130, s[50:51]
	s_mov_b32 m0, s23
	s_nop 0
	global_load_lds_dwordx4 v134, s[30:31]
	s_mov_b32 m0, s35
	s_nop 0
	global_load_lds_dwordx4 v132, s[30:31]
	s_waitcnt vmcnt(8)
	s_waitcnt lgkmcnt(0)
	s_barrier
	s_setprio 1
	s_waitcnt lgkmcnt(0)
	v_mfma_f32_16x16x32_bf16 v[62:65], v[158:161], v[190:193], 0
	v_mfma_f32_16x16x32_bf16 v[58:61], v[166:169], v[190:193], 0
	v_mfma_f32_16x16x32_bf16 v[50:53], v[158:161], v[208:211], 0
	v_mfma_f32_16x16x32_bf16 v[42:45], v[166:169], v[208:211], 0
	v_mfma_f32_16x16x32_bf16 v[34:37], v[158:161], v[216:219], 0
	v_mfma_f32_16x16x32_bf16 v[26:29], v[166:169], v[216:219], 0
	v_mfma_f32_16x16x32_bf16 v[18:21], v[158:161], v[224:227], 0
	v_mfma_f32_16x16x32_bf16 v[10:13], v[166:169], v[224:227], 0
	v_mfma_f32_16x16x32_bf16 v[62:65], v[162:165], v[204:207], v[62:65]
	v_mfma_f32_16x16x32_bf16 v[58:61], v[170:173], v[204:207], v[58:61]
	v_mfma_f32_16x16x32_bf16 v[50:53], v[162:165], v[212:215], v[50:53]
	v_mfma_f32_16x16x32_bf16 v[42:45], v[170:173], v[212:215], v[42:45]
	v_mfma_f32_16x16x32_bf16 v[34:37], v[162:165], v[220:223], v[34:37]
	v_mfma_f32_16x16x32_bf16 v[26:29], v[170:173], v[220:223], v[26:29]
	v_mfma_f32_16x16x32_bf16 v[18:21], v[162:165], v[228:231], v[18:21]
	v_mfma_f32_16x16x32_bf16 v[10:13], v[170:173], v[228:231], v[10:13]
	s_setprio 0
	s_setprio 1
	v_mfma_f32_16x16x32_bf16 v[54:57], v[174:177], v[190:193], 0
	v_mfma_f32_16x16x32_bf16 v[46:49], v[182:185], v[190:193], 0
	v_mfma_f32_16x16x32_bf16 v[38:41], v[174:177], v[208:211], 0
	v_mfma_f32_16x16x32_bf16 v[30:33], v[182:185], v[208:211], 0
	v_mfma_f32_16x16x32_bf16 v[22:25], v[174:177], v[216:219], 0
	v_mfma_f32_16x16x32_bf16 v[14:17], v[182:185], v[216:219], 0
	v_mfma_f32_16x16x32_bf16 v[6:9], v[174:177], v[224:227], 0
	v_mfma_f32_16x16x32_bf16 v[2:5], v[182:185], v[224:227], 0
	v_mfma_f32_16x16x32_bf16 v[54:57], v[178:181], v[204:207], v[54:57]
	v_mfma_f32_16x16x32_bf16 v[46:49], v[186:189], v[204:207], v[46:49]
	v_mfma_f32_16x16x32_bf16 v[38:41], v[178:181], v[212:215], v[38:41]
	v_mfma_f32_16x16x32_bf16 v[30:33], v[186:189], v[212:215], v[30:33]
	v_mfma_f32_16x16x32_bf16 v[22:25], v[178:181], v[220:223], v[22:25]
	v_mfma_f32_16x16x32_bf16 v[14:17], v[186:189], v[220:223], v[14:17]
	v_mfma_f32_16x16x32_bf16 v[6:9], v[178:181], v[228:231], v[6:9]
	v_mfma_f32_16x16x32_bf16 v[2:5], v[186:189], v[228:231], v[2:5]
	s_setprio 0
	s_barrier
	s_nop 0
	s_add_i32 s46, 0, 0x18000
	s_add_i32 s50, 0, 0x1c000
	ds_read_b128 v[158:161], v253 offset:32768
	ds_read_b128 v[162:165], v253 offset:33792
	ds_read_b128 v[166:169], v253 offset:34816
	ds_read_b128 v[170:173], v253 offset:35840
	ds_read_b128 v[174:177], v253 offset:49152
	ds_read_b128 v[178:181], v253 offset:50176
	ds_read_b128 v[182:185], v253 offset:51200
	ds_read_b128 v[186:189], v253 offset:52224
	s_add_u32 s30, s30, 0x20000
	s_addc_u32 s31, s31, 0
	s_mov_b32 m0, s36
	ds_read_b128 v[190:193], v156 offset:32768
	ds_read_b128 v[204:207], v156 offset:33792
	ds_read_b128 v[208:211], v156 offset:34816
	ds_read_b128 v[212:215], v156 offset:35840
	ds_read_b128 v[216:219], v156 offset:36864
	ds_read_b128 v[220:223], v156 offset:37888
	ds_read_b128 v[224:227], v156 offset:38912
	ds_read_b128 v[228:231], v156 offset:39936
	global_load_lds_dwordx4 v134, s[30:31]
	s_mov_b32 m0, s37
	s_nop 0
	global_load_lds_dwordx4 v132, s[30:31]
	s_waitcnt vmcnt(8)
	s_waitcnt lgkmcnt(0)
	s_barrier
	s_setprio 1
	s_waitcnt lgkmcnt(0)
	v_mfma_f32_16x16x32_bf16 v[126:129], v[158:161], v[190:193], v[126:129]
	v_mfma_f32_16x16x32_bf16 v[122:125], v[166:169], v[190:193], v[122:125]
	v_mfma_f32_16x16x32_bf16 v[114:117], v[158:161], v[208:211], v[114:117]
	v_mfma_f32_16x16x32_bf16 v[106:109], v[166:169], v[208:211], v[106:109]
	v_mfma_f32_16x16x32_bf16 v[98:101], v[158:161], v[216:219], v[98:101]
	v_mfma_f32_16x16x32_bf16 v[90:93], v[166:169], v[216:219], v[90:93]
	v_mfma_f32_16x16x32_bf16 v[82:85], v[158:161], v[224:227], v[82:85]
	v_mfma_f32_16x16x32_bf16 v[74:77], v[166:169], v[224:227], v[74:77]
	v_mfma_f32_16x16x32_bf16 v[126:129], v[162:165], v[204:207], v[126:129]
	v_mfma_f32_16x16x32_bf16 v[122:125], v[170:173], v[204:207], v[122:125]
	v_mfma_f32_16x16x32_bf16 v[114:117], v[162:165], v[212:215], v[114:117]
	v_mfma_f32_16x16x32_bf16 v[106:109], v[170:173], v[212:215], v[106:109]
	v_mfma_f32_16x16x32_bf16 v[98:101], v[162:165], v[220:223], v[98:101]
	v_mfma_f32_16x16x32_bf16 v[90:93], v[170:173], v[220:223], v[90:93]
	v_mfma_f32_16x16x32_bf16 v[82:85], v[162:165], v[228:231], v[82:85]
	v_mfma_f32_16x16x32_bf16 v[74:77], v[170:173], v[228:231], v[74:77]
	s_setprio 0
	s_setprio 1
	v_mfma_f32_16x16x32_bf16 v[118:121], v[174:177], v[190:193], v[118:121]
	v_mfma_f32_16x16x32_bf16 v[110:113], v[182:185], v[190:193], v[110:113]
	v_mfma_f32_16x16x32_bf16 v[102:105], v[174:177], v[208:211], v[102:105]
	v_mfma_f32_16x16x32_bf16 v[94:97], v[182:185], v[208:211], v[94:97]
	v_mfma_f32_16x16x32_bf16 v[86:89], v[174:177], v[216:219], v[86:89]
	v_mfma_f32_16x16x32_bf16 v[78:81], v[182:185], v[216:219], v[78:81]
	v_mfma_f32_16x16x32_bf16 v[70:73], v[174:177], v[224:227], v[70:73]
	v_mfma_f32_16x16x32_bf16 v[66:69], v[182:185], v[224:227], v[66:69]
	v_mfma_f32_16x16x32_bf16 v[118:121], v[178:181], v[204:207], v[118:121]
	v_mfma_f32_16x16x32_bf16 v[110:113], v[186:189], v[204:207], v[110:113]
	v_mfma_f32_16x16x32_bf16 v[102:105], v[178:181], v[212:215], v[102:105]
	v_mfma_f32_16x16x32_bf16 v[94:97], v[186:189], v[212:215], v[94:97]
	v_mfma_f32_16x16x32_bf16 v[86:89], v[178:181], v[220:223], v[86:89]
	v_mfma_f32_16x16x32_bf16 v[78:81], v[186:189], v[220:223], v[78:81]
	v_mfma_f32_16x16x32_bf16 v[70:73], v[178:181], v[228:231], v[70:73]
	v_mfma_f32_16x16x32_bf16 v[66:69], v[186:189], v[228:231], v[66:69]
	s_setprio 0
	s_barrier
	s_add_u32 s100, s30, 0xfffe0080
	s_addc_u32 s101, s31, -1
	s_add_u32 s98, s26, 0x80
	s_addc_u32 s99, s27, 0
	s_add_i32 s30, s46, s29
	s_mov_b32 m0, s30
	ds_read_b128 v[190:193], v156 offset:49152
	ds_read_b128 v[204:207], v156 offset:50176
	ds_read_b128 v[208:211], v156 offset:51200
	ds_read_b128 v[212:215], v156 offset:52224
	ds_read_b128 v[216:219], v156 offset:53248
	ds_read_b128 v[220:223], v156 offset:54272
	ds_read_b128 v[224:227], v156 offset:55296
	ds_read_b128 v[228:231], v156 offset:56320
	global_load_lds_dwordx4 v0, s[98:99]
	s_add_i32 m0, s30, 0x2000
	s_add_u32 s26, s26, 0x20080
	s_addc_u32 s27, s27, 0
	s_add_i32 s30, s50, s29
	global_load_lds_dwordx4 v130, s[98:99]
	s_mov_b32 m0, s30
	s_nop 0
	global_load_lds_dwordx4 v0, s[26:27]
	s_add_i32 m0, s30, 0x2000
	s_nop 0
	global_load_lds_dwordx4 v130, s[26:27]
	s_mov_b32 m0, s38
	s_nop 0
	global_load_lds_dwordx4 v134, s[100:101]
	s_mov_b32 m0, s39
	s_nop 0
	global_load_lds_dwordx4 v132, s[100:101]
	s_waitcnt vmcnt(8)
	s_waitcnt lgkmcnt(0)
	s_barrier
	s_setprio 1
	s_waitcnt lgkmcnt(0)
	v_mfma_f32_16x16x32_bf16 v[62:65], v[158:161], v[190:193], v[62:65]
	v_mfma_f32_16x16x32_bf16 v[58:61], v[166:169], v[190:193], v[58:61]
	v_mfma_f32_16x16x32_bf16 v[50:53], v[158:161], v[208:211], v[50:53]
	v_mfma_f32_16x16x32_bf16 v[42:45], v[166:169], v[208:211], v[42:45]
	v_mfma_f32_16x16x32_bf16 v[34:37], v[158:161], v[216:219], v[34:37]
	v_mfma_f32_16x16x32_bf16 v[26:29], v[166:169], v[216:219], v[26:29]
	v_mfma_f32_16x16x32_bf16 v[18:21], v[158:161], v[224:227], v[18:21]
	v_mfma_f32_16x16x32_bf16 v[10:13], v[166:169], v[224:227], v[10:13]
	v_mfma_f32_16x16x32_bf16 v[62:65], v[162:165], v[204:207], v[62:65]
	v_mfma_f32_16x16x32_bf16 v[58:61], v[170:173], v[204:207], v[58:61]
	v_mfma_f32_16x16x32_bf16 v[50:53], v[162:165], v[212:215], v[50:53]
	v_mfma_f32_16x16x32_bf16 v[42:45], v[170:173], v[212:215], v[42:45]
	v_mfma_f32_16x16x32_bf16 v[34:37], v[162:165], v[220:223], v[34:37]
	v_mfma_f32_16x16x32_bf16 v[26:29], v[170:173], v[220:223], v[26:29]
	v_mfma_f32_16x16x32_bf16 v[18:21], v[162:165], v[228:231], v[18:21]
	v_mfma_f32_16x16x32_bf16 v[10:13], v[170:173], v[228:231], v[10:13]
	s_setprio 0
	s_setprio 1
	v_mfma_f32_16x16x32_bf16 v[54:57], v[174:177], v[190:193], v[54:57]
	v_mfma_f32_16x16x32_bf16 v[46:49], v[182:185], v[190:193], v[46:49]
	v_mfma_f32_16x16x32_bf16 v[38:41], v[174:177], v[208:211], v[38:41]
	v_mfma_f32_16x16x32_bf16 v[30:33], v[182:185], v[208:211], v[30:33]
	v_mfma_f32_16x16x32_bf16 v[22:25], v[174:177], v[216:219], v[22:25]
	v_mfma_f32_16x16x32_bf16 v[14:17], v[182:185], v[216:219], v[14:17]
	v_mfma_f32_16x16x32_bf16 v[6:9], v[174:177], v[224:227], v[6:9]
	v_mfma_f32_16x16x32_bf16 v[2:5], v[182:185], v[224:227], v[2:5]
	v_mfma_f32_16x16x32_bf16 v[54:57], v[178:181], v[204:207], v[54:57]
	v_mfma_f32_16x16x32_bf16 v[46:49], v[186:189], v[204:207], v[46:49]
	v_mfma_f32_16x16x32_bf16 v[38:41], v[178:181], v[212:215], v[38:41]
	v_mfma_f32_16x16x32_bf16 v[30:33], v[186:189], v[212:215], v[30:33]
	v_mfma_f32_16x16x32_bf16 v[22:25], v[178:181], v[220:223], v[22:25]
	v_mfma_f32_16x16x32_bf16 v[14:17], v[186:189], v[220:223], v[14:17]
	v_mfma_f32_16x16x32_bf16 v[6:9], v[178:181], v[228:231], v[6:9]
	v_mfma_f32_16x16x32_bf16 v[2:5], v[186:189], v[228:231], v[2:5]
	s_setprio 0
	s_barrier
	s_add_i32 s45, s45, 2
	s_add_u32 s24, s24, 0x100
	s_addc_u32 s25, s25, 0
	s_add_u32 s43, s43, 0x100
	s_addc_u32 s44, s44, 0
	s_cmp_gt_u32 s45, 5
	s_cbranch_scc0 .LBB0_345
	s_branch .Lpeel_exit_1
.LBB0_345:
	s_add_u32 s26, s24, 0xfffe0080
	s_addc_u32 s27, s25, -1
	s_add_i32 s46, 0, 0x10000
	s_cmp_eq_u32 s45, 4
	s_cselect_b32 s31, s13, s27
	s_cselect_b32 s30, s40, s26
	s_cselect_b32 s27, s11, s44
	s_cselect_b32 s26, s41, s43
	s_add_i32 s52, 0, 0x14000
	ds_read_b128 v[158:161], v253
	ds_read_b128 v[162:165], v253 offset:1024
	ds_read_b128 v[166:169], v253 offset:2048
	ds_read_b128 v[170:173], v253 offset:3072
	ds_read_b128 v[174:177], v253 offset:16384
	ds_read_b128 v[178:181], v253 offset:17408
	ds_read_b128 v[182:185], v253 offset:18432
	ds_read_b128 v[186:189], v253 offset:19456
	s_add_i32 m0, s23, 0xc000
	ds_read_b128 v[190:193], v156
	ds_read_b128 v[204:207], v156 offset:1024
	ds_read_b128 v[208:211], v156 offset:2048
	ds_read_b128 v[212:215], v156 offset:3072
	ds_read_b128 v[216:219], v156 offset:4096
	ds_read_b128 v[220:223], v156 offset:5120
	ds_read_b128 v[224:227], v156 offset:6144
	ds_read_b128 v[228:231], v156 offset:7168
	global_load_lds_dwordx4 v136, s[24:25]
	s_add_i32 m0, s23, 0xe000
	s_nop 0
	global_load_lds_dwordx4 v138, s[24:25]
	s_waitcnt vmcnt(8)
	s_waitcnt lgkmcnt(0)
	s_barrier
	s_setprio 1
	s_waitcnt lgkmcnt(0)
	v_mfma_f32_16x16x32_bf16 v[126:129], v[158:161], v[190:193], v[126:129]
	v_mfma_f32_16x16x32_bf16 v[122:125], v[166:169], v[190:193], v[122:125]
	v_mfma_f32_16x16x32_bf16 v[114:117], v[158:161], v[208:211], v[114:117]
	v_mfma_f32_16x16x32_bf16 v[106:109], v[166:169], v[208:211], v[106:109]
	v_mfma_f32_16x16x32_bf16 v[98:101], v[158:161], v[216:219], v[98:101]
	v_mfma_f32_16x16x32_bf16 v[90:93], v[166:169], v[216:219], v[90:93]
	v_mfma_f32_16x16x32_bf16 v[82:85], v[158:161], v[224:227], v[82:85]
	v_mfma_f32_16x16x32_bf16 v[74:77], v[166:169], v[224:227], v[74:77]
	v_mfma_f32_16x16x32_bf16 v[126:129], v[162:165], v[204:207], v[126:129]
	v_mfma_f32_16x16x32_bf16 v[122:125], v[170:173], v[204:207], v[122:125]
	v_mfma_f32_16x16x32_bf16 v[114:117], v[162:165], v[212:215], v[114:117]
	v_mfma_f32_16x16x32_bf16 v[106:109], v[170:173], v[212:215], v[106:109]
	v_mfma_f32_16x16x32_bf16 v[98:101], v[162:165], v[220:223], v[98:101]
	v_mfma_f32_16x16x32_bf16 v[90:93], v[170:173], v[220:223], v[90:93]
	v_mfma_f32_16x16x32_bf16 v[82:85], v[162:165], v[228:231], v[82:85]
	v_mfma_f32_16x16x32_bf16 v[74:77], v[170:173], v[228:231], v[74:77]
	s_setprio 0
	s_setprio 1
	v_mfma_f32_16x16x32_bf16 v[118:121], v[174:177], v[190:193], v[118:121]
	v_mfma_f32_16x16x32_bf16 v[110:113], v[182:185], v[190:193], v[110:113]
	v_mfma_f32_16x16x32_bf16 v[102:105], v[174:177], v[208:211], v[102:105]
	v_mfma_f32_16x16x32_bf16 v[94:97], v[182:185], v[208:211], v[94:97]
	v_mfma_f32_16x16x32_bf16 v[86:89], v[174:177], v[216:219], v[86:89]
	v_mfma_f32_16x16x32_bf16 v[78:81], v[182:185], v[216:219], v[78:81]
	v_mfma_f32_16x16x32_bf16 v[70:73], v[174:177], v[224:227], v[70:73]
	v_mfma_f32_16x16x32_bf16 v[66:69], v[182:185], v[224:227], v[66:69]
	v_mfma_f32_16x16x32_bf16 v[118:121], v[178:181], v[204:207], v[118:121]
	v_mfma_f32_16x16x32_bf16 v[110:113], v[186:189], v[204:207], v[110:113]
	v_mfma_f32_16x16x32_bf16 v[102:105], v[178:181], v[212:215], v[102:105]
	v_mfma_f32_16x16x32_bf16 v[94:97], v[186:189], v[212:215], v[94:97]
	v_mfma_f32_16x16x32_bf16 v[86:89], v[178:181], v[220:223], v[86:89]
	v_mfma_f32_16x16x32_bf16 v[78:81], v[186:189], v[220:223], v[78:81]
	v_mfma_f32_16x16x32_bf16 v[70:73], v[178:181], v[228:231], v[70:73]
	v_mfma_f32_16x16x32_bf16 v[66:69], v[186:189], v[228:231], v[66:69]
	s_setprio 0
	s_barrier
	s_add_i32 s46, s46, s29
	s_mov_b32 m0, s46
	ds_read_b128 v[190:193], v156 offset:16384
	ds_read_b128 v[204:207], v156 offset:17408
	ds_read_b128 v[208:211], v156 offset:18432
	ds_read_b128 v[212:215], v156 offset:19456
	ds_read_b128 v[216:219], v156 offset:20480
	ds_read_b128 v[220:223], v156 offset:21504
	ds_read_b128 v[224:227], v156 offset:22528
	ds_read_b128 v[228:231], v156 offset:23552
	global_load_lds_dwordx4 v0, s[26:27]
	s_add_i32 m0, s46, 0x2000
	s_add_u32 s50, s26, 0x20000
	s_addc_u32 s51, s27, 0
	s_add_i32 s46, s52, s29
	global_load_lds_dwordx4 v130, s[26:27]
	s_mov_b32 m0, s46
	s_nop 0
	global_load_lds_dwordx4 v0, s[50:51]
	s_add_i32 m0, s46, 0x2000
	s_nop 0
	global_load_lds_dwordx4 v130, s[50:51]
	s_mov_b32 m0, s23
	s_nop 0
	global_load_lds_dwordx4 v134, s[30:31]
	s_mov_b32 m0, s35
	s_nop 0
	global_load_lds_dwordx4 v132, s[30:31]
	s_waitcnt vmcnt(8)
	s_waitcnt lgkmcnt(0)
	s_barrier
	s_setprio 1
	s_waitcnt lgkmcnt(0)
	v_mfma_f32_16x16x32_bf16 v[62:65], v[158:161], v[190:193], v[62:65]
	v_mfma_f32_16x16x32_bf16 v[58:61], v[166:169], v[190:193], v[58:61]
	v_mfma_f32_16x16x32_bf16 v[50:53], v[158:161], v[208:211], v[50:53]
	v_mfma_f32_16x16x32_bf16 v[42:45], v[166:169], v[208:211], v[42:45]
	v_mfma_f32_16x16x32_bf16 v[34:37], v[158:161], v[216:219], v[34:37]
	v_mfma_f32_16x16x32_bf16 v[26:29], v[166:169], v[216:219], v[26:29]
	v_mfma_f32_16x16x32_bf16 v[18:21], v[158:161], v[224:227], v[18:21]
	v_mfma_f32_16x16x32_bf16 v[10:13], v[166:169], v[224:227], v[10:13]
	v_mfma_f32_16x16x32_bf16 v[62:65], v[162:165], v[204:207], v[62:65]
	v_mfma_f32_16x16x32_bf16 v[58:61], v[170:173], v[204:207], v[58:61]
	v_mfma_f32_16x16x32_bf16 v[50:53], v[162:165], v[212:215], v[50:53]
	v_mfma_f32_16x16x32_bf16 v[42:45], v[170:173], v[212:215], v[42:45]
	v_mfma_f32_16x16x32_bf16 v[34:37], v[162:165], v[220:223], v[34:37]
	v_mfma_f32_16x16x32_bf16 v[26:29], v[170:173], v[220:223], v[26:29]
	v_mfma_f32_16x16x32_bf16 v[18:21], v[162:165], v[228:231], v[18:21]
	v_mfma_f32_16x16x32_bf16 v[10:13], v[170:173], v[228:231], v[10:13]
	s_setprio 0
	s_setprio 1
	v_mfma_f32_16x16x32_bf16 v[54:57], v[174:177], v[190:193], v[54:57]
	v_mfma_f32_16x16x32_bf16 v[46:49], v[182:185], v[190:193], v[46:49]
	v_mfma_f32_16x16x32_bf16 v[38:41], v[174:177], v[208:211], v[38:41]
	v_mfma_f32_16x16x32_bf16 v[30:33], v[182:185], v[208:211], v[30:33]
	v_mfma_f32_16x16x32_bf16 v[22:25], v[174:177], v[216:219], v[22:25]
	v_mfma_f32_16x16x32_bf16 v[14:17], v[182:185], v[216:219], v[14:17]
	v_mfma_f32_16x16x32_bf16 v[6:9], v[174:177], v[224:227], v[6:9]
	v_mfma_f32_16x16x32_bf16 v[2:5], v[182:185], v[224:227], v[2:5]
	v_mfma_f32_16x16x32_bf16 v[54:57], v[178:181], v[204:207], v[54:57]
	v_mfma_f32_16x16x32_bf16 v[46:49], v[186:189], v[204:207], v[46:49]
	v_mfma_f32_16x16x32_bf16 v[38:41], v[178:181], v[212:215], v[38:41]
	v_mfma_f32_16x16x32_bf16 v[30:33], v[186:189], v[212:215], v[30:33]
	v_mfma_f32_16x16x32_bf16 v[22:25], v[178:181], v[220:223], v[22:25]
	v_mfma_f32_16x16x32_bf16 v[14:17], v[186:189], v[220:223], v[14:17]
	v_mfma_f32_16x16x32_bf16 v[6:9], v[178:181], v[228:231], v[6:9]
	v_mfma_f32_16x16x32_bf16 v[2:5], v[186:189], v[228:231], v[2:5]
	s_setprio 0
	s_barrier
	s_nop 0
	s_add_i32 s46, 0, 0x18000
	s_add_i32 s50, 0, 0x1c000
	ds_read_b128 v[158:161], v253 offset:32768
	ds_read_b128 v[162:165], v253 offset:33792
	ds_read_b128 v[166:169], v253 offset:34816
	ds_read_b128 v[170:173], v253 offset:35840
	ds_read_b128 v[174:177], v253 offset:49152
	ds_read_b128 v[178:181], v253 offset:50176
	ds_read_b128 v[182:185], v253 offset:51200
	ds_read_b128 v[186:189], v253 offset:52224
	s_add_u32 s30, s30, 0x20000
	s_addc_u32 s31, s31, 0
	s_mov_b32 m0, s36
	ds_read_b128 v[190:193], v156 offset:32768
	ds_read_b128 v[204:207], v156 offset:33792
	ds_read_b128 v[208:211], v156 offset:34816
	ds_read_b128 v[212:215], v156 offset:35840
	ds_read_b128 v[216:219], v156 offset:36864
	ds_read_b128 v[220:223], v156 offset:37888
	ds_read_b128 v[224:227], v156 offset:38912
	ds_read_b128 v[228:231], v156 offset:39936
	global_load_lds_dwordx4 v134, s[30:31]
	s_mov_b32 m0, s37
	s_nop 0
	global_load_lds_dwordx4 v132, s[30:31]
	s_waitcnt vmcnt(8)
	s_waitcnt lgkmcnt(0)
	s_barrier
	s_setprio 1
	s_waitcnt lgkmcnt(0)
	v_mfma_f32_16x16x32_bf16 v[126:129], v[158:161], v[190:193], v[126:129]
	v_mfma_f32_16x16x32_bf16 v[122:125], v[166:169], v[190:193], v[122:125]
	v_mfma_f32_16x16x32_bf16 v[114:117], v[158:161], v[208:211], v[114:117]
	v_mfma_f32_16x16x32_bf16 v[106:109], v[166:169], v[208:211], v[106:109]
	v_mfma_f32_16x16x32_bf16 v[98:101], v[158:161], v[216:219], v[98:101]
	v_mfma_f32_16x16x32_bf16 v[90:93], v[166:169], v[216:219], v[90:93]
	v_mfma_f32_16x16x32_bf16 v[82:85], v[158:161], v[224:227], v[82:85]
	v_mfma_f32_16x16x32_bf16 v[74:77], v[166:169], v[224:227], v[74:77]
	v_mfma_f32_16x16x32_bf16 v[126:129], v[162:165], v[204:207], v[126:129]
	v_mfma_f32_16x16x32_bf16 v[122:125], v[170:173], v[204:207], v[122:125]
	v_mfma_f32_16x16x32_bf16 v[114:117], v[162:165], v[212:215], v[114:117]
	v_mfma_f32_16x16x32_bf16 v[106:109], v[170:173], v[212:215], v[106:109]
	v_mfma_f32_16x16x32_bf16 v[98:101], v[162:165], v[220:223], v[98:101]
	v_mfma_f32_16x16x32_bf16 v[90:93], v[170:173], v[220:223], v[90:93]
	v_mfma_f32_16x16x32_bf16 v[82:85], v[162:165], v[228:231], v[82:85]
	v_mfma_f32_16x16x32_bf16 v[74:77], v[170:173], v[228:231], v[74:77]
	s_setprio 0
	s_setprio 1
	v_mfma_f32_16x16x32_bf16 v[118:121], v[174:177], v[190:193], v[118:121]
	v_mfma_f32_16x16x32_bf16 v[110:113], v[182:185], v[190:193], v[110:113]
	v_mfma_f32_16x16x32_bf16 v[102:105], v[174:177], v[208:211], v[102:105]
	v_mfma_f32_16x16x32_bf16 v[94:97], v[182:185], v[208:211], v[94:97]
	v_mfma_f32_16x16x32_bf16 v[86:89], v[174:177], v[216:219], v[86:89]
	v_mfma_f32_16x16x32_bf16 v[78:81], v[182:185], v[216:219], v[78:81]
	v_mfma_f32_16x16x32_bf16 v[70:73], v[174:177], v[224:227], v[70:73]
	v_mfma_f32_16x16x32_bf16 v[66:69], v[182:185], v[224:227], v[66:69]
	v_mfma_f32_16x16x32_bf16 v[118:121], v[178:181], v[204:207], v[118:121]
	v_mfma_f32_16x16x32_bf16 v[110:113], v[186:189], v[204:207], v[110:113]
	v_mfma_f32_16x16x32_bf16 v[102:105], v[178:181], v[212:215], v[102:105]
	v_mfma_f32_16x16x32_bf16 v[94:97], v[186:189], v[212:215], v[94:97]
	v_mfma_f32_16x16x32_bf16 v[86:89], v[178:181], v[220:223], v[86:89]
	v_mfma_f32_16x16x32_bf16 v[78:81], v[186:189], v[220:223], v[78:81]
	v_mfma_f32_16x16x32_bf16 v[70:73], v[178:181], v[228:231], v[70:73]
	v_mfma_f32_16x16x32_bf16 v[66:69], v[186:189], v[228:231], v[66:69]
	s_setprio 0
	s_barrier
	s_add_u32 s100, s30, 0xfffe0080
	s_addc_u32 s101, s31, -1
	s_add_u32 s98, s26, 0x80
	s_addc_u32 s99, s27, 0
	s_add_i32 s30, s46, s29
	s_mov_b32 m0, s30
	ds_read_b128 v[190:193], v156 offset:49152
	ds_read_b128 v[204:207], v156 offset:50176
	ds_read_b128 v[208:211], v156 offset:51200
	ds_read_b128 v[212:215], v156 offset:52224
	ds_read_b128 v[216:219], v156 offset:53248
	ds_read_b128 v[220:223], v156 offset:54272
	ds_read_b128 v[224:227], v156 offset:55296
	ds_read_b128 v[228:231], v156 offset:56320
	global_load_lds_dwordx4 v0, s[98:99]
	s_add_i32 m0, s30, 0x2000
	s_add_u32 s26, s26, 0x20080
	s_addc_u32 s27, s27, 0
	s_add_i32 s30, s50, s29
	global_load_lds_dwordx4 v130, s[98:99]
	s_mov_b32 m0, s30
	s_nop 0
	global_load_lds_dwordx4 v0, s[26:27]
	s_add_i32 m0, s30, 0x2000
	s_nop 0
	global_load_lds_dwordx4 v130, s[26:27]
	s_mov_b32 m0, s38
	s_nop 0
	global_load_lds_dwordx4 v134, s[100:101]
	s_mov_b32 m0, s39
	s_nop 0
	global_load_lds_dwordx4 v132, s[100:101]
	s_waitcnt vmcnt(8)
	s_waitcnt lgkmcnt(0)
	s_barrier
	s_setprio 1
	s_waitcnt lgkmcnt(0)
	v_mfma_f32_16x16x32_bf16 v[62:65], v[158:161], v[190:193], v[62:65]
	v_mfma_f32_16x16x32_bf16 v[58:61], v[166:169], v[190:193], v[58:61]
	v_mfma_f32_16x16x32_bf16 v[50:53], v[158:161], v[208:211], v[50:53]
	v_mfma_f32_16x16x32_bf16 v[42:45], v[166:169], v[208:211], v[42:45]
	v_mfma_f32_16x16x32_bf16 v[34:37], v[158:161], v[216:219], v[34:37]
	v_mfma_f32_16x16x32_bf16 v[26:29], v[166:169], v[216:219], v[26:29]
	v_mfma_f32_16x16x32_bf16 v[18:21], v[158:161], v[224:227], v[18:21]
	v_mfma_f32_16x16x32_bf16 v[10:13], v[166:169], v[224:227], v[10:13]
	v_mfma_f32_16x16x32_bf16 v[62:65], v[162:165], v[204:207], v[62:65]
	v_mfma_f32_16x16x32_bf16 v[58:61], v[170:173], v[204:207], v[58:61]
	v_mfma_f32_16x16x32_bf16 v[50:53], v[162:165], v[212:215], v[50:53]
	v_mfma_f32_16x16x32_bf16 v[42:45], v[170:173], v[212:215], v[42:45]
	v_mfma_f32_16x16x32_bf16 v[34:37], v[162:165], v[220:223], v[34:37]
	v_mfma_f32_16x16x32_bf16 v[26:29], v[170:173], v[220:223], v[26:29]
	v_mfma_f32_16x16x32_bf16 v[18:21], v[162:165], v[228:231], v[18:21]
	v_mfma_f32_16x16x32_bf16 v[10:13], v[170:173], v[228:231], v[10:13]
	s_setprio 0
	s_setprio 1
	v_mfma_f32_16x16x32_bf16 v[54:57], v[174:177], v[190:193], v[54:57]
	v_mfma_f32_16x16x32_bf16 v[46:49], v[182:185], v[190:193], v[46:49]
	v_mfma_f32_16x16x32_bf16 v[38:41], v[174:177], v[208:211], v[38:41]
	v_mfma_f32_16x16x32_bf16 v[30:33], v[182:185], v[208:211], v[30:33]
	v_mfma_f32_16x16x32_bf16 v[22:25], v[174:177], v[216:219], v[22:25]
	v_mfma_f32_16x16x32_bf16 v[14:17], v[182:185], v[216:219], v[14:17]
	v_mfma_f32_16x16x32_bf16 v[6:9], v[174:177], v[224:227], v[6:9]
	v_mfma_f32_16x16x32_bf16 v[2:5], v[182:185], v[224:227], v[2:5]
	v_mfma_f32_16x16x32_bf16 v[54:57], v[178:181], v[204:207], v[54:57]
	v_mfma_f32_16x16x32_bf16 v[46:49], v[186:189], v[204:207], v[46:49]
	v_mfma_f32_16x16x32_bf16 v[38:41], v[178:181], v[212:215], v[38:41]
	v_mfma_f32_16x16x32_bf16 v[30:33], v[186:189], v[212:215], v[30:33]
	v_mfma_f32_16x16x32_bf16 v[22:25], v[178:181], v[220:223], v[22:25]
	v_mfma_f32_16x16x32_bf16 v[14:17], v[186:189], v[220:223], v[14:17]
	v_mfma_f32_16x16x32_bf16 v[6:9], v[178:181], v[228:231], v[6:9]
	v_mfma_f32_16x16x32_bf16 v[2:5], v[186:189], v[228:231], v[2:5]
	s_setprio 0
	s_barrier
	s_add_i32 s45, s45, 2
	s_add_u32 s24, s24, 0x100
	s_addc_u32 s25, s25, 0
	s_add_u32 s43, s43, 0x100
	s_addc_u32 s44, s44, 0
	s_cmp_gt_u32 s45, 5
	s_cbranch_scc0 .LBB0_345

.LBB0_360:
	s_nop 0
	s_ashr_i32 s11, s10, 31
	s_lshl_b64 s[12:13], s[10:11], 17
	s_add_u32 s12, s28, s12
	s_addc_u32 s13, s29, s13
	s_and_b64 s[14:15], s[4:5], exec
	s_cselect_b32 s11, s13, s25
	s_cselect_b32 s40, s12, s24
	s_ashr_i32 s9, s8, 31
	s_lshl_b64 s[14:15], s[8:9], 17
	s_add_u32 s14, s17, s14
	s_addc_u32 s15, s18, s15
	s_and_b64 s[26:27], s[4:5], exec
	s_cselect_b32 s9, s15, s23
	s_cselect_b32 s41, s14, s22
	s_mov_b32 s36, 0
	s_mov_b64 s[26:27], -1
	s_mov_b64 s[30:31], 0
	v_add_u32_e32 v253, 0x10000, v139
	s_add_u32 s37, s24, s36
	s_addc_u32 s44, s25, 0
	s_add_u32 s42, s37, 0x100
	s_addc_u32 s43, s44, 0
	s_and_b64 s[38:39], s[30:31], exec
	s_cselect_b32 s39, s11, s43
	s_cselect_b32 s38, s40, s42
	s_add_u32 s36, s22, s36
	s_addc_u32 s42, s23, 0
	s_add_u32 s36, s36, 0x100
	s_addc_u32 s42, s42, 0
	s_add_i32 s64, 0, 0x10000
	s_and_b64 s[30:31], s[30:31], exec
	s_cselect_b32 s43, s9, s42
	s_cselect_b32 s42, s41, s36
	s_add_i32 s31, 0, 0x14000
	s_add_u32 s52, s37, 0x10080
	s_addc_u32 s53, s44, 0
	s_add_i32 s63, s64, s19
	s_add_i32 m0, s21, 0xc000
	s_add_i32 s66, s21, 0xe000
	s_add_i32 s60, s63, 0x2000
	s_add_u32 s50, s42, 0x10000
	ds_read_b128 v[144:147], v253
	ds_read_b128 v[148:151], v253 offset:1024
	ds_read_b128 v[152:155], v253 offset:2048
	ds_read_b128 v[156:159], v253 offset:3072
	s_addc_u32 s51, s43, 0
	s_add_i32 s62, s31, s19
	ds_read_b128 v[160:163], v253 offset:16384
	ds_read_b128 v[164:167], v253 offset:17408
	ds_read_b128 v[168:171], v253 offset:18432
	ds_read_b128 v[172:175], v253 offset:19456
	s_add_i32 s61, s62, 0x2000
	s_add_i32 s59, 0, 0x18000
	s_add_i32 s58, 0, 0x1c000
	s_add_u32 s36, s38, 0x10000
	s_addc_u32 s37, s39, 0
	s_add_i32 s45, s59, s19
	s_add_i32 s44, s45, 0x2000
	s_add_u32 s30, s42, 0x10080
	s_addc_u32 s31, s43, 0
	s_add_i32 s65, s58, s19
	s_add_i32 s64, s65, 0x2000
	ds_read_b128 v[176:179], v141
	ds_read_b128 v[180:183], v141 offset:1024
	ds_read_b128 v[184:187], v141 offset:2048
	ds_read_b128 v[188:191], v141 offset:3072
	ds_read_b128 v[204:207], v141 offset:4096
	ds_read_b128 v[208:211], v141 offset:5120
	ds_read_b128 v[212:215], v141 offset:6144
	ds_read_b128 v[216:219], v141 offset:7168
	global_load_lds_dwordx4 v134, s[52:53]
	s_mov_b32 m0, s66
	s_nop 0
	global_load_lds_dwordx4 v132, s[52:53]
	s_waitcnt vmcnt(8)
	s_waitcnt lgkmcnt(0)
	s_barrier
	s_setprio 1
	s_waitcnt lgkmcnt(0)
	v_mfma_f32_16x16x32_bf16 v[126:129], v[144:147], v[176:179], 0
	v_mfma_f32_16x16x32_bf16 v[122:125], v[152:155], v[176:179], 0
	v_mfma_f32_16x16x32_bf16 v[114:117], v[144:147], v[184:187], 0
	v_mfma_f32_16x16x32_bf16 v[106:109], v[152:155], v[184:187], 0
	v_mfma_f32_16x16x32_bf16 v[98:101], v[144:147], v[204:207], 0
	v_mfma_f32_16x16x32_bf16 v[90:93], v[152:155], v[204:207], 0
	v_mfma_f32_16x16x32_bf16 v[82:85], v[144:147], v[212:215], 0
	v_mfma_f32_16x16x32_bf16 v[74:77], v[152:155], v[212:215], 0
	v_mfma_f32_16x16x32_bf16 v[126:129], v[148:151], v[180:183], v[126:129]
	v_mfma_f32_16x16x32_bf16 v[122:125], v[156:159], v[180:183], v[122:125]
	v_mfma_f32_16x16x32_bf16 v[114:117], v[148:151], v[188:191], v[114:117]
	v_mfma_f32_16x16x32_bf16 v[106:109], v[156:159], v[188:191], v[106:109]
	v_mfma_f32_16x16x32_bf16 v[98:101], v[148:151], v[208:211], v[98:101]
	v_mfma_f32_16x16x32_bf16 v[90:93], v[156:159], v[208:211], v[90:93]
	v_mfma_f32_16x16x32_bf16 v[82:85], v[148:151], v[216:219], v[82:85]
	v_mfma_f32_16x16x32_bf16 v[74:77], v[156:159], v[216:219], v[74:77]
	s_setprio 0
	s_setprio 1
	v_mfma_f32_16x16x32_bf16 v[118:121], v[160:163], v[176:179], 0
	v_mfma_f32_16x16x32_bf16 v[110:113], v[168:171], v[176:179], 0
	v_mfma_f32_16x16x32_bf16 v[102:105], v[160:163], v[184:187], 0
	v_mfma_f32_16x16x32_bf16 v[94:97], v[168:171], v[184:187], 0
	v_mfma_f32_16x16x32_bf16 v[86:89], v[160:163], v[204:207], 0
	v_mfma_f32_16x16x32_bf16 v[78:81], v[168:171], v[204:207], 0
	v_mfma_f32_16x16x32_bf16 v[70:73], v[160:163], v[212:215], 0
	v_mfma_f32_16x16x32_bf16 v[66:69], v[168:171], v[212:215], 0
	v_mfma_f32_16x16x32_bf16 v[118:121], v[164:167], v[180:183], v[118:121]
	v_mfma_f32_16x16x32_bf16 v[110:113], v[172:175], v[180:183], v[110:113]
	v_mfma_f32_16x16x32_bf16 v[102:105], v[164:167], v[188:191], v[102:105]
	v_mfma_f32_16x16x32_bf16 v[94:97], v[172:175], v[188:191], v[94:97]
	v_mfma_f32_16x16x32_bf16 v[86:89], v[164:167], v[208:211], v[86:89]
	v_mfma_f32_16x16x32_bf16 v[78:81], v[172:175], v[208:211], v[78:81]
	v_mfma_f32_16x16x32_bf16 v[70:73], v[164:167], v[216:219], v[70:73]
	v_mfma_f32_16x16x32_bf16 v[66:69], v[172:175], v[216:219], v[66:69]
	s_setprio 0
	s_barrier
	s_mov_b32 m0, s63
	ds_read_b128 v[176:179], v141 offset:16384
	ds_read_b128 v[180:183], v141 offset:17408
	ds_read_b128 v[184:187], v141 offset:18432
	ds_read_b128 v[188:191], v141 offset:19456
	ds_read_b128 v[204:207], v141 offset:20480
	ds_read_b128 v[208:211], v141 offset:21504
	ds_read_b128 v[212:215], v141 offset:22528
	ds_read_b128 v[216:219], v141 offset:23552
	global_load_lds_dwordx4 v0, s[42:43]
	s_mov_b32 m0, s60
	s_nop 0
	global_load_lds_dwordx4 v130, s[42:43]
	s_mov_b32 m0, s62
	s_nop 0
	global_load_lds_dwordx4 v0, s[50:51]
	s_mov_b32 m0, s61
	s_nop 0
	global_load_lds_dwordx4 v130, s[50:51]
	s_mov_b32 m0, s21
	s_nop 0
	global_load_lds_dwordx4 v134, s[38:39]
	s_mov_b32 m0, s35
	s_nop 0
	global_load_lds_dwordx4 v132, s[38:39]
	s_waitcnt vmcnt(8)
	s_waitcnt lgkmcnt(0)
	s_barrier
	s_setprio 1
	s_waitcnt lgkmcnt(0)
	v_mfma_f32_16x16x32_bf16 v[62:65], v[144:147], v[176:179], 0
	v_mfma_f32_16x16x32_bf16 v[58:61], v[152:155], v[176:179], 0
	v_mfma_f32_16x16x32_bf16 v[50:53], v[144:147], v[184:187], 0
	v_mfma_f32_16x16x32_bf16 v[42:45], v[152:155], v[184:187], 0
	v_mfma_f32_16x16x32_bf16 v[34:37], v[144:147], v[204:207], 0
	v_mfma_f32_16x16x32_bf16 v[26:29], v[152:155], v[204:207], 0
	v_mfma_f32_16x16x32_bf16 v[18:21], v[144:147], v[212:215], 0
	v_mfma_f32_16x16x32_bf16 v[10:13], v[152:155], v[212:215], 0
	v_mfma_f32_16x16x32_bf16 v[62:65], v[148:151], v[180:183], v[62:65]
	v_mfma_f32_16x16x32_bf16 v[58:61], v[156:159], v[180:183], v[58:61]
	v_mfma_f32_16x16x32_bf16 v[50:53], v[148:151], v[188:191], v[50:53]
	v_mfma_f32_16x16x32_bf16 v[42:45], v[156:159], v[188:191], v[42:45]
	v_mfma_f32_16x16x32_bf16 v[34:37], v[148:151], v[208:211], v[34:37]
	v_mfma_f32_16x16x32_bf16 v[26:29], v[156:159], v[208:211], v[26:29]
	v_mfma_f32_16x16x32_bf16 v[18:21], v[148:151], v[216:219], v[18:21]
	v_mfma_f32_16x16x32_bf16 v[10:13], v[156:159], v[216:219], v[10:13]
	s_setprio 0
	s_setprio 1
	v_mfma_f32_16x16x32_bf16 v[54:57], v[160:163], v[176:179], 0
	v_mfma_f32_16x16x32_bf16 v[46:49], v[168:171], v[176:179], 0
	v_mfma_f32_16x16x32_bf16 v[38:41], v[160:163], v[184:187], 0
	v_mfma_f32_16x16x32_bf16 v[30:33], v[168:171], v[184:187], 0
	v_mfma_f32_16x16x32_bf16 v[22:25], v[160:163], v[204:207], 0
	v_mfma_f32_16x16x32_bf16 v[14:17], v[168:171], v[204:207], 0
	v_mfma_f32_16x16x32_bf16 v[6:9], v[160:163], v[212:215], 0
	v_mfma_f32_16x16x32_bf16 v[2:5], v[168:171], v[212:215], 0
	v_mfma_f32_16x16x32_bf16 v[54:57], v[164:167], v[180:183], v[54:57]
	v_mfma_f32_16x16x32_bf16 v[46:49], v[172:175], v[180:183], v[46:49]
	v_mfma_f32_16x16x32_bf16 v[38:41], v[164:167], v[188:191], v[38:41]
	v_mfma_f32_16x16x32_bf16 v[30:33], v[172:175], v[188:191], v[30:33]
	v_mfma_f32_16x16x32_bf16 v[22:25], v[164:167], v[208:211], v[22:25]
	v_mfma_f32_16x16x32_bf16 v[14:17], v[172:175], v[208:211], v[14:17]
	v_mfma_f32_16x16x32_bf16 v[6:9], v[164:167], v[216:219], v[6:9]
	v_mfma_f32_16x16x32_bf16 v[2:5], v[172:175], v[216:219], v[2:5]
	s_setprio 0
	s_barrier
	ds_read_b128 v[144:147], v253 offset:32768
	ds_read_b128 v[148:151], v253 offset:33792
	ds_read_b128 v[152:155], v253 offset:34816
	ds_read_b128 v[156:159], v253 offset:35840
	ds_read_b128 v[160:163], v253 offset:49152
	ds_read_b128 v[164:167], v253 offset:50176
	ds_read_b128 v[168:171], v253 offset:51200
	ds_read_b128 v[172:175], v253 offset:52224
	s_mov_b32 m0, s46
	ds_read_b128 v[176:179], v141 offset:32768
	ds_read_b128 v[180:183], v141 offset:33792
	ds_read_b128 v[184:187], v141 offset:34816
	ds_read_b128 v[188:191], v141 offset:35840
	ds_read_b128 v[204:207], v141 offset:36864
	ds_read_b128 v[208:211], v141 offset:37888
	ds_read_b128 v[212:215], v141 offset:38912
	ds_read_b128 v[216:219], v141 offset:39936
	global_load_lds_dwordx4 v134, s[36:37]
	s_mov_b32 m0, s54
	s_nop 0
	global_load_lds_dwordx4 v132, s[36:37]
	s_waitcnt vmcnt(8)
	s_waitcnt lgkmcnt(0)
	s_barrier
	s_setprio 1
	s_waitcnt lgkmcnt(0)
	v_mfma_f32_16x16x32_bf16 v[126:129], v[144:147], v[176:179], v[126:129]
	v_mfma_f32_16x16x32_bf16 v[122:125], v[152:155], v[176:179], v[122:125]
	v_mfma_f32_16x16x32_bf16 v[114:117], v[144:147], v[184:187], v[114:117]
	v_mfma_f32_16x16x32_bf16 v[106:109], v[152:155], v[184:187], v[106:109]
	v_mfma_f32_16x16x32_bf16 v[98:101], v[144:147], v[204:207], v[98:101]
	v_mfma_f32_16x16x32_bf16 v[90:93], v[152:155], v[204:207], v[90:93]
	v_mfma_f32_16x16x32_bf16 v[82:85], v[144:147], v[212:215], v[82:85]
	v_mfma_f32_16x16x32_bf16 v[74:77], v[152:155], v[212:215], v[74:77]
	v_mfma_f32_16x16x32_bf16 v[126:129], v[148:151], v[180:183], v[126:129]
	v_mfma_f32_16x16x32_bf16 v[122:125], v[156:159], v[180:183], v[122:125]
	v_mfma_f32_16x16x32_bf16 v[114:117], v[148:151], v[188:191], v[114:117]
	v_mfma_f32_16x16x32_bf16 v[106:109], v[156:159], v[188:191], v[106:109]
	v_mfma_f32_16x16x32_bf16 v[98:101], v[148:151], v[208:211], v[98:101]
	v_mfma_f32_16x16x32_bf16 v[90:93], v[156:159], v[208:211], v[90:93]
	v_mfma_f32_16x16x32_bf16 v[82:85], v[148:151], v[216:219], v[82:85]
	v_mfma_f32_16x16x32_bf16 v[74:77], v[156:159], v[216:219], v[74:77]
	s_setprio 0
	s_setprio 1
	v_mfma_f32_16x16x32_bf16 v[118:121], v[160:163], v[176:179], v[118:121]
	v_mfma_f32_16x16x32_bf16 v[110:113], v[168:171], v[176:179], v[110:113]
	v_mfma_f32_16x16x32_bf16 v[102:105], v[160:163], v[184:187], v[102:105]
	v_mfma_f32_16x16x32_bf16 v[94:97], v[168:171], v[184:187], v[94:97]
	v_mfma_f32_16x16x32_bf16 v[86:89], v[160:163], v[204:207], v[86:89]
	v_mfma_f32_16x16x32_bf16 v[78:81], v[168:171], v[204:207], v[78:81]
	v_mfma_f32_16x16x32_bf16 v[70:73], v[160:163], v[212:215], v[70:73]
	v_mfma_f32_16x16x32_bf16 v[66:69], v[168:171], v[212:215], v[66:69]
	v_mfma_f32_16x16x32_bf16 v[118:121], v[164:167], v[180:183], v[118:121]
	v_mfma_f32_16x16x32_bf16 v[110:113], v[172:175], v[180:183], v[110:113]
	v_mfma_f32_16x16x32_bf16 v[102:105], v[164:167], v[188:191], v[102:105]
	v_mfma_f32_16x16x32_bf16 v[94:97], v[172:175], v[188:191], v[94:97]
	v_mfma_f32_16x16x32_bf16 v[86:89], v[164:167], v[208:211], v[86:89]
	v_mfma_f32_16x16x32_bf16 v[78:81], v[172:175], v[208:211], v[78:81]
	v_mfma_f32_16x16x32_bf16 v[70:73], v[164:167], v[216:219], v[70:73]
	v_mfma_f32_16x16x32_bf16 v[66:69], v[172:175], v[216:219], v[66:69]
	s_setprio 0
	s_barrier
	s_add_u32 s100, s38, 0x80
	s_addc_u32 s101, s39, 0
	s_add_u32 s98, s42, 0x80
	s_addc_u32 s99, s43, 0
	s_mov_b32 m0, s45
	ds_read_b128 v[176:179], v141 offset:49152
	ds_read_b128 v[180:183], v141 offset:50176
	ds_read_b128 v[184:187], v141 offset:51200
	ds_read_b128 v[188:191], v141 offset:52224
	ds_read_b128 v[204:207], v141 offset:53248
	ds_read_b128 v[208:211], v141 offset:54272
	ds_read_b128 v[212:215], v141 offset:55296
	ds_read_b128 v[216:219], v141 offset:56320
	global_load_lds_dwordx4 v0, s[98:99]
	s_mov_b32 m0, s44
	s_nop 0
	global_load_lds_dwordx4 v130, s[98:99]
	s_mov_b32 m0, s65
	s_nop 0
	global_load_lds_dwordx4 v0, s[30:31]
	s_mov_b32 m0, s64
	s_nop 0
	global_load_lds_dwordx4 v130, s[30:31]
	s_mov_b32 m0, s55
	s_nop 0
	global_load_lds_dwordx4 v134, s[100:101]
	s_mov_b32 m0, s56
	s_nop 0
	global_load_lds_dwordx4 v132, s[100:101]
	s_waitcnt vmcnt(8)
	s_waitcnt lgkmcnt(0)
	s_barrier
	s_setprio 1
	s_waitcnt lgkmcnt(0)
	v_mfma_f32_16x16x32_bf16 v[62:65], v[144:147], v[176:179], v[62:65]
	v_mfma_f32_16x16x32_bf16 v[58:61], v[152:155], v[176:179], v[58:61]
	v_mfma_f32_16x16x32_bf16 v[50:53], v[144:147], v[184:187], v[50:53]
	v_mfma_f32_16x16x32_bf16 v[42:45], v[152:155], v[184:187], v[42:45]
	v_mfma_f32_16x16x32_bf16 v[34:37], v[144:147], v[204:207], v[34:37]
	v_mfma_f32_16x16x32_bf16 v[26:29], v[152:155], v[204:207], v[26:29]
	v_mfma_f32_16x16x32_bf16 v[18:21], v[144:147], v[212:215], v[18:21]
	v_mfma_f32_16x16x32_bf16 v[10:13], v[152:155], v[212:215], v[10:13]
	v_mfma_f32_16x16x32_bf16 v[62:65], v[148:151], v[180:183], v[62:65]
	v_mfma_f32_16x16x32_bf16 v[58:61], v[156:159], v[180:183], v[58:61]
	v_mfma_f32_16x16x32_bf16 v[50:53], v[148:151], v[188:191], v[50:53]
	v_mfma_f32_16x16x32_bf16 v[42:45], v[156:159], v[188:191], v[42:45]
	v_mfma_f32_16x16x32_bf16 v[34:37], v[148:151], v[208:211], v[34:37]
	v_mfma_f32_16x16x32_bf16 v[26:29], v[156:159], v[208:211], v[26:29]
	v_mfma_f32_16x16x32_bf16 v[18:21], v[148:151], v[216:219], v[18:21]
	v_mfma_f32_16x16x32_bf16 v[10:13], v[156:159], v[216:219], v[10:13]
	s_setprio 0
	s_setprio 1
	v_mfma_f32_16x16x32_bf16 v[54:57], v[160:163], v[176:179], v[54:57]
	v_mfma_f32_16x16x32_bf16 v[46:49], v[168:171], v[176:179], v[46:49]
	v_mfma_f32_16x16x32_bf16 v[38:41], v[160:163], v[184:187], v[38:41]
	v_mfma_f32_16x16x32_bf16 v[30:33], v[168:171], v[184:187], v[30:33]
	v_mfma_f32_16x16x32_bf16 v[22:25], v[160:163], v[204:207], v[22:25]
	v_mfma_f32_16x16x32_bf16 v[14:17], v[168:171], v[204:207], v[14:17]
	v_mfma_f32_16x16x32_bf16 v[6:9], v[160:163], v[212:215], v[6:9]
	v_mfma_f32_16x16x32_bf16 v[2:5], v[168:171], v[212:215], v[2:5]
	v_mfma_f32_16x16x32_bf16 v[54:57], v[164:167], v[180:183], v[54:57]
	v_mfma_f32_16x16x32_bf16 v[46:49], v[172:175], v[180:183], v[46:49]
	v_mfma_f32_16x16x32_bf16 v[38:41], v[164:167], v[188:191], v[38:41]
	v_mfma_f32_16x16x32_bf16 v[30:33], v[172:175], v[188:191], v[30:33]
	v_mfma_f32_16x16x32_bf16 v[22:25], v[164:167], v[208:211], v[22:25]
	v_mfma_f32_16x16x32_bf16 v[14:17], v[172:175], v[208:211], v[14:17]
	v_mfma_f32_16x16x32_bf16 v[6:9], v[164:167], v[216:219], v[6:9]
	v_mfma_f32_16x16x32_bf16 v[2:5], v[172:175], v[216:219], v[2:5]
	s_setprio 0
	s_barrier
	s_movk_i32 s36, 0x100
	s_andn2_b64 vcc, exec, s[26:27]
	s_mov_b64 s[30:31], -1
	s_mov_b64 s[26:27], 0
	s_cbranch_vccz .LBB0_361
	s_branch .Lpeel_exit_2
.LBB0_361:
	s_nop 0
	s_add_u32 s37, s24, s36
	s_addc_u32 s44, s25, 0
	s_add_u32 s42, s37, 0x100
	s_addc_u32 s43, s44, 0
	s_and_b64 s[38:39], s[30:31], exec
	s_cselect_b32 s39, s11, s43
	s_cselect_b32 s38, s40, s42
	s_add_u32 s36, s22, s36
	s_addc_u32 s42, s23, 0
	s_add_u32 s36, s36, 0x100
	s_addc_u32 s42, s42, 0
	s_add_i32 s64, 0, 0x10000
	s_and_b64 s[30:31], s[30:31], exec
	s_cselect_b32 s43, s9, s42
	s_cselect_b32 s42, s41, s36
	s_add_i32 s31, 0, 0x14000
	s_add_u32 s52, s37, 0x10080
	s_addc_u32 s53, s44, 0
	s_add_i32 s63, s64, s19
	s_add_i32 m0, s21, 0xc000
	s_add_i32 s66, s21, 0xe000
	s_add_i32 s60, s63, 0x2000
	s_add_u32 s50, s42, 0x10000
	ds_read_b128 v[144:147], v253
	ds_read_b128 v[148:151], v253 offset:1024
	ds_read_b128 v[152:155], v253 offset:2048
	ds_read_b128 v[156:159], v253 offset:3072
	s_addc_u32 s51, s43, 0
	s_add_i32 s62, s31, s19
	ds_read_b128 v[160:163], v253 offset:16384
	ds_read_b128 v[164:167], v253 offset:17408
	ds_read_b128 v[168:171], v253 offset:18432
	ds_read_b128 v[172:175], v253 offset:19456
	s_add_i32 s61, s62, 0x2000
	s_add_i32 s59, 0, 0x18000
	s_add_i32 s58, 0, 0x1c000
	s_add_u32 s36, s38, 0x10000
	s_addc_u32 s37, s39, 0
	s_add_i32 s45, s59, s19
	s_add_i32 s44, s45, 0x2000
	s_add_u32 s30, s42, 0x10080
	s_addc_u32 s31, s43, 0
	s_add_i32 s65, s58, s19
	s_add_i32 s64, s65, 0x2000
	ds_read_b128 v[176:179], v141
	ds_read_b128 v[180:183], v141 offset:1024
	ds_read_b128 v[184:187], v141 offset:2048
	ds_read_b128 v[188:191], v141 offset:3072
	ds_read_b128 v[204:207], v141 offset:4096
	ds_read_b128 v[208:211], v141 offset:5120
	ds_read_b128 v[212:215], v141 offset:6144
	ds_read_b128 v[216:219], v141 offset:7168
	global_load_lds_dwordx4 v134, s[52:53]
	s_mov_b32 m0, s66
	s_nop 0
	global_load_lds_dwordx4 v132, s[52:53]
	s_waitcnt vmcnt(8)
	s_waitcnt lgkmcnt(0)
	s_barrier
	s_setprio 1
	s_waitcnt lgkmcnt(0)
	v_mfma_f32_16x16x32_bf16 v[126:129], v[144:147], v[176:179], v[126:129]
	v_mfma_f32_16x16x32_bf16 v[122:125], v[152:155], v[176:179], v[122:125]
	v_mfma_f32_16x16x32_bf16 v[114:117], v[144:147], v[184:187], v[114:117]
	v_mfma_f32_16x16x32_bf16 v[106:109], v[152:155], v[184:187], v[106:109]
	v_mfma_f32_16x16x32_bf16 v[98:101], v[144:147], v[204:207], v[98:101]
	v_mfma_f32_16x16x32_bf16 v[90:93], v[152:155], v[204:207], v[90:93]
	v_mfma_f32_16x16x32_bf16 v[82:85], v[144:147], v[212:215], v[82:85]
	v_mfma_f32_16x16x32_bf16 v[74:77], v[152:155], v[212:215], v[74:77]
	v_mfma_f32_16x16x32_bf16 v[126:129], v[148:151], v[180:183], v[126:129]
	v_mfma_f32_16x16x32_bf16 v[122:125], v[156:159], v[180:183], v[122:125]
	v_mfma_f32_16x16x32_bf16 v[114:117], v[148:151], v[188:191], v[114:117]
	v_mfma_f32_16x16x32_bf16 v[106:109], v[156:159], v[188:191], v[106:109]
	v_mfma_f32_16x16x32_bf16 v[98:101], v[148:151], v[208:211], v[98:101]
	v_mfma_f32_16x16x32_bf16 v[90:93], v[156:159], v[208:211], v[90:93]
	v_mfma_f32_16x16x32_bf16 v[82:85], v[148:151], v[216:219], v[82:85]
	v_mfma_f32_16x16x32_bf16 v[74:77], v[156:159], v[216:219], v[74:77]
	s_setprio 0
	s_setprio 1
	v_mfma_f32_16x16x32_bf16 v[118:121], v[160:163], v[176:179], v[118:121]
	v_mfma_f32_16x16x32_bf16 v[110:113], v[168:171], v[176:179], v[110:113]
	v_mfma_f32_16x16x32_bf16 v[102:105], v[160:163], v[184:187], v[102:105]
	v_mfma_f32_16x16x32_bf16 v[94:97], v[168:171], v[184:187], v[94:97]
	v_mfma_f32_16x16x32_bf16 v[86:89], v[160:163], v[204:207], v[86:89]
	v_mfma_f32_16x16x32_bf16 v[78:81], v[168:171], v[204:207], v[78:81]
	v_mfma_f32_16x16x32_bf16 v[70:73], v[160:163], v[212:215], v[70:73]
	v_mfma_f32_16x16x32_bf16 v[66:69], v[168:171], v[212:215], v[66:69]
	v_mfma_f32_16x16x32_bf16 v[118:121], v[164:167], v[180:183], v[118:121]
	v_mfma_f32_16x16x32_bf16 v[110:113], v[172:175], v[180:183], v[110:113]
	v_mfma_f32_16x16x32_bf16 v[102:105], v[164:167], v[188:191], v[102:105]
	v_mfma_f32_16x16x32_bf16 v[94:97], v[172:175], v[188:191], v[94:97]
	v_mfma_f32_16x16x32_bf16 v[86:89], v[164:167], v[208:211], v[86:89]
	v_mfma_f32_16x16x32_bf16 v[78:81], v[172:175], v[208:211], v[78:81]
	v_mfma_f32_16x16x32_bf16 v[70:73], v[164:167], v[216:219], v[70:73]
	v_mfma_f32_16x16x32_bf16 v[66:69], v[172:175], v[216:219], v[66:69]
	s_setprio 0
	s_barrier
	s_mov_b32 m0, s63
	ds_read_b128 v[176:179], v141 offset:16384
	ds_read_b128 v[180:183], v141 offset:17408
	ds_read_b128 v[184:187], v141 offset:18432
	ds_read_b128 v[188:191], v141 offset:19456
	ds_read_b128 v[204:207], v141 offset:20480
	ds_read_b128 v[208:211], v141 offset:21504
	ds_read_b128 v[212:215], v141 offset:22528
	ds_read_b128 v[216:219], v141 offset:23552
	global_load_lds_dwordx4 v0, s[42:43]
	s_mov_b32 m0, s60
	s_nop 0
	global_load_lds_dwordx4 v130, s[42:43]
	s_mov_b32 m0, s62
	s_nop 0
	global_load_lds_dwordx4 v0, s[50:51]
	s_mov_b32 m0, s61
	s_nop 0
	global_load_lds_dwordx4 v130, s[50:51]
	s_mov_b32 m0, s21
	s_nop 0
	global_load_lds_dwordx4 v134, s[38:39]
	s_mov_b32 m0, s35
	s_nop 0
	global_load_lds_dwordx4 v132, s[38:39]
	s_waitcnt vmcnt(8)
	s_waitcnt lgkmcnt(0)
	s_barrier
	s_setprio 1
	s_waitcnt lgkmcnt(0)
	v_mfma_f32_16x16x32_bf16 v[62:65], v[144:147], v[176:179], v[62:65]
	v_mfma_f32_16x16x32_bf16 v[58:61], v[152:155], v[176:179], v[58:61]
	v_mfma_f32_16x16x32_bf16 v[50:53], v[144:147], v[184:187], v[50:53]
	v_mfma_f32_16x16x32_bf16 v[42:45], v[152:155], v[184:187], v[42:45]
	v_mfma_f32_16x16x32_bf16 v[34:37], v[144:147], v[204:207], v[34:37]
	v_mfma_f32_16x16x32_bf16 v[26:29], v[152:155], v[204:207], v[26:29]
	v_mfma_f32_16x16x32_bf16 v[18:21], v[144:147], v[212:215], v[18:21]
	v_mfma_f32_16x16x32_bf16 v[10:13], v[152:155], v[212:215], v[10:13]
	v_mfma_f32_16x16x32_bf16 v[62:65], v[148:151], v[180:183], v[62:65]
	v_mfma_f32_16x16x32_bf16 v[58:61], v[156:159], v[180:183], v[58:61]
	v_mfma_f32_16x16x32_bf16 v[50:53], v[148:151], v[188:191], v[50:53]
	v_mfma_f32_16x16x32_bf16 v[42:45], v[156:159], v[188:191], v[42:45]
	v_mfma_f32_16x16x32_bf16 v[34:37], v[148:151], v[208:211], v[34:37]
	v_mfma_f32_16x16x32_bf16 v[26:29], v[156:159], v[208:211], v[26:29]
	v_mfma_f32_16x16x32_bf16 v[18:21], v[148:151], v[216:219], v[18:21]
	v_mfma_f32_16x16x32_bf16 v[10:13], v[156:159], v[216:219], v[10:13]
	s_setprio 0
	s_setprio 1
	v_mfma_f32_16x16x32_bf16 v[54:57], v[160:163], v[176:179], v[54:57]
	v_mfma_f32_16x16x32_bf16 v[46:49], v[168:171], v[176:179], v[46:49]
	v_mfma_f32_16x16x32_bf16 v[38:41], v[160:163], v[184:187], v[38:41]
	v_mfma_f32_16x16x32_bf16 v[30:33], v[168:171], v[184:187], v[30:33]
	v_mfma_f32_16x16x32_bf16 v[22:25], v[160:163], v[204:207], v[22:25]
	v_mfma_f32_16x16x32_bf16 v[14:17], v[168:171], v[204:207], v[14:17]
	v_mfma_f32_16x16x32_bf16 v[6:9], v[160:163], v[212:215], v[6:9]
	v_mfma_f32_16x16x32_bf16 v[2:5], v[168:171], v[212:215], v[2:5]
	v_mfma_f32_16x16x32_bf16 v[54:57], v[164:167], v[180:183], v[54:57]
	v_mfma_f32_16x16x32_bf16 v[46:49], v[172:175], v[180:183], v[46:49]
	v_mfma_f32_16x16x32_bf16 v[38:41], v[164:167], v[188:191], v[38:41]
	v_mfma_f32_16x16x32_bf16 v[30:33], v[172:175], v[188:191], v[30:33]
	v_mfma_f32_16x16x32_bf16 v[22:25], v[164:167], v[208:211], v[22:25]
	v_mfma_f32_16x16x32_bf16 v[14:17], v[172:175], v[208:211], v[14:17]
	v_mfma_f32_16x16x32_bf16 v[6:9], v[164:167], v[216:219], v[6:9]
	v_mfma_f32_16x16x32_bf16 v[2:5], v[172:175], v[216:219], v[2:5]
	s_setprio 0
	s_barrier
	ds_read_b128 v[144:147], v253 offset:32768
	ds_read_b128 v[148:151], v253 offset:33792
	ds_read_b128 v[152:155], v253 offset:34816
	ds_read_b128 v[156:159], v253 offset:35840
	ds_read_b128 v[160:163], v253 offset:49152
	ds_read_b128 v[164:167], v253 offset:50176
	ds_read_b128 v[168:171], v253 offset:51200
	ds_read_b128 v[172:175], v253 offset:52224
	s_mov_b32 m0, s46
	ds_read_b128 v[176:179], v141 offset:32768
	ds_read_b128 v[180:183], v141 offset:33792
	ds_read_b128 v[184:187], v141 offset:34816
	ds_read_b128 v[188:191], v141 offset:35840
	ds_read_b128 v[204:207], v141 offset:36864
	ds_read_b128 v[208:211], v141 offset:37888
	ds_read_b128 v[212:215], v141 offset:38912
	ds_read_b128 v[216:219], v141 offset:39936
	global_load_lds_dwordx4 v134, s[36:37]
	s_mov_b32 m0, s54
	s_nop 0
	global_load_lds_dwordx4 v132, s[36:37]
	s_waitcnt vmcnt(8)
	s_waitcnt lgkmcnt(0)
	s_barrier
	s_setprio 1
	s_waitcnt lgkmcnt(0)
	v_mfma_f32_16x16x32_bf16 v[126:129], v[144:147], v[176:179], v[126:129]
	v_mfma_f32_16x16x32_bf16 v[122:125], v[152:155], v[176:179], v[122:125]
	v_mfma_f32_16x16x32_bf16 v[114:117], v[144:147], v[184:187], v[114:117]
	v_mfma_f32_16x16x32_bf16 v[106:109], v[152:155], v[184:187], v[106:109]
	v_mfma_f32_16x16x32_bf16 v[98:101], v[144:147], v[204:207], v[98:101]
	v_mfma_f32_16x16x32_bf16 v[90:93], v[152:155], v[204:207], v[90:93]
	v_mfma_f32_16x16x32_bf16 v[82:85], v[144:147], v[212:215], v[82:85]
	v_mfma_f32_16x16x32_bf16 v[74:77], v[152:155], v[212:215], v[74:77]
	v_mfma_f32_16x16x32_bf16 v[126:129], v[148:151], v[180:183], v[126:129]
	v_mfma_f32_16x16x32_bf16 v[122:125], v[156:159], v[180:183], v[122:125]
	v_mfma_f32_16x16x32_bf16 v[114:117], v[148:151], v[188:191], v[114:117]
	v_mfma_f32_16x16x32_bf16 v[106:109], v[156:159], v[188:191], v[106:109]
	v_mfma_f32_16x16x32_bf16 v[98:101], v[148:151], v[208:211], v[98:101]
	v_mfma_f32_16x16x32_bf16 v[90:93], v[156:159], v[208:211], v[90:93]
	v_mfma_f32_16x16x32_bf16 v[82:85], v[148:151], v[216:219], v[82:85]
	v_mfma_f32_16x16x32_bf16 v[74:77], v[156:159], v[216:219], v[74:77]
	s_setprio 0
	s_setprio 1
	v_mfma_f32_16x16x32_bf16 v[118:121], v[160:163], v[176:179], v[118:121]
	v_mfma_f32_16x16x32_bf16 v[110:113], v[168:171], v[176:179], v[110:113]
	v_mfma_f32_16x16x32_bf16 v[102:105], v[160:163], v[184:187], v[102:105]
	v_mfma_f32_16x16x32_bf16 v[94:97], v[168:171], v[184:187], v[94:97]
	v_mfma_f32_16x16x32_bf16 v[86:89], v[160:163], v[204:207], v[86:89]
	v_mfma_f32_16x16x32_bf16 v[78:81], v[168:171], v[204:207], v[78:81]
	v_mfma_f32_16x16x32_bf16 v[70:73], v[160:163], v[212:215], v[70:73]
	v_mfma_f32_16x16x32_bf16 v[66:69], v[168:171], v[212:215], v[66:69]
	v_mfma_f32_16x16x32_bf16 v[118:121], v[164:167], v[180:183], v[118:121]
	v_mfma_f32_16x16x32_bf16 v[110:113], v[172:175], v[180:183], v[110:113]
	v_mfma_f32_16x16x32_bf16 v[102:105], v[164:167], v[188:191], v[102:105]
	v_mfma_f32_16x16x32_bf16 v[94:97], v[172:175], v[188:191], v[94:97]
	v_mfma_f32_16x16x32_bf16 v[86:89], v[164:167], v[208:211], v[86:89]
	v_mfma_f32_16x16x32_bf16 v[78:81], v[172:175], v[208:211], v[78:81]
	v_mfma_f32_16x16x32_bf16 v[70:73], v[164:167], v[216:219], v[70:73]
	v_mfma_f32_16x16x32_bf16 v[66:69], v[172:175], v[216:219], v[66:69]
	s_setprio 0
	s_barrier
	s_add_u32 s100, s38, 0x80
	s_addc_u32 s101, s39, 0
	s_add_u32 s98, s42, 0x80
	s_addc_u32 s99, s43, 0
	s_mov_b32 m0, s45
	ds_read_b128 v[176:179], v141 offset:49152
	ds_read_b128 v[180:183], v141 offset:50176
	ds_read_b128 v[184:187], v141 offset:51200
	ds_read_b128 v[188:191], v141 offset:52224
	ds_read_b128 v[204:207], v141 offset:53248
	ds_read_b128 v[208:211], v141 offset:54272
	ds_read_b128 v[212:215], v141 offset:55296
	ds_read_b128 v[216:219], v141 offset:56320
	global_load_lds_dwordx4 v0, s[98:99]
	s_mov_b32 m0, s44
	s_nop 0
	global_load_lds_dwordx4 v130, s[98:99]
	s_mov_b32 m0, s65
	s_nop 0
	global_load_lds_dwordx4 v0, s[30:31]
	s_mov_b32 m0, s64
	s_nop 0
	global_load_lds_dwordx4 v130, s[30:31]
	s_mov_b32 m0, s55
	s_nop 0
	global_load_lds_dwordx4 v134, s[100:101]
	s_mov_b32 m0, s56
	s_nop 0
	global_load_lds_dwordx4 v132, s[100:101]
	s_waitcnt vmcnt(8)
	s_waitcnt lgkmcnt(0)
	s_barrier
	s_setprio 1
	s_waitcnt lgkmcnt(0)
	v_mfma_f32_16x16x32_bf16 v[62:65], v[144:147], v[176:179], v[62:65]
	v_mfma_f32_16x16x32_bf16 v[58:61], v[152:155], v[176:179], v[58:61]
	v_mfma_f32_16x16x32_bf16 v[50:53], v[144:147], v[184:187], v[50:53]
	v_mfma_f32_16x16x32_bf16 v[42:45], v[152:155], v[184:187], v[42:45]
	v_mfma_f32_16x16x32_bf16 v[34:37], v[144:147], v[204:207], v[34:37]
	v_mfma_f32_16x16x32_bf16 v[26:29], v[152:155], v[204:207], v[26:29]
	v_mfma_f32_16x16x32_bf16 v[18:21], v[144:147], v[212:215], v[18:21]
	v_mfma_f32_16x16x32_bf16 v[10:13], v[152:155], v[212:215], v[10:13]
	v_mfma_f32_16x16x32_bf16 v[62:65], v[148:151], v[180:183], v[62:65]
	v_mfma_f32_16x16x32_bf16 v[58:61], v[156:159], v[180:183], v[58:61]
	v_mfma_f32_16x16x32_bf16 v[50:53], v[148:151], v[188:191], v[50:53]
	v_mfma_f32_16x16x32_bf16 v[42:45], v[156:159], v[188:191], v[42:45]
	v_mfma_f32_16x16x32_bf16 v[34:37], v[148:151], v[208:211], v[34:37]
	v_mfma_f32_16x16x32_bf16 v[26:29], v[156:159], v[208:211], v[26:29]
	v_mfma_f32_16x16x32_bf16 v[18:21], v[148:151], v[216:219], v[18:21]
	v_mfma_f32_16x16x32_bf16 v[10:13], v[156:159], v[216:219], v[10:13]
	s_setprio 0
	s_setprio 1
	v_mfma_f32_16x16x32_bf16 v[54:57], v[160:163], v[176:179], v[54:57]
	v_mfma_f32_16x16x32_bf16 v[46:49], v[168:171], v[176:179], v[46:49]
	v_mfma_f32_16x16x32_bf16 v[38:41], v[160:163], v[184:187], v[38:41]
	v_mfma_f32_16x16x32_bf16 v[30:33], v[168:171], v[184:187], v[30:33]
	v_mfma_f32_16x16x32_bf16 v[22:25], v[160:163], v[204:207], v[22:25]
	v_mfma_f32_16x16x32_bf16 v[14:17], v[168:171], v[204:207], v[14:17]
	v_mfma_f32_16x16x32_bf16 v[6:9], v[160:163], v[212:215], v[6:9]
	v_mfma_f32_16x16x32_bf16 v[2:5], v[168:171], v[212:215], v[2:5]
	v_mfma_f32_16x16x32_bf16 v[54:57], v[164:167], v[180:183], v[54:57]
	v_mfma_f32_16x16x32_bf16 v[46:49], v[172:175], v[180:183], v[46:49]
	v_mfma_f32_16x16x32_bf16 v[38:41], v[164:167], v[188:191], v[38:41]
	v_mfma_f32_16x16x32_bf16 v[30:33], v[172:175], v[188:191], v[30:33]
	v_mfma_f32_16x16x32_bf16 v[22:25], v[164:167], v[208:211], v[22:25]
	v_mfma_f32_16x16x32_bf16 v[14:17], v[172:175], v[208:211], v[14:17]
	v_mfma_f32_16x16x32_bf16 v[6:9], v[164:167], v[216:219], v[6:9]
	v_mfma_f32_16x16x32_bf16 v[2:5], v[172:175], v[216:219], v[2:5]
	s_setprio 0
	s_barrier
	s_movk_i32 s36, 0x100
	s_andn2_b64 vcc, exec, s[26:27]
	s_mov_b64 s[30:31], -1
	s_mov_b64 s[26:27], 0
	s_cbranch_vccz .LBB0_361

.LBB0_976:
	s_add_i32 s13, s27, -2
	s_add_u32 s38, s38, 0x80080
	s_addc_u32 s39, s39, 0
	s_add_u32 s15, s42, 0x100
	s_addc_u32 s21, s43, 0
	s_mov_b32 s33, 0
	s_waitcnt vmcnt(0)
	v_add_u32_e32 v253, 0x10000, v192
	s_add_i32 s37, s33, 2
	s_add_u32 s40, s38, 0xfff80080
	s_addc_u32 s41, s39, -1
	s_add_i32 s44, 0, 0x10000
	s_cmp_eq_u32 s13, s33
	s_cselect_b32 s51, s23, s41
	s_cselect_b32 s50, s22, s40
	s_cselect_b32 s43, s25, s21
	s_cselect_b32 s42, s24, s15
	s_add_i32 s33, 0, 0x14000
	ds_read_b128 v[122:125], v253
	ds_read_b128 v[126:129], v253 offset:1024
	ds_read_b128 v[130:133], v253 offset:2048
	ds_read_b128 v[134:137], v253 offset:3072
	ds_read_b128 v[146:149], v253 offset:16384
	ds_read_b128 v[150:153], v253 offset:17408
	ds_read_b128 v[154:157], v253 offset:18432
	ds_read_b128 v[158:161], v253 offset:19456
	s_add_i32 m0, s31, 0xc000
	ds_read_b128 v[162:165], v204
	ds_read_b128 v[176:179], v204 offset:1024
	ds_read_b128 v[180:183], v204 offset:2048
	ds_read_b128 v[184:187], v204 offset:3072
	ds_read_b128 v[206:209], v204 offset:4096
	ds_read_b128 v[210:213], v204 offset:5120
	ds_read_b128 v[214:217], v204 offset:6144
	ds_read_b128 v[218:221], v204 offset:7168
	global_load_lds_dwordx4 v172, s[38:39]
	s_add_i32 m0, s31, 0xe000
	s_nop 0
	global_load_lds_dwordx4 v174, s[38:39]
	s_waitcnt vmcnt(8)
	s_waitcnt lgkmcnt(0)
	s_barrier
	s_setprio 1
	s_waitcnt lgkmcnt(0)
	v_mfma_f32_16x16x32_bf16 v[142:145], v[122:125], v[162:165], 0
	v_mfma_f32_16x16x32_bf16 v[138:141], v[130:133], v[162:165], 0
	v_mfma_f32_16x16x32_bf16 v[118:121], v[122:125], v[180:183], 0
	v_mfma_f32_16x16x32_bf16 v[110:113], v[130:133], v[180:183], 0
	v_mfma_f32_16x16x32_bf16 v[98:101], v[122:125], v[206:209], 0
	v_mfma_f32_16x16x32_bf16 v[90:93], v[130:133], v[206:209], 0
	v_mfma_f32_16x16x32_bf16 v[82:85], v[122:125], v[214:217], 0
	v_mfma_f32_16x16x32_bf16 v[74:77], v[130:133], v[214:217], 0
	v_mfma_f32_16x16x32_bf16 v[142:145], v[126:129], v[176:179], v[142:145]
	v_mfma_f32_16x16x32_bf16 v[138:141], v[134:137], v[176:179], v[138:141]
	v_mfma_f32_16x16x32_bf16 v[118:121], v[126:129], v[184:187], v[118:121]
	v_mfma_f32_16x16x32_bf16 v[110:113], v[134:137], v[184:187], v[110:113]
	v_mfma_f32_16x16x32_bf16 v[98:101], v[126:129], v[210:213], v[98:101]
	v_mfma_f32_16x16x32_bf16 v[90:93], v[134:137], v[210:213], v[90:93]
	v_mfma_f32_16x16x32_bf16 v[82:85], v[126:129], v[218:221], v[82:85]
	v_mfma_f32_16x16x32_bf16 v[74:77], v[134:137], v[218:221], v[74:77]
	s_setprio 0
	s_setprio 1
	v_mfma_f32_16x16x32_bf16 v[114:117], v[146:149], v[162:165], 0
	v_mfma_f32_16x16x32_bf16 v[106:109], v[154:157], v[162:165], 0
	v_mfma_f32_16x16x32_bf16 v[102:105], v[146:149], v[180:183], 0
	v_mfma_f32_16x16x32_bf16 v[94:97], v[154:157], v[180:183], 0
	v_mfma_f32_16x16x32_bf16 v[86:89], v[146:149], v[206:209], 0
	v_mfma_f32_16x16x32_bf16 v[78:81], v[154:157], v[206:209], 0
	v_mfma_f32_16x16x32_bf16 v[70:73], v[146:149], v[214:217], 0
	v_mfma_f32_16x16x32_bf16 v[66:69], v[154:157], v[214:217], 0
	v_mfma_f32_16x16x32_bf16 v[114:117], v[150:153], v[176:179], v[114:117]
	v_mfma_f32_16x16x32_bf16 v[106:109], v[158:161], v[176:179], v[106:109]
	v_mfma_f32_16x16x32_bf16 v[102:105], v[150:153], v[184:187], v[102:105]
	v_mfma_f32_16x16x32_bf16 v[94:97], v[158:161], v[184:187], v[94:97]
	v_mfma_f32_16x16x32_bf16 v[86:89], v[150:153], v[210:213], v[86:89]
	v_mfma_f32_16x16x32_bf16 v[78:81], v[158:161], v[210:213], v[78:81]
	v_mfma_f32_16x16x32_bf16 v[70:73], v[150:153], v[218:221], v[70:73]
	v_mfma_f32_16x16x32_bf16 v[66:69], v[158:161], v[218:221], v[66:69]
	s_setprio 0
	s_barrier
	s_add_i32 s40, s44, s19
	s_mov_b32 m0, s40
	ds_read_b128 v[162:165], v204 offset:16384
	ds_read_b128 v[176:179], v204 offset:17408
	ds_read_b128 v[180:183], v204 offset:18432
	ds_read_b128 v[184:187], v204 offset:19456
	ds_read_b128 v[206:209], v204 offset:20480
	ds_read_b128 v[210:213], v204 offset:21504
	ds_read_b128 v[214:217], v204 offset:22528
	ds_read_b128 v[218:221], v204 offset:23552
	global_load_lds_dwordx4 v0, s[42:43]
	s_add_i32 m0, s40, 0x2000
	s_add_u32 s40, s42, 0x80000
	s_addc_u32 s41, s43, 0
	s_add_i32 s33, s33, s19
	global_load_lds_dwordx4 v170, s[42:43]
	s_mov_b32 m0, s33
	s_nop 0
	global_load_lds_dwordx4 v0, s[40:41]
	s_add_i32 m0, s33, 0x2000
	s_nop 0
	global_load_lds_dwordx4 v170, s[40:41]
	s_mov_b32 m0, s31
	s_nop 0
	global_load_lds_dwordx4 v166, s[50:51]
	s_mov_b32 m0, s34
	s_nop 0
	global_load_lds_dwordx4 v168, s[50:51]
	s_waitcnt vmcnt(8)
	s_waitcnt lgkmcnt(0)
	s_barrier
	s_setprio 1
	s_waitcnt lgkmcnt(0)
	v_mfma_f32_16x16x32_bf16 v[62:65], v[122:125], v[162:165], 0
	v_mfma_f32_16x16x32_bf16 v[58:61], v[130:133], v[162:165], 0
	v_mfma_f32_16x16x32_bf16 v[50:53], v[122:125], v[180:183], 0
	v_mfma_f32_16x16x32_bf16 v[42:45], v[130:133], v[180:183], 0
	v_mfma_f32_16x16x32_bf16 v[34:37], v[122:125], v[206:209], 0
	v_mfma_f32_16x16x32_bf16 v[26:29], v[130:133], v[206:209], 0
	v_mfma_f32_16x16x32_bf16 v[18:21], v[122:125], v[214:217], 0
	v_mfma_f32_16x16x32_bf16 v[10:13], v[130:133], v[214:217], 0
	v_mfma_f32_16x16x32_bf16 v[62:65], v[126:129], v[176:179], v[62:65]
	v_mfma_f32_16x16x32_bf16 v[58:61], v[134:137], v[176:179], v[58:61]
	v_mfma_f32_16x16x32_bf16 v[50:53], v[126:129], v[184:187], v[50:53]
	v_mfma_f32_16x16x32_bf16 v[42:45], v[134:137], v[184:187], v[42:45]
	v_mfma_f32_16x16x32_bf16 v[34:37], v[126:129], v[210:213], v[34:37]
	v_mfma_f32_16x16x32_bf16 v[26:29], v[134:137], v[210:213], v[26:29]
	v_mfma_f32_16x16x32_bf16 v[18:21], v[126:129], v[218:221], v[18:21]
	v_mfma_f32_16x16x32_bf16 v[10:13], v[134:137], v[218:221], v[10:13]
	s_setprio 0
	s_setprio 1
	v_mfma_f32_16x16x32_bf16 v[54:57], v[146:149], v[162:165], 0
	v_mfma_f32_16x16x32_bf16 v[46:49], v[154:157], v[162:165], 0
	v_mfma_f32_16x16x32_bf16 v[38:41], v[146:149], v[180:183], 0
	v_mfma_f32_16x16x32_bf16 v[30:33], v[154:157], v[180:183], 0
	v_mfma_f32_16x16x32_bf16 v[22:25], v[146:149], v[206:209], 0
	v_mfma_f32_16x16x32_bf16 v[14:17], v[154:157], v[206:209], 0
	v_mfma_f32_16x16x32_bf16 v[6:9], v[146:149], v[214:217], 0
	v_mfma_f32_16x16x32_bf16 v[2:5], v[154:157], v[214:217], 0
	v_mfma_f32_16x16x32_bf16 v[54:57], v[150:153], v[176:179], v[54:57]
	v_mfma_f32_16x16x32_bf16 v[46:49], v[158:161], v[176:179], v[46:49]
	v_mfma_f32_16x16x32_bf16 v[38:41], v[150:153], v[184:187], v[38:41]
	v_mfma_f32_16x16x32_bf16 v[30:33], v[158:161], v[184:187], v[30:33]
	v_mfma_f32_16x16x32_bf16 v[22:25], v[150:153], v[210:213], v[22:25]
	v_mfma_f32_16x16x32_bf16 v[14:17], v[158:161], v[210:213], v[14:17]
	v_mfma_f32_16x16x32_bf16 v[6:9], v[150:153], v[218:221], v[6:9]
	v_mfma_f32_16x16x32_bf16 v[2:5], v[158:161], v[218:221], v[2:5]
	s_setprio 0
	s_barrier
	s_nop 0
	s_add_i32 s33, 0, 0x18000
	s_add_i32 s44, 0, 0x1c000
	ds_read_b128 v[122:125], v253 offset:32768
	ds_read_b128 v[126:129], v253 offset:33792
	ds_read_b128 v[130:133], v253 offset:34816
	ds_read_b128 v[134:137], v253 offset:35840
	ds_read_b128 v[146:149], v253 offset:49152
	ds_read_b128 v[150:153], v253 offset:50176
	ds_read_b128 v[154:157], v253 offset:51200
	ds_read_b128 v[158:161], v253 offset:52224
	s_add_u32 s40, s50, 0x80000
	s_addc_u32 s41, s51, 0
	s_mov_b32 m0, s35
	ds_read_b128 v[162:165], v204 offset:32768
	ds_read_b128 v[176:179], v204 offset:33792
	ds_read_b128 v[180:183], v204 offset:34816
	ds_read_b128 v[184:187], v204 offset:35840
	ds_read_b128 v[206:209], v204 offset:36864
	ds_read_b128 v[210:213], v204 offset:37888
	ds_read_b128 v[214:217], v204 offset:38912
	ds_read_b128 v[218:221], v204 offset:39936
	global_load_lds_dwordx4 v166, s[40:41]
	s_mov_b32 m0, s46
	s_nop 0
	global_load_lds_dwordx4 v168, s[40:41]
	s_waitcnt vmcnt(8)
	s_waitcnt lgkmcnt(0)
	s_barrier
	s_setprio 1
	s_waitcnt lgkmcnt(0)
	v_mfma_f32_16x16x32_bf16 v[142:145], v[122:125], v[162:165], v[142:145]
	v_mfma_f32_16x16x32_bf16 v[138:141], v[130:133], v[162:165], v[138:141]
	v_mfma_f32_16x16x32_bf16 v[118:121], v[122:125], v[180:183], v[118:121]
	v_mfma_f32_16x16x32_bf16 v[110:113], v[130:133], v[180:183], v[110:113]
	v_mfma_f32_16x16x32_bf16 v[98:101], v[122:125], v[206:209], v[98:101]
	v_mfma_f32_16x16x32_bf16 v[90:93], v[130:133], v[206:209], v[90:93]
	v_mfma_f32_16x16x32_bf16 v[82:85], v[122:125], v[214:217], v[82:85]
	v_mfma_f32_16x16x32_bf16 v[74:77], v[130:133], v[214:217], v[74:77]
	v_mfma_f32_16x16x32_bf16 v[142:145], v[126:129], v[176:179], v[142:145]
	v_mfma_f32_16x16x32_bf16 v[138:141], v[134:137], v[176:179], v[138:141]
	v_mfma_f32_16x16x32_bf16 v[118:121], v[126:129], v[184:187], v[118:121]
	v_mfma_f32_16x16x32_bf16 v[110:113], v[134:137], v[184:187], v[110:113]
	v_mfma_f32_16x16x32_bf16 v[98:101], v[126:129], v[210:213], v[98:101]
	v_mfma_f32_16x16x32_bf16 v[90:93], v[134:137], v[210:213], v[90:93]
	v_mfma_f32_16x16x32_bf16 v[82:85], v[126:129], v[218:221], v[82:85]
	v_mfma_f32_16x16x32_bf16 v[74:77], v[134:137], v[218:221], v[74:77]
	s_setprio 0
	s_setprio 1
	v_mfma_f32_16x16x32_bf16 v[114:117], v[146:149], v[162:165], v[114:117]
	v_mfma_f32_16x16x32_bf16 v[106:109], v[154:157], v[162:165], v[106:109]
	v_mfma_f32_16x16x32_bf16 v[102:105], v[146:149], v[180:183], v[102:105]
	v_mfma_f32_16x16x32_bf16 v[94:97], v[154:157], v[180:183], v[94:97]
	v_mfma_f32_16x16x32_bf16 v[86:89], v[146:149], v[206:209], v[86:89]
	v_mfma_f32_16x16x32_bf16 v[78:81], v[154:157], v[206:209], v[78:81]
	v_mfma_f32_16x16x32_bf16 v[70:73], v[146:149], v[214:217], v[70:73]
	v_mfma_f32_16x16x32_bf16 v[66:69], v[154:157], v[214:217], v[66:69]
	v_mfma_f32_16x16x32_bf16 v[114:117], v[150:153], v[176:179], v[114:117]
	v_mfma_f32_16x16x32_bf16 v[106:109], v[158:161], v[176:179], v[106:109]
	v_mfma_f32_16x16x32_bf16 v[102:105], v[150:153], v[184:187], v[102:105]
	v_mfma_f32_16x16x32_bf16 v[94:97], v[158:161], v[184:187], v[94:97]
	v_mfma_f32_16x16x32_bf16 v[86:89], v[150:153], v[210:213], v[86:89]
	v_mfma_f32_16x16x32_bf16 v[78:81], v[158:161], v[210:213], v[78:81]
	v_mfma_f32_16x16x32_bf16 v[70:73], v[150:153], v[218:221], v[70:73]
	v_mfma_f32_16x16x32_bf16 v[66:69], v[158:161], v[218:221], v[66:69]
	s_setprio 0
	s_barrier
	s_add_u32 s100, s40, 0xfff80080
	s_addc_u32 s101, s41, -1
	s_add_u32 s98, s42, 0x80
	s_addc_u32 s99, s43, 0
	s_add_i32 s33, s33, s19
	s_mov_b32 m0, s33
	ds_read_b128 v[162:165], v204 offset:49152
	ds_read_b128 v[176:179], v204 offset:50176
	ds_read_b128 v[180:183], v204 offset:51200
	ds_read_b128 v[184:187], v204 offset:52224
	ds_read_b128 v[206:209], v204 offset:53248
	ds_read_b128 v[210:213], v204 offset:54272
	ds_read_b128 v[214:217], v204 offset:55296
	ds_read_b128 v[218:221], v204 offset:56320
	global_load_lds_dwordx4 v0, s[98:99]
	s_add_i32 m0, s33, 0x2000
	s_add_u32 s40, s42, 0x80080
	s_addc_u32 s41, s43, 0
	s_add_i32 s33, s44, s19
	global_load_lds_dwordx4 v170, s[98:99]
	s_mov_b32 m0, s33
	s_nop 0
	global_load_lds_dwordx4 v0, s[40:41]
	s_add_i32 m0, s33, 0x2000
	s_nop 0
	global_load_lds_dwordx4 v170, s[40:41]
	s_mov_b32 m0, s54
	s_nop 0
	global_load_lds_dwordx4 v166, s[100:101]
	s_mov_b32 m0, s55
	s_nop 0
	global_load_lds_dwordx4 v168, s[100:101]
	s_waitcnt vmcnt(8)
	s_waitcnt lgkmcnt(0)
	s_barrier
	s_setprio 1
	s_waitcnt lgkmcnt(0)
	v_mfma_f32_16x16x32_bf16 v[62:65], v[122:125], v[162:165], v[62:65]
	v_mfma_f32_16x16x32_bf16 v[58:61], v[130:133], v[162:165], v[58:61]
	v_mfma_f32_16x16x32_bf16 v[50:53], v[122:125], v[180:183], v[50:53]
	v_mfma_f32_16x16x32_bf16 v[42:45], v[130:133], v[180:183], v[42:45]
	v_mfma_f32_16x16x32_bf16 v[34:37], v[122:125], v[206:209], v[34:37]
	v_mfma_f32_16x16x32_bf16 v[26:29], v[130:133], v[206:209], v[26:29]
	v_mfma_f32_16x16x32_bf16 v[18:21], v[122:125], v[214:217], v[18:21]
	v_mfma_f32_16x16x32_bf16 v[10:13], v[130:133], v[214:217], v[10:13]
	v_mfma_f32_16x16x32_bf16 v[62:65], v[126:129], v[176:179], v[62:65]
	v_mfma_f32_16x16x32_bf16 v[58:61], v[134:137], v[176:179], v[58:61]
	v_mfma_f32_16x16x32_bf16 v[50:53], v[126:129], v[184:187], v[50:53]
	v_mfma_f32_16x16x32_bf16 v[42:45], v[134:137], v[184:187], v[42:45]
	v_mfma_f32_16x16x32_bf16 v[34:37], v[126:129], v[210:213], v[34:37]
	v_mfma_f32_16x16x32_bf16 v[26:29], v[134:137], v[210:213], v[26:29]
	v_mfma_f32_16x16x32_bf16 v[18:21], v[126:129], v[218:221], v[18:21]
	v_mfma_f32_16x16x32_bf16 v[10:13], v[134:137], v[218:221], v[10:13]
	s_setprio 0
	s_setprio 1
	v_mfma_f32_16x16x32_bf16 v[54:57], v[146:149], v[162:165], v[54:57]
	v_mfma_f32_16x16x32_bf16 v[46:49], v[154:157], v[162:165], v[46:49]
	v_mfma_f32_16x16x32_bf16 v[38:41], v[146:149], v[180:183], v[38:41]
	v_mfma_f32_16x16x32_bf16 v[30:33], v[154:157], v[180:183], v[30:33]
	v_mfma_f32_16x16x32_bf16 v[22:25], v[146:149], v[206:209], v[22:25]
	v_mfma_f32_16x16x32_bf16 v[14:17], v[154:157], v[206:209], v[14:17]
	v_mfma_f32_16x16x32_bf16 v[6:9], v[146:149], v[214:217], v[6:9]
	v_mfma_f32_16x16x32_bf16 v[2:5], v[154:157], v[214:217], v[2:5]
	v_mfma_f32_16x16x32_bf16 v[54:57], v[150:153], v[176:179], v[54:57]
	v_mfma_f32_16x16x32_bf16 v[46:49], v[158:161], v[176:179], v[46:49]
	v_mfma_f32_16x16x32_bf16 v[38:41], v[150:153], v[184:187], v[38:41]
	v_mfma_f32_16x16x32_bf16 v[30:33], v[158:161], v[184:187], v[30:33]
	v_mfma_f32_16x16x32_bf16 v[22:25], v[150:153], v[210:213], v[22:25]
	v_mfma_f32_16x16x32_bf16 v[14:17], v[158:161], v[210:213], v[14:17]
	v_mfma_f32_16x16x32_bf16 v[6:9], v[150:153], v[218:221], v[6:9]
	v_mfma_f32_16x16x32_bf16 v[2:5], v[158:161], v[218:221], v[2:5]
	s_setprio 0
	s_barrier
	s_add_u32 s38, s38, 0x100
	s_addc_u32 s39, s39, 0
	s_add_u32 s15, s15, 0x100
	s_addc_u32 s21, s21, 0
	s_cmp_ge_u32 s37, s27
	s_mov_b32 s33, s37
	s_cbranch_scc0 .LBB0_977
	s_branch .Lpeel_exit_3
.LBB0_977:
	s_nop 0
	s_add_i32 s37, s33, 2
	s_add_u32 s40, s38, 0xfff80080
	s_addc_u32 s41, s39, -1
	s_add_i32 s44, 0, 0x10000
	s_cmp_eq_u32 s13, s33
	s_cselect_b32 s51, s23, s41
	s_cselect_b32 s50, s22, s40
	s_cselect_b32 s43, s25, s21
	s_cselect_b32 s42, s24, s15
	s_add_i32 s33, 0, 0x14000
	ds_read_b128 v[122:125], v253
	ds_read_b128 v[126:129], v253 offset:1024
	ds_read_b128 v[130:133], v253 offset:2048
	ds_read_b128 v[134:137], v253 offset:3072
	ds_read_b128 v[146:149], v253 offset:16384
	ds_read_b128 v[150:153], v253 offset:17408
	ds_read_b128 v[154:157], v253 offset:18432
	ds_read_b128 v[158:161], v253 offset:19456
	s_add_i32 m0, s31, 0xc000
	ds_read_b128 v[162:165], v204
	ds_read_b128 v[176:179], v204 offset:1024
	ds_read_b128 v[180:183], v204 offset:2048
	ds_read_b128 v[184:187], v204 offset:3072
	ds_read_b128 v[206:209], v204 offset:4096
	ds_read_b128 v[210:213], v204 offset:5120
	ds_read_b128 v[214:217], v204 offset:6144
	ds_read_b128 v[218:221], v204 offset:7168
	global_load_lds_dwordx4 v172, s[38:39]
	s_add_i32 m0, s31, 0xe000
	s_nop 0
	global_load_lds_dwordx4 v174, s[38:39]
	s_waitcnt vmcnt(8)
	s_waitcnt lgkmcnt(0)
	s_barrier
	s_setprio 1
	s_waitcnt lgkmcnt(0)
	v_mfma_f32_16x16x32_bf16 v[142:145], v[122:125], v[162:165], v[142:145]
	v_mfma_f32_16x16x32_bf16 v[138:141], v[130:133], v[162:165], v[138:141]
	v_mfma_f32_16x16x32_bf16 v[118:121], v[122:125], v[180:183], v[118:121]
	v_mfma_f32_16x16x32_bf16 v[110:113], v[130:133], v[180:183], v[110:113]
	v_mfma_f32_16x16x32_bf16 v[98:101], v[122:125], v[206:209], v[98:101]
	v_mfma_f32_16x16x32_bf16 v[90:93], v[130:133], v[206:209], v[90:93]
	v_mfma_f32_16x16x32_bf16 v[82:85], v[122:125], v[214:217], v[82:85]
	v_mfma_f32_16x16x32_bf16 v[74:77], v[130:133], v[214:217], v[74:77]
	v_mfma_f32_16x16x32_bf16 v[142:145], v[126:129], v[176:179], v[142:145]
	v_mfma_f32_16x16x32_bf16 v[138:141], v[134:137], v[176:179], v[138:141]
	v_mfma_f32_16x16x32_bf16 v[118:121], v[126:129], v[184:187], v[118:121]
	v_mfma_f32_16x16x32_bf16 v[110:113], v[134:137], v[184:187], v[110:113]
	v_mfma_f32_16x16x32_bf16 v[98:101], v[126:129], v[210:213], v[98:101]
	v_mfma_f32_16x16x32_bf16 v[90:93], v[134:137], v[210:213], v[90:93]
	v_mfma_f32_16x16x32_bf16 v[82:85], v[126:129], v[218:221], v[82:85]
	v_mfma_f32_16x16x32_bf16 v[74:77], v[134:137], v[218:221], v[74:77]
	s_setprio 0
	s_setprio 1
	v_mfma_f32_16x16x32_bf16 v[114:117], v[146:149], v[162:165], v[114:117]
	v_mfma_f32_16x16x32_bf16 v[106:109], v[154:157], v[162:165], v[106:109]
	v_mfma_f32_16x16x32_bf16 v[102:105], v[146:149], v[180:183], v[102:105]
	v_mfma_f32_16x16x32_bf16 v[94:97], v[154:157], v[180:183], v[94:97]
	v_mfma_f32_16x16x32_bf16 v[86:89], v[146:149], v[206:209], v[86:89]
	v_mfma_f32_16x16x32_bf16 v[78:81], v[154:157], v[206:209], v[78:81]
	v_mfma_f32_16x16x32_bf16 v[70:73], v[146:149], v[214:217], v[70:73]
	v_mfma_f32_16x16x32_bf16 v[66:69], v[154:157], v[214:217], v[66:69]
	v_mfma_f32_16x16x32_bf16 v[114:117], v[150:153], v[176:179], v[114:117]
	v_mfma_f32_16x16x32_bf16 v[106:109], v[158:161], v[176:179], v[106:109]
	v_mfma_f32_16x16x32_bf16 v[102:105], v[150:153], v[184:187], v[102:105]
	v_mfma_f32_16x16x32_bf16 v[94:97], v[158:161], v[184:187], v[94:97]
	v_mfma_f32_16x16x32_bf16 v[86:89], v[150:153], v[210:213], v[86:89]
	v_mfma_f32_16x16x32_bf16 v[78:81], v[158:161], v[210:213], v[78:81]
	v_mfma_f32_16x16x32_bf16 v[70:73], v[150:153], v[218:221], v[70:73]
	v_mfma_f32_16x16x32_bf16 v[66:69], v[158:161], v[218:221], v[66:69]
	s_setprio 0
	s_barrier
	s_add_i32 s40, s44, s19
	s_mov_b32 m0, s40
	ds_read_b128 v[162:165], v204 offset:16384
	ds_read_b128 v[176:179], v204 offset:17408
	ds_read_b128 v[180:183], v204 offset:18432
	ds_read_b128 v[184:187], v204 offset:19456
	ds_read_b128 v[206:209], v204 offset:20480
	ds_read_b128 v[210:213], v204 offset:21504
	ds_read_b128 v[214:217], v204 offset:22528
	ds_read_b128 v[218:221], v204 offset:23552
	global_load_lds_dwordx4 v0, s[42:43]
	s_add_i32 m0, s40, 0x2000
	s_add_u32 s40, s42, 0x80000
	s_addc_u32 s41, s43, 0
	s_add_i32 s33, s33, s19
	global_load_lds_dwordx4 v170, s[42:43]
	s_mov_b32 m0, s33
	s_nop 0
	global_load_lds_dwordx4 v0, s[40:41]
	s_add_i32 m0, s33, 0x2000
	s_nop 0
	global_load_lds_dwordx4 v170, s[40:41]
	s_mov_b32 m0, s31
	s_nop 0
	global_load_lds_dwordx4 v166, s[50:51]
	s_mov_b32 m0, s34
	s_nop 0
	global_load_lds_dwordx4 v168, s[50:51]
	s_waitcnt vmcnt(8)
	s_waitcnt lgkmcnt(0)
	s_barrier
	s_setprio 1
	s_waitcnt lgkmcnt(0)
	v_mfma_f32_16x16x32_bf16 v[62:65], v[122:125], v[162:165], v[62:65]
	v_mfma_f32_16x16x32_bf16 v[58:61], v[130:133], v[162:165], v[58:61]
	v_mfma_f32_16x16x32_bf16 v[50:53], v[122:125], v[180:183], v[50:53]
	v_mfma_f32_16x16x32_bf16 v[42:45], v[130:133], v[180:183], v[42:45]
	v_mfma_f32_16x16x32_bf16 v[34:37], v[122:125], v[206:209], v[34:37]
	v_mfma_f32_16x16x32_bf16 v[26:29], v[130:133], v[206:209], v[26:29]
	v_mfma_f32_16x16x32_bf16 v[18:21], v[122:125], v[214:217], v[18:21]
	v_mfma_f32_16x16x32_bf16 v[10:13], v[130:133], v[214:217], v[10:13]
	v_mfma_f32_16x16x32_bf16 v[62:65], v[126:129], v[176:179], v[62:65]
	v_mfma_f32_16x16x32_bf16 v[58:61], v[134:137], v[176:179], v[58:61]
	v_mfma_f32_16x16x32_bf16 v[50:53], v[126:129], v[184:187], v[50:53]
	v_mfma_f32_16x16x32_bf16 v[42:45], v[134:137], v[184:187], v[42:45]
	v_mfma_f32_16x16x32_bf16 v[34:37], v[126:129], v[210:213], v[34:37]
	v_mfma_f32_16x16x32_bf16 v[26:29], v[134:137], v[210:213], v[26:29]
	v_mfma_f32_16x16x32_bf16 v[18:21], v[126:129], v[218:221], v[18:21]
	v_mfma_f32_16x16x32_bf16 v[10:13], v[134:137], v[218:221], v[10:13]
	s_setprio 0
	s_setprio 1
	v_mfma_f32_16x16x32_bf16 v[54:57], v[146:149], v[162:165], v[54:57]
	v_mfma_f32_16x16x32_bf16 v[46:49], v[154:157], v[162:165], v[46:49]
	v_mfma_f32_16x16x32_bf16 v[38:41], v[146:149], v[180:183], v[38:41]
	v_mfma_f32_16x16x32_bf16 v[30:33], v[154:157], v[180:183], v[30:33]
	v_mfma_f32_16x16x32_bf16 v[22:25], v[146:149], v[206:209], v[22:25]
	v_mfma_f32_16x16x32_bf16 v[14:17], v[154:157], v[206:209], v[14:17]
	v_mfma_f32_16x16x32_bf16 v[6:9], v[146:149], v[214:217], v[6:9]
	v_mfma_f32_16x16x32_bf16 v[2:5], v[154:157], v[214:217], v[2:5]
	v_mfma_f32_16x16x32_bf16 v[54:57], v[150:153], v[176:179], v[54:57]
	v_mfma_f32_16x16x32_bf16 v[46:49], v[158:161], v[176:179], v[46:49]
	v_mfma_f32_16x16x32_bf16 v[38:41], v[150:153], v[184:187], v[38:41]
	v_mfma_f32_16x16x32_bf16 v[30:33], v[158:161], v[184:187], v[30:33]
	v_mfma_f32_16x16x32_bf16 v[22:25], v[150:153], v[210:213], v[22:25]
	v_mfma_f32_16x16x32_bf16 v[14:17], v[158:161], v[210:213], v[14:17]
	v_mfma_f32_16x16x32_bf16 v[6:9], v[150:153], v[218:221], v[6:9]
	v_mfma_f32_16x16x32_bf16 v[2:5], v[158:161], v[218:221], v[2:5]
	s_setprio 0
	s_barrier
	s_nop 0
	s_add_i32 s33, 0, 0x18000
	s_add_i32 s44, 0, 0x1c000
	ds_read_b128 v[122:125], v253 offset:32768
	ds_read_b128 v[126:129], v253 offset:33792
	ds_read_b128 v[130:133], v253 offset:34816
	ds_read_b128 v[134:137], v253 offset:35840
	ds_read_b128 v[146:149], v253 offset:49152
	ds_read_b128 v[150:153], v253 offset:50176
	ds_read_b128 v[154:157], v253 offset:51200
	ds_read_b128 v[158:161], v253 offset:52224
	s_add_u32 s40, s50, 0x80000
	s_addc_u32 s41, s51, 0
	s_mov_b32 m0, s35
	ds_read_b128 v[162:165], v204 offset:32768
	ds_read_b128 v[176:179], v204 offset:33792
	ds_read_b128 v[180:183], v204 offset:34816
	ds_read_b128 v[184:187], v204 offset:35840
	ds_read_b128 v[206:209], v204 offset:36864
	ds_read_b128 v[210:213], v204 offset:37888
	ds_read_b128 v[214:217], v204 offset:38912
	ds_read_b128 v[218:221], v204 offset:39936
	global_load_lds_dwordx4 v166, s[40:41]
	s_mov_b32 m0, s46
	s_nop 0
	global_load_lds_dwordx4 v168, s[40:41]
	s_waitcnt vmcnt(8)
	s_waitcnt lgkmcnt(0)
	s_barrier
	s_setprio 1
	s_waitcnt lgkmcnt(0)
	v_mfma_f32_16x16x32_bf16 v[142:145], v[122:125], v[162:165], v[142:145]
	v_mfma_f32_16x16x32_bf16 v[138:141], v[130:133], v[162:165], v[138:141]
	v_mfma_f32_16x16x32_bf16 v[118:121], v[122:125], v[180:183], v[118:121]
	v_mfma_f32_16x16x32_bf16 v[110:113], v[130:133], v[180:183], v[110:113]
	v_mfma_f32_16x16x32_bf16 v[98:101], v[122:125], v[206:209], v[98:101]
	v_mfma_f32_16x16x32_bf16 v[90:93], v[130:133], v[206:209], v[90:93]
	v_mfma_f32_16x16x32_bf16 v[82:85], v[122:125], v[214:217], v[82:85]
	v_mfma_f32_16x16x32_bf16 v[74:77], v[130:133], v[214:217], v[74:77]
	v_mfma_f32_16x16x32_bf16 v[142:145], v[126:129], v[176:179], v[142:145]
	v_mfma_f32_16x16x32_bf16 v[138:141], v[134:137], v[176:179], v[138:141]
	v_mfma_f32_16x16x32_bf16 v[118:121], v[126:129], v[184:187], v[118:121]
	v_mfma_f32_16x16x32_bf16 v[110:113], v[134:137], v[184:187], v[110:113]
	v_mfma_f32_16x16x32_bf16 v[98:101], v[126:129], v[210:213], v[98:101]
	v_mfma_f32_16x16x32_bf16 v[90:93], v[134:137], v[210:213], v[90:93]
	v_mfma_f32_16x16x32_bf16 v[82:85], v[126:129], v[218:221], v[82:85]
	v_mfma_f32_16x16x32_bf16 v[74:77], v[134:137], v[218:221], v[74:77]
	s_setprio 0
	s_setprio 1
	v_mfma_f32_16x16x32_bf16 v[114:117], v[146:149], v[162:165], v[114:117]
	v_mfma_f32_16x16x32_bf16 v[106:109], v[154:157], v[162:165], v[106:109]
	v_mfma_f32_16x16x32_bf16 v[102:105], v[146:149], v[180:183], v[102:105]
	v_mfma_f32_16x16x32_bf16 v[94:97], v[154:157], v[180:183], v[94:97]
	v_mfma_f32_16x16x32_bf16 v[86:89], v[146:149], v[206:209], v[86:89]
	v_mfma_f32_16x16x32_bf16 v[78:81], v[154:157], v[206:209], v[78:81]
	v_mfma_f32_16x16x32_bf16 v[70:73], v[146:149], v[214:217], v[70:73]
	v_mfma_f32_16x16x32_bf16 v[66:69], v[154:157], v[214:217], v[66:69]
	v_mfma_f32_16x16x32_bf16 v[114:117], v[150:153], v[176:179], v[114:117]
	v_mfma_f32_16x16x32_bf16 v[106:109], v[158:161], v[176:179], v[106:109]
	v_mfma_f32_16x16x32_bf16 v[102:105], v[150:153], v[184:187], v[102:105]
	v_mfma_f32_16x16x32_bf16 v[94:97], v[158:161], v[184:187], v[94:97]
	v_mfma_f32_16x16x32_bf16 v[86:89], v[150:153], v[210:213], v[86:89]
	v_mfma_f32_16x16x32_bf16 v[78:81], v[158:161], v[210:213], v[78:81]
	v_mfma_f32_16x16x32_bf16 v[70:73], v[150:153], v[218:221], v[70:73]
	v_mfma_f32_16x16x32_bf16 v[66:69], v[158:161], v[218:221], v[66:69]
	s_setprio 0
	s_barrier
	s_add_u32 s100, s40, 0xfff80080
	s_addc_u32 s101, s41, -1
	s_add_u32 s98, s42, 0x80
	s_addc_u32 s99, s43, 0
	s_add_i32 s33, s33, s19
	s_mov_b32 m0, s33
	ds_read_b128 v[162:165], v204 offset:49152
	ds_read_b128 v[176:179], v204 offset:50176
	ds_read_b128 v[180:183], v204 offset:51200
	ds_read_b128 v[184:187], v204 offset:52224
	ds_read_b128 v[206:209], v204 offset:53248
	ds_read_b128 v[210:213], v204 offset:54272
	ds_read_b128 v[214:217], v204 offset:55296
	ds_read_b128 v[218:221], v204 offset:56320
	global_load_lds_dwordx4 v0, s[98:99]
	s_add_i32 m0, s33, 0x2000
	s_add_u32 s40, s42, 0x80080
	s_addc_u32 s41, s43, 0
	s_add_i32 s33, s44, s19
	global_load_lds_dwordx4 v170, s[98:99]
	s_mov_b32 m0, s33
	s_nop 0
	global_load_lds_dwordx4 v0, s[40:41]
	s_add_i32 m0, s33, 0x2000
	s_nop 0
	global_load_lds_dwordx4 v170, s[40:41]
	s_mov_b32 m0, s54
	s_nop 0
	global_load_lds_dwordx4 v166, s[100:101]
	s_mov_b32 m0, s55
	s_nop 0
	global_load_lds_dwordx4 v168, s[100:101]
	s_waitcnt vmcnt(8)
	s_waitcnt lgkmcnt(0)
	s_barrier
	s_setprio 1
	s_waitcnt lgkmcnt(0)
	v_mfma_f32_16x16x32_bf16 v[62:65], v[122:125], v[162:165], v[62:65]
	v_mfma_f32_16x16x32_bf16 v[58:61], v[130:133], v[162:165], v[58:61]
	v_mfma_f32_16x16x32_bf16 v[50:53], v[122:125], v[180:183], v[50:53]
	v_mfma_f32_16x16x32_bf16 v[42:45], v[130:133], v[180:183], v[42:45]
	v_mfma_f32_16x16x32_bf16 v[34:37], v[122:125], v[206:209], v[34:37]
	v_mfma_f32_16x16x32_bf16 v[26:29], v[130:133], v[206:209], v[26:29]
	v_mfma_f32_16x16x32_bf16 v[18:21], v[122:125], v[214:217], v[18:21]
	v_mfma_f32_16x16x32_bf16 v[10:13], v[130:133], v[214:217], v[10:13]
	v_mfma_f32_16x16x32_bf16 v[62:65], v[126:129], v[176:179], v[62:65]
	v_mfma_f32_16x16x32_bf16 v[58:61], v[134:137], v[176:179], v[58:61]
	v_mfma_f32_16x16x32_bf16 v[50:53], v[126:129], v[184:187], v[50:53]
	v_mfma_f32_16x16x32_bf16 v[42:45], v[134:137], v[184:187], v[42:45]
	v_mfma_f32_16x16x32_bf16 v[34:37], v[126:129], v[210:213], v[34:37]
	v_mfma_f32_16x16x32_bf16 v[26:29], v[134:137], v[210:213], v[26:29]
	v_mfma_f32_16x16x32_bf16 v[18:21], v[126:129], v[218:221], v[18:21]
	v_mfma_f32_16x16x32_bf16 v[10:13], v[134:137], v[218:221], v[10:13]
	s_setprio 0
	s_setprio 1
	v_mfma_f32_16x16x32_bf16 v[54:57], v[146:149], v[162:165], v[54:57]
	v_mfma_f32_16x16x32_bf16 v[46:49], v[154:157], v[162:165], v[46:49]
	v_mfma_f32_16x16x32_bf16 v[38:41], v[146:149], v[180:183], v[38:41]
	v_mfma_f32_16x16x32_bf16 v[30:33], v[154:157], v[180:183], v[30:33]
	v_mfma_f32_16x16x32_bf16 v[22:25], v[146:149], v[206:209], v[22:25]
	v_mfma_f32_16x16x32_bf16 v[14:17], v[154:157], v[206:209], v[14:17]
	v_mfma_f32_16x16x32_bf16 v[6:9], v[146:149], v[214:217], v[6:9]
	v_mfma_f32_16x16x32_bf16 v[2:5], v[154:157], v[214:217], v[2:5]
	v_mfma_f32_16x16x32_bf16 v[54:57], v[150:153], v[176:179], v[54:57]
	v_mfma_f32_16x16x32_bf16 v[46:49], v[158:161], v[176:179], v[46:49]
	v_mfma_f32_16x16x32_bf16 v[38:41], v[150:153], v[184:187], v[38:41]
	v_mfma_f32_16x16x32_bf16 v[30:33], v[158:161], v[184:187], v[30:33]
	v_mfma_f32_16x16x32_bf16 v[22:25], v[150:153], v[210:213], v[22:25]
	v_mfma_f32_16x16x32_bf16 v[14:17], v[158:161], v[210:213], v[14:17]
	v_mfma_f32_16x16x32_bf16 v[6:9], v[150:153], v[218:221], v[6:9]
	v_mfma_f32_16x16x32_bf16 v[2:5], v[158:161], v[218:221], v[2:5]
	s_setprio 0
	s_barrier
	s_add_u32 s38, s38, 0x100
	s_addc_u32 s39, s39, 0
	s_add_u32 s15, s15, 0x100
	s_addc_u32 s21, s21, 0
	s_cmp_ge_u32 s37, s27
	s_mov_b32 s33, s37
	s_cbranch_scc0 .LBB0_977

.LBB0_1079:
	s_ashr_i32 s43, s42, 31
	s_lshl_b64 s[40:41], s[42:43], 20
	s_add_u32 s50, s19, s40
	s_addc_u32 s51, s28, s41
	s_and_b64 s[40:41], s[8:9], exec
	s_cselect_b32 s11, s51, s57
	s_cselect_b32 s33, s50, s56
	s_ashr_i32 s39, s38, 31
	s_lshl_b64 s[40:41], s[38:39], 20
	s_add_u32 s52, s29, s40
	s_addc_u32 s53, s34, s41
	s_and_b64 s[40:41], s[8:9], exec
	s_cselect_b32 s39, s53, s61
	s_cselect_b32 s40, s52, s60
	s_add_u32 s41, s60, 0x100
	s_addc_u32 s43, s61, 0
	s_mov_b32 s44, -2
	v_add_u32_e32 v253, 0x10000, v223
	s_add_u32 s60, s56, 0x100
	s_addc_u32 s61, s57, 0
	s_add_i32 s45, 0, 0x10000
	s_cmp_eq_u32 s44, 28
	s_cselect_b32 s65, s11, s61
	s_cselect_b32 s64, s33, s60
	s_cselect_b32 s63, s39, s43
	s_cselect_b32 s62, s40, s41
	s_add_i32 s55, 0, 0x14000
	ds_read_b128 v[62:65], v253
	ds_read_b128 v[66:69], v253 offset:1024
	ds_read_b128 v[106:109], v253 offset:2048
	ds_read_b128 v[110:113], v253 offset:3072
	ds_read_b128 v[138:141], v253 offset:16384
	ds_read_b128 v[150:153], v253 offset:17408
	ds_read_b128 v[154:157], v253 offset:18432
	ds_read_b128 v[158:161], v253 offset:19456
	s_add_i32 m0, s46, 0xc000
	ds_read_b128 v[162:165], v227
	ds_read_b128 v[166:169], v227 offset:1024
	ds_read_b128 v[170:173], v227 offset:2048
	ds_read_b128 v[174:177], v227 offset:3072
	ds_read_b128 v[178:181], v227 offset:4096
	ds_read_b128 v[182:185], v227 offset:5120
	ds_read_b128 v[186:189], v227 offset:6144
	ds_read_b128 v[190:193], v227 offset:7168
	global_load_lds_dwordx4 v210, s[56:57]
	s_add_i32 m0, s46, 0xe000
	s_nop 0
	global_load_lds_dwordx4 v212, s[56:57]
	s_waitcnt vmcnt(8)
	s_waitcnt lgkmcnt(0)
	s_barrier
	s_setprio 1
	s_waitcnt lgkmcnt(0)
	v_mfma_f32_16x16x32_bf16 v[146:149], v[62:65], v[162:165], 0
	v_mfma_f32_16x16x32_bf16 v[70:73], v[106:109], v[162:165], 0
	v_mfma_f32_16x16x32_bf16 v[134:137], v[62:65], v[170:173], 0
	v_mfma_f32_16x16x32_bf16 v[54:57], v[106:109], v[170:173], 0
	v_mfma_f32_16x16x32_bf16 v[126:129], v[62:65], v[178:181], 0
	v_mfma_f32_16x16x32_bf16 v[46:49], v[106:109], v[178:181], 0
	v_mfma_f32_16x16x32_bf16 v[118:121], v[62:65], v[186:189], 0
	v_mfma_f32_16x16x32_bf16 v[38:41], v[106:109], v[186:189], 0
	v_mfma_f32_16x16x32_bf16 v[146:149], v[66:69], v[166:169], v[146:149]
	v_mfma_f32_16x16x32_bf16 v[70:73], v[110:113], v[166:169], v[70:73]
	v_mfma_f32_16x16x32_bf16 v[134:137], v[66:69], v[174:177], v[134:137]
	v_mfma_f32_16x16x32_bf16 v[54:57], v[110:113], v[174:177], v[54:57]
	v_mfma_f32_16x16x32_bf16 v[126:129], v[66:69], v[182:185], v[126:129]
	v_mfma_f32_16x16x32_bf16 v[46:49], v[110:113], v[182:185], v[46:49]
	v_mfma_f32_16x16x32_bf16 v[118:121], v[66:69], v[190:193], v[118:121]
	v_mfma_f32_16x16x32_bf16 v[38:41], v[110:113], v[190:193], v[38:41]
	s_setprio 0
	s_setprio 1
	v_mfma_f32_16x16x32_bf16 v[142:145], v[138:141], v[162:165], 0
	v_mfma_f32_16x16x32_bf16 v[58:61], v[154:157], v[162:165], 0
	v_mfma_f32_16x16x32_bf16 v[130:133], v[138:141], v[170:173], 0
	v_mfma_f32_16x16x32_bf16 v[50:53], v[154:157], v[170:173], 0
	v_mfma_f32_16x16x32_bf16 v[122:125], v[138:141], v[178:181], 0
	v_mfma_f32_16x16x32_bf16 v[42:45], v[154:157], v[178:181], 0
	v_mfma_f32_16x16x32_bf16 v[114:117], v[138:141], v[186:189], 0
	v_mfma_f32_16x16x32_bf16 v[34:37], v[154:157], v[186:189], 0
	v_mfma_f32_16x16x32_bf16 v[142:145], v[150:153], v[166:169], v[142:145]
	v_mfma_f32_16x16x32_bf16 v[58:61], v[158:161], v[166:169], v[58:61]
	v_mfma_f32_16x16x32_bf16 v[130:133], v[150:153], v[174:177], v[130:133]
	v_mfma_f32_16x16x32_bf16 v[50:53], v[158:161], v[174:177], v[50:53]
	v_mfma_f32_16x16x32_bf16 v[122:125], v[150:153], v[182:185], v[122:125]
	v_mfma_f32_16x16x32_bf16 v[42:45], v[158:161], v[182:185], v[42:45]
	v_mfma_f32_16x16x32_bf16 v[114:117], v[150:153], v[190:193], v[114:117]
	v_mfma_f32_16x16x32_bf16 v[34:37], v[158:161], v[190:193], v[34:37]
	s_setprio 0
	s_barrier
	s_add_i32 s45, s45, s35
	s_mov_b32 m0, s45
	ds_read_b128 v[162:165], v227 offset:16384
	ds_read_b128 v[166:169], v227 offset:17408
	ds_read_b128 v[170:173], v227 offset:18432
	ds_read_b128 v[174:177], v227 offset:19456
	ds_read_b128 v[178:181], v227 offset:20480
	ds_read_b128 v[182:185], v227 offset:21504
	ds_read_b128 v[186:189], v227 offset:22528
	ds_read_b128 v[190:193], v227 offset:23552
	global_load_lds_dwordx4 v0, s[62:63]
	s_add_i32 m0, s45, 0x2000
	s_add_u32 s56, s62, 0x80000
	s_addc_u32 s57, s63, 0
	s_add_i32 s45, s55, s35
	global_load_lds_dwordx4 v208, s[62:63]
	s_mov_b32 m0, s45
	s_nop 0
	global_load_lds_dwordx4 v0, s[56:57]
	s_add_i32 m0, s45, 0x2000
	s_nop 0
	global_load_lds_dwordx4 v208, s[56:57]
	s_mov_b32 m0, s46
	s_nop 0
	global_load_lds_dwordx4 v204, s[64:65]
	s_mov_b32 m0, s66
	s_nop 0
	global_load_lds_dwordx4 v206, s[64:65]
	s_waitcnt vmcnt(8)
	s_waitcnt lgkmcnt(0)
	s_barrier
	s_setprio 1
	s_waitcnt lgkmcnt(0)
	v_mfma_f32_16x16x32_bf16 v[102:105], v[62:65], v[162:165], 0
	v_mfma_f32_16x16x32_bf16 v[30:33], v[106:109], v[162:165], 0
	v_mfma_f32_16x16x32_bf16 v[94:97], v[62:65], v[170:173], 0
	v_mfma_f32_16x16x32_bf16 v[22:25], v[106:109], v[170:173], 0
	v_mfma_f32_16x16x32_bf16 v[86:89], v[62:65], v[178:181], 0
	v_mfma_f32_16x16x32_bf16 v[14:17], v[106:109], v[178:181], 0
	v_mfma_f32_16x16x32_bf16 v[10:13], v[106:109], v[186:189], 0
	v_mfma_f32_16x16x32_bf16 v[102:105], v[66:69], v[166:169], v[102:105]
	v_mfma_f32_16x16x32_bf16 v[30:33], v[110:113], v[166:169], v[30:33]
	v_mfma_f32_16x16x32_bf16 v[94:97], v[66:69], v[174:177], v[94:97]
	v_mfma_f32_16x16x32_bf16 v[22:25], v[110:113], v[174:177], v[22:25]
	v_mfma_f32_16x16x32_bf16 v[86:89], v[66:69], v[182:185], v[86:89]
	v_mfma_f32_16x16x32_bf16 v[14:17], v[110:113], v[182:185], v[14:17]
	v_mfma_f32_16x16x32_bf16 v[62:65], v[62:65], v[186:189], 0
	v_mfma_f32_16x16x32_bf16 v[10:13], v[110:113], v[190:193], v[10:13]
	v_mfma_f32_16x16x32_bf16 v[62:65], v[66:69], v[190:193], v[62:65]
	s_setprio 0
	s_setprio 1
	v_mfma_f32_16x16x32_bf16 v[26:29], v[154:157], v[162:165], 0
	v_mfma_f32_16x16x32_bf16 v[82:85], v[138:141], v[170:173], 0
	v_mfma_f32_16x16x32_bf16 v[18:21], v[154:157], v[170:173], 0
	v_mfma_f32_16x16x32_bf16 v[78:81], v[138:141], v[178:181], 0
	v_mfma_f32_16x16x32_bf16 v[6:9], v[154:157], v[178:181], 0
	v_mfma_f32_16x16x32_bf16 v[74:77], v[138:141], v[186:189], 0
	v_mfma_f32_16x16x32_bf16 v[2:5], v[154:157], v[186:189], 0
	v_mfma_f32_16x16x32_bf16 v[66:69], v[138:141], v[162:165], 0
	v_mfma_f32_16x16x32_bf16 v[26:29], v[158:161], v[166:169], v[26:29]
	v_mfma_f32_16x16x32_bf16 v[90:93], v[150:153], v[174:177], v[82:85]
	v_mfma_f32_16x16x32_bf16 v[18:21], v[158:161], v[174:177], v[18:21]
	v_mfma_f32_16x16x32_bf16 v[78:81], v[150:153], v[182:185], v[78:81]
	v_mfma_f32_16x16x32_bf16 v[6:9], v[158:161], v[182:185], v[6:9]
	v_mfma_f32_16x16x32_bf16 v[74:77], v[150:153], v[190:193], v[74:77]
	v_mfma_f32_16x16x32_bf16 v[2:5], v[158:161], v[190:193], v[2:5]
	v_mfma_f32_16x16x32_bf16 v[66:69], v[150:153], v[166:169], v[66:69]
	s_setprio 0
	s_barrier
	s_nop 0
	s_add_i32 s45, 0, 0x18000
	s_add_i32 s55, 0, 0x1c000
	ds_read_b128 v[82:85], v253 offset:32768
	ds_read_b128 v[98:101], v253 offset:33792
	ds_read_b128 v[106:109], v253 offset:34816
	ds_read_b128 v[110:113], v253 offset:35840
	ds_read_b128 v[138:141], v253 offset:49152
	ds_read_b128 v[150:153], v253 offset:50176
	ds_read_b128 v[154:157], v253 offset:51200
	ds_read_b128 v[158:161], v253 offset:52224
	s_add_u32 s56, s64, 0x4000
	s_addc_u32 s57, s65, 0
	s_mov_b32 m0, s67
	ds_read_b128 v[162:165], v227 offset:32768
	ds_read_b128 v[166:169], v227 offset:33792
	ds_read_b128 v[170:173], v227 offset:34816
	ds_read_b128 v[174:177], v227 offset:35840
	ds_read_b128 v[178:181], v227 offset:36864
	ds_read_b128 v[182:185], v227 offset:37888
	ds_read_b128 v[186:189], v227 offset:38912
	ds_read_b128 v[190:193], v227 offset:39936
	global_load_lds_dwordx4 v204, s[56:57]
	s_mov_b32 m0, s68
	s_nop 0
	global_load_lds_dwordx4 v206, s[56:57]
	s_waitcnt vmcnt(8)
	s_waitcnt lgkmcnt(0)
	s_barrier
	s_setprio 1
	s_waitcnt lgkmcnt(0)
	v_mfma_f32_16x16x32_bf16 v[146:149], v[82:85], v[162:165], v[146:149]
	v_mfma_f32_16x16x32_bf16 v[70:73], v[106:109], v[162:165], v[70:73]
	v_mfma_f32_16x16x32_bf16 v[134:137], v[82:85], v[170:173], v[134:137]
	v_mfma_f32_16x16x32_bf16 v[54:57], v[106:109], v[170:173], v[54:57]
	v_mfma_f32_16x16x32_bf16 v[126:129], v[82:85], v[178:181], v[126:129]
	v_mfma_f32_16x16x32_bf16 v[46:49], v[106:109], v[178:181], v[46:49]
	v_mfma_f32_16x16x32_bf16 v[118:121], v[82:85], v[186:189], v[118:121]
	v_mfma_f32_16x16x32_bf16 v[38:41], v[106:109], v[186:189], v[38:41]
	v_mfma_f32_16x16x32_bf16 v[146:149], v[98:101], v[166:169], v[146:149]
	v_mfma_f32_16x16x32_bf16 v[70:73], v[110:113], v[166:169], v[70:73]
	v_mfma_f32_16x16x32_bf16 v[134:137], v[98:101], v[174:177], v[134:137]
	v_mfma_f32_16x16x32_bf16 v[54:57], v[110:113], v[174:177], v[54:57]
	v_mfma_f32_16x16x32_bf16 v[126:129], v[98:101], v[182:185], v[126:129]
	v_mfma_f32_16x16x32_bf16 v[46:49], v[110:113], v[182:185], v[46:49]
	v_mfma_f32_16x16x32_bf16 v[118:121], v[98:101], v[190:193], v[118:121]
	v_mfma_f32_16x16x32_bf16 v[38:41], v[110:113], v[190:193], v[38:41]
	s_setprio 0
	s_setprio 1
	v_mfma_f32_16x16x32_bf16 v[142:145], v[138:141], v[162:165], v[142:145]
	v_mfma_f32_16x16x32_bf16 v[58:61], v[154:157], v[162:165], v[58:61]
	v_mfma_f32_16x16x32_bf16 v[130:133], v[138:141], v[170:173], v[130:133]
	v_mfma_f32_16x16x32_bf16 v[50:53], v[154:157], v[170:173], v[50:53]
	v_mfma_f32_16x16x32_bf16 v[122:125], v[138:141], v[178:181], v[122:125]
	v_mfma_f32_16x16x32_bf16 v[42:45], v[154:157], v[178:181], v[42:45]
	v_mfma_f32_16x16x32_bf16 v[114:117], v[138:141], v[186:189], v[114:117]
	v_mfma_f32_16x16x32_bf16 v[34:37], v[154:157], v[186:189], v[34:37]
	v_mfma_f32_16x16x32_bf16 v[142:145], v[150:153], v[166:169], v[142:145]
	v_mfma_f32_16x16x32_bf16 v[58:61], v[158:161], v[166:169], v[58:61]
	v_mfma_f32_16x16x32_bf16 v[130:133], v[150:153], v[174:177], v[130:133]
	v_mfma_f32_16x16x32_bf16 v[50:53], v[158:161], v[174:177], v[50:53]
	v_mfma_f32_16x16x32_bf16 v[122:125], v[150:153], v[182:185], v[122:125]
	v_mfma_f32_16x16x32_bf16 v[42:45], v[158:161], v[182:185], v[42:45]
	v_mfma_f32_16x16x32_bf16 v[114:117], v[150:153], v[190:193], v[114:117]
	v_mfma_f32_16x16x32_bf16 v[34:37], v[158:161], v[190:193], v[34:37]
	s_setprio 0
	s_barrier
	s_add_u32 s100, s56, 0xffffc080
	s_addc_u32 s101, s57, -1
	s_add_u32 s98, s62, 0x80
	s_addc_u32 s99, s63, 0
	s_add_i32 s45, s45, s35
	s_mov_b32 m0, s45
	ds_read_b128 v[162:165], v227 offset:49152
	ds_read_b128 v[166:169], v227 offset:50176
	ds_read_b128 v[170:173], v227 offset:51200
	ds_read_b128 v[174:177], v227 offset:52224
	ds_read_b128 v[178:181], v227 offset:53248
	ds_read_b128 v[182:185], v227 offset:54272
	ds_read_b128 v[186:189], v227 offset:55296
	ds_read_b128 v[190:193], v227 offset:56320
	global_load_lds_dwordx4 v0, s[98:99]
	s_add_i32 m0, s45, 0x2000
	s_add_u32 s56, s62, 0x80080
	s_addc_u32 s57, s63, 0
	s_add_i32 s45, s55, s35
	global_load_lds_dwordx4 v208, s[98:99]
	s_mov_b32 m0, s45
	s_nop 0
	global_load_lds_dwordx4 v0, s[56:57]
	s_add_i32 m0, s45, 0x2000
	s_nop 0
	global_load_lds_dwordx4 v208, s[56:57]
	s_mov_b32 m0, s71
	s_nop 0
	global_load_lds_dwordx4 v204, s[100:101]
	s_mov_b32 m0, s74
	s_nop 0
	global_load_lds_dwordx4 v206, s[100:101]
	s_waitcnt vmcnt(8)
	s_waitcnt lgkmcnt(0)
	s_barrier
	s_setprio 1
	s_waitcnt lgkmcnt(0)
	v_mfma_f32_16x16x32_bf16 v[102:105], v[82:85], v[162:165], v[102:105]
	v_mfma_f32_16x16x32_bf16 v[30:33], v[106:109], v[162:165], v[30:33]
	v_mfma_f32_16x16x32_bf16 v[94:97], v[82:85], v[170:173], v[94:97]
	v_mfma_f32_16x16x32_bf16 v[22:25], v[106:109], v[170:173], v[22:25]
	v_mfma_f32_16x16x32_bf16 v[86:89], v[82:85], v[178:181], v[86:89]
	v_mfma_f32_16x16x32_bf16 v[14:17], v[106:109], v[178:181], v[14:17]
	v_mfma_f32_16x16x32_bf16 v[62:65], v[82:85], v[186:189], v[62:65]
	v_mfma_f32_16x16x32_bf16 v[10:13], v[106:109], v[186:189], v[10:13]
	v_mfma_f32_16x16x32_bf16 v[102:105], v[98:101], v[166:169], v[102:105]
	v_mfma_f32_16x16x32_bf16 v[30:33], v[110:113], v[166:169], v[30:33]
	v_mfma_f32_16x16x32_bf16 v[94:97], v[98:101], v[174:177], v[94:97]
	v_mfma_f32_16x16x32_bf16 v[22:25], v[110:113], v[174:177], v[22:25]
	v_mfma_f32_16x16x32_bf16 v[86:89], v[98:101], v[182:185], v[86:89]
	v_mfma_f32_16x16x32_bf16 v[14:17], v[110:113], v[182:185], v[14:17]
	v_mfma_f32_16x16x32_bf16 v[82:85], v[98:101], v[190:193], v[62:65]
	v_mfma_f32_16x16x32_bf16 v[10:13], v[110:113], v[190:193], v[10:13]
	s_setprio 0
	s_setprio 1
	v_mfma_f32_16x16x32_bf16 v[62:65], v[138:141], v[162:165], v[66:69]
	v_mfma_f32_16x16x32_bf16 v[98:101], v[150:153], v[166:169], v[62:65]
	v_mfma_f32_16x16x32_bf16 v[62:65], v[138:141], v[170:173], v[90:93]
	v_mfma_f32_16x16x32_bf16 v[90:93], v[150:153], v[174:177], v[62:65]
	v_mfma_f32_16x16x32_bf16 v[62:65], v[138:141], v[178:181], v[78:81]
	v_mfma_f32_16x16x32_bf16 v[26:29], v[154:157], v[162:165], v[26:29]
	v_mfma_f32_16x16x32_bf16 v[18:21], v[154:157], v[170:173], v[18:21]
	v_mfma_f32_16x16x32_bf16 v[78:81], v[150:153], v[182:185], v[62:65]
	v_mfma_f32_16x16x32_bf16 v[6:9], v[154:157], v[178:181], v[6:9]
	v_mfma_f32_16x16x32_bf16 v[62:65], v[138:141], v[186:189], v[74:77]
	v_mfma_f32_16x16x32_bf16 v[2:5], v[154:157], v[186:189], v[2:5]
	v_mfma_f32_16x16x32_bf16 v[26:29], v[158:161], v[166:169], v[26:29]
	v_mfma_f32_16x16x32_bf16 v[18:21], v[158:161], v[174:177], v[18:21]
	v_mfma_f32_16x16x32_bf16 v[6:9], v[158:161], v[182:185], v[6:9]
	v_mfma_f32_16x16x32_bf16 v[74:77], v[150:153], v[190:193], v[62:65]
	v_mfma_f32_16x16x32_bf16 v[2:5], v[158:161], v[190:193], v[2:5]
	s_setprio 0
	s_barrier
	s_add_i32 s44, s44, 2
	s_add_u32 s41, s41, 0x100
	s_addc_u32 s43, s43, 0
	s_cmp_gt_u32 s44, 29
	s_mov_b64 s[56:57], s[60:61]
	s_cbranch_scc0 .LBB0_1080
	s_branch .Lpeel_exit_4
.LBB0_1080:
	s_add_u32 s60, s56, 0x100
	s_addc_u32 s61, s57, 0
	s_add_i32 s45, 0, 0x10000
	s_cmp_eq_u32 s44, 28
	s_cselect_b32 s65, s11, s61
	s_cselect_b32 s64, s33, s60
	s_cselect_b32 s63, s39, s43
	s_cselect_b32 s62, s40, s41
	s_add_i32 s55, 0, 0x14000
	ds_read_b128 v[62:65], v253
	ds_read_b128 v[66:69], v253 offset:1024
	ds_read_b128 v[106:109], v253 offset:2048
	ds_read_b128 v[110:113], v253 offset:3072
	ds_read_b128 v[138:141], v253 offset:16384
	ds_read_b128 v[150:153], v253 offset:17408
	ds_read_b128 v[154:157], v253 offset:18432
	ds_read_b128 v[158:161], v253 offset:19456
	s_add_i32 m0, s46, 0xc000
	ds_read_b128 v[162:165], v227
	ds_read_b128 v[166:169], v227 offset:1024
	ds_read_b128 v[170:173], v227 offset:2048
	ds_read_b128 v[174:177], v227 offset:3072
	ds_read_b128 v[178:181], v227 offset:4096
	ds_read_b128 v[182:185], v227 offset:5120
	ds_read_b128 v[186:189], v227 offset:6144
	ds_read_b128 v[190:193], v227 offset:7168
	global_load_lds_dwordx4 v210, s[56:57]
	s_add_i32 m0, s46, 0xe000
	s_nop 0
	global_load_lds_dwordx4 v212, s[56:57]
	s_waitcnt vmcnt(8)
	s_waitcnt lgkmcnt(0)
	s_barrier
	s_setprio 1
	s_waitcnt lgkmcnt(0)
	v_mfma_f32_16x16x32_bf16 v[146:149], v[62:65], v[162:165], v[146:149]
	v_mfma_f32_16x16x32_bf16 v[70:73], v[106:109], v[162:165], v[70:73]
	v_mfma_f32_16x16x32_bf16 v[134:137], v[62:65], v[170:173], v[134:137]
	v_mfma_f32_16x16x32_bf16 v[54:57], v[106:109], v[170:173], v[54:57]
	v_mfma_f32_16x16x32_bf16 v[126:129], v[62:65], v[178:181], v[126:129]
	v_mfma_f32_16x16x32_bf16 v[46:49], v[106:109], v[178:181], v[46:49]
	v_mfma_f32_16x16x32_bf16 v[118:121], v[62:65], v[186:189], v[118:121]
	v_mfma_f32_16x16x32_bf16 v[38:41], v[106:109], v[186:189], v[38:41]
	v_mfma_f32_16x16x32_bf16 v[146:149], v[66:69], v[166:169], v[146:149]
	v_mfma_f32_16x16x32_bf16 v[70:73], v[110:113], v[166:169], v[70:73]
	v_mfma_f32_16x16x32_bf16 v[134:137], v[66:69], v[174:177], v[134:137]
	v_mfma_f32_16x16x32_bf16 v[54:57], v[110:113], v[174:177], v[54:57]
	v_mfma_f32_16x16x32_bf16 v[126:129], v[66:69], v[182:185], v[126:129]
	v_mfma_f32_16x16x32_bf16 v[46:49], v[110:113], v[182:185], v[46:49]
	v_mfma_f32_16x16x32_bf16 v[118:121], v[66:69], v[190:193], v[118:121]
	v_mfma_f32_16x16x32_bf16 v[38:41], v[110:113], v[190:193], v[38:41]
	s_setprio 0
	s_setprio 1
	v_mfma_f32_16x16x32_bf16 v[142:145], v[138:141], v[162:165], v[142:145]
	v_mfma_f32_16x16x32_bf16 v[58:61], v[154:157], v[162:165], v[58:61]
	v_mfma_f32_16x16x32_bf16 v[130:133], v[138:141], v[170:173], v[130:133]
	v_mfma_f32_16x16x32_bf16 v[50:53], v[154:157], v[170:173], v[50:53]
	v_mfma_f32_16x16x32_bf16 v[122:125], v[138:141], v[178:181], v[122:125]
	v_mfma_f32_16x16x32_bf16 v[42:45], v[154:157], v[178:181], v[42:45]
	v_mfma_f32_16x16x32_bf16 v[114:117], v[138:141], v[186:189], v[114:117]
	v_mfma_f32_16x16x32_bf16 v[34:37], v[154:157], v[186:189], v[34:37]
	v_mfma_f32_16x16x32_bf16 v[142:145], v[150:153], v[166:169], v[142:145]
	v_mfma_f32_16x16x32_bf16 v[58:61], v[158:161], v[166:169], v[58:61]
	v_mfma_f32_16x16x32_bf16 v[130:133], v[150:153], v[174:177], v[130:133]
	v_mfma_f32_16x16x32_bf16 v[50:53], v[158:161], v[174:177], v[50:53]
	v_mfma_f32_16x16x32_bf16 v[122:125], v[150:153], v[182:185], v[122:125]
	v_mfma_f32_16x16x32_bf16 v[42:45], v[158:161], v[182:185], v[42:45]
	v_mfma_f32_16x16x32_bf16 v[114:117], v[150:153], v[190:193], v[114:117]
	v_mfma_f32_16x16x32_bf16 v[34:37], v[158:161], v[190:193], v[34:37]
	s_setprio 0
	s_barrier
	s_add_i32 s45, s45, s35
	s_mov_b32 m0, s45
	ds_read_b128 v[162:165], v227 offset:16384
	ds_read_b128 v[166:169], v227 offset:17408
	ds_read_b128 v[170:173], v227 offset:18432
	ds_read_b128 v[174:177], v227 offset:19456
	ds_read_b128 v[178:181], v227 offset:20480
	ds_read_b128 v[182:185], v227 offset:21504
	ds_read_b128 v[186:189], v227 offset:22528
	ds_read_b128 v[190:193], v227 offset:23552
	global_load_lds_dwordx4 v0, s[62:63]
	s_add_i32 m0, s45, 0x2000
	s_add_u32 s56, s62, 0x80000
	s_addc_u32 s57, s63, 0
	s_add_i32 s45, s55, s35
	global_load_lds_dwordx4 v208, s[62:63]
	s_mov_b32 m0, s45
	s_nop 0
	global_load_lds_dwordx4 v0, s[56:57]
	s_add_i32 m0, s45, 0x2000
	s_nop 0
	global_load_lds_dwordx4 v208, s[56:57]
	s_mov_b32 m0, s46
	s_nop 0
	global_load_lds_dwordx4 v204, s[64:65]
	s_mov_b32 m0, s66
	s_nop 0
	global_load_lds_dwordx4 v206, s[64:65]
	s_waitcnt vmcnt(8)
	s_waitcnt lgkmcnt(0)
	s_barrier
	s_setprio 1
	s_waitcnt lgkmcnt(0)
	v_mfma_f32_16x16x32_bf16 v[102:105], v[62:65], v[162:165], v[102:105]
	v_mfma_f32_16x16x32_bf16 v[30:33], v[106:109], v[162:165], v[30:33]
	v_mfma_f32_16x16x32_bf16 v[94:97], v[62:65], v[170:173], v[94:97]
	v_mfma_f32_16x16x32_bf16 v[22:25], v[106:109], v[170:173], v[22:25]
	v_mfma_f32_16x16x32_bf16 v[86:89], v[62:65], v[178:181], v[86:89]
	v_mfma_f32_16x16x32_bf16 v[14:17], v[106:109], v[178:181], v[14:17]
	v_mfma_f32_16x16x32_bf16 v[10:13], v[106:109], v[186:189], v[10:13]
	v_mfma_f32_16x16x32_bf16 v[102:105], v[66:69], v[166:169], v[102:105]
	v_mfma_f32_16x16x32_bf16 v[30:33], v[110:113], v[166:169], v[30:33]
	v_mfma_f32_16x16x32_bf16 v[94:97], v[66:69], v[174:177], v[94:97]
	v_mfma_f32_16x16x32_bf16 v[22:25], v[110:113], v[174:177], v[22:25]
	v_mfma_f32_16x16x32_bf16 v[86:89], v[66:69], v[182:185], v[86:89]
	v_mfma_f32_16x16x32_bf16 v[14:17], v[110:113], v[182:185], v[14:17]
	v_mfma_f32_16x16x32_bf16 v[62:65], v[62:65], v[186:189], v[82:85]
	v_mfma_f32_16x16x32_bf16 v[10:13], v[110:113], v[190:193], v[10:13]
	v_mfma_f32_16x16x32_bf16 v[62:65], v[66:69], v[190:193], v[62:65]
	s_setprio 0
	s_setprio 1
	v_mfma_f32_16x16x32_bf16 v[26:29], v[154:157], v[162:165], v[26:29]
	v_mfma_f32_16x16x32_bf16 v[82:85], v[138:141], v[170:173], v[90:93]
	v_mfma_f32_16x16x32_bf16 v[18:21], v[154:157], v[170:173], v[18:21]
	v_mfma_f32_16x16x32_bf16 v[78:81], v[138:141], v[178:181], v[78:81]
	v_mfma_f32_16x16x32_bf16 v[6:9], v[154:157], v[178:181], v[6:9]
	v_mfma_f32_16x16x32_bf16 v[74:77], v[138:141], v[186:189], v[74:77]
	v_mfma_f32_16x16x32_bf16 v[2:5], v[154:157], v[186:189], v[2:5]
	v_mfma_f32_16x16x32_bf16 v[66:69], v[138:141], v[162:165], v[98:101]
	v_mfma_f32_16x16x32_bf16 v[26:29], v[158:161], v[166:169], v[26:29]
	v_mfma_f32_16x16x32_bf16 v[90:93], v[150:153], v[174:177], v[82:85]
	v_mfma_f32_16x16x32_bf16 v[18:21], v[158:161], v[174:177], v[18:21]
	v_mfma_f32_16x16x32_bf16 v[78:81], v[150:153], v[182:185], v[78:81]
	v_mfma_f32_16x16x32_bf16 v[6:9], v[158:161], v[182:185], v[6:9]
	v_mfma_f32_16x16x32_bf16 v[74:77], v[150:153], v[190:193], v[74:77]
	v_mfma_f32_16x16x32_bf16 v[2:5], v[158:161], v[190:193], v[2:5]
	v_mfma_f32_16x16x32_bf16 v[66:69], v[150:153], v[166:169], v[66:69]
	s_setprio 0
	s_barrier
	s_nop 0
	s_add_i32 s45, 0, 0x18000
	s_add_i32 s55, 0, 0x1c000
	ds_read_b128 v[82:85], v253 offset:32768
	ds_read_b128 v[98:101], v253 offset:33792
	ds_read_b128 v[106:109], v253 offset:34816
	ds_read_b128 v[110:113], v253 offset:35840
	ds_read_b128 v[138:141], v253 offset:49152
	ds_read_b128 v[150:153], v253 offset:50176
	ds_read_b128 v[154:157], v253 offset:51200
	ds_read_b128 v[158:161], v253 offset:52224
	s_add_u32 s56, s64, 0x4000
	s_addc_u32 s57, s65, 0
	s_mov_b32 m0, s67
	ds_read_b128 v[162:165], v227 offset:32768
	ds_read_b128 v[166:169], v227 offset:33792
	ds_read_b128 v[170:173], v227 offset:34816
	ds_read_b128 v[174:177], v227 offset:35840
	ds_read_b128 v[178:181], v227 offset:36864
	ds_read_b128 v[182:185], v227 offset:37888
	ds_read_b128 v[186:189], v227 offset:38912
	ds_read_b128 v[190:193], v227 offset:39936
	global_load_lds_dwordx4 v204, s[56:57]
	s_mov_b32 m0, s68
	s_nop 0
	global_load_lds_dwordx4 v206, s[56:57]
	s_waitcnt vmcnt(8)
	s_waitcnt lgkmcnt(0)
	s_barrier
	s_setprio 1
	s_waitcnt lgkmcnt(0)
	v_mfma_f32_16x16x32_bf16 v[146:149], v[82:85], v[162:165], v[146:149]
	v_mfma_f32_16x16x32_bf16 v[70:73], v[106:109], v[162:165], v[70:73]
	v_mfma_f32_16x16x32_bf16 v[134:137], v[82:85], v[170:173], v[134:137]
	v_mfma_f32_16x16x32_bf16 v[54:57], v[106:109], v[170:173], v[54:57]
	v_mfma_f32_16x16x32_bf16 v[126:129], v[82:85], v[178:181], v[126:129]
	v_mfma_f32_16x16x32_bf16 v[46:49], v[106:109], v[178:181], v[46:49]
	v_mfma_f32_16x16x32_bf16 v[118:121], v[82:85], v[186:189], v[118:121]
	v_mfma_f32_16x16x32_bf16 v[38:41], v[106:109], v[186:189], v[38:41]
	v_mfma_f32_16x16x32_bf16 v[146:149], v[98:101], v[166:169], v[146:149]
	v_mfma_f32_16x16x32_bf16 v[70:73], v[110:113], v[166:169], v[70:73]
	v_mfma_f32_16x16x32_bf16 v[134:137], v[98:101], v[174:177], v[134:137]
	v_mfma_f32_16x16x32_bf16 v[54:57], v[110:113], v[174:177], v[54:57]
	v_mfma_f32_16x16x32_bf16 v[126:129], v[98:101], v[182:185], v[126:129]
	v_mfma_f32_16x16x32_bf16 v[46:49], v[110:113], v[182:185], v[46:49]
	v_mfma_f32_16x16x32_bf16 v[118:121], v[98:101], v[190:193], v[118:121]
	v_mfma_f32_16x16x32_bf16 v[38:41], v[110:113], v[190:193], v[38:41]
	s_setprio 0
	s_setprio 1
	v_mfma_f32_16x16x32_bf16 v[142:145], v[138:141], v[162:165], v[142:145]
	v_mfma_f32_16x16x32_bf16 v[58:61], v[154:157], v[162:165], v[58:61]
	v_mfma_f32_16x16x32_bf16 v[130:133], v[138:141], v[170:173], v[130:133]
	v_mfma_f32_16x16x32_bf16 v[50:53], v[154:157], v[170:173], v[50:53]
	v_mfma_f32_16x16x32_bf16 v[122:125], v[138:141], v[178:181], v[122:125]
	v_mfma_f32_16x16x32_bf16 v[42:45], v[154:157], v[178:181], v[42:45]
	v_mfma_f32_16x16x32_bf16 v[114:117], v[138:141], v[186:189], v[114:117]
	v_mfma_f32_16x16x32_bf16 v[34:37], v[154:157], v[186:189], v[34:37]
	v_mfma_f32_16x16x32_bf16 v[142:145], v[150:153], v[166:169], v[142:145]
	v_mfma_f32_16x16x32_bf16 v[58:61], v[158:161], v[166:169], v[58:61]
	v_mfma_f32_16x16x32_bf16 v[130:133], v[150:153], v[174:177], v[130:133]
	v_mfma_f32_16x16x32_bf16 v[50:53], v[158:161], v[174:177], v[50:53]
	v_mfma_f32_16x16x32_bf16 v[122:125], v[150:153], v[182:185], v[122:125]
	v_mfma_f32_16x16x32_bf16 v[42:45], v[158:161], v[182:185], v[42:45]
	v_mfma_f32_16x16x32_bf16 v[114:117], v[150:153], v[190:193], v[114:117]
	v_mfma_f32_16x16x32_bf16 v[34:37], v[158:161], v[190:193], v[34:37]
	s_setprio 0
	s_barrier
	s_add_u32 s100, s56, 0xffffc080
	s_addc_u32 s101, s57, -1
	s_add_u32 s98, s62, 0x80
	s_addc_u32 s99, s63, 0
	s_add_i32 s45, s45, s35
	s_mov_b32 m0, s45
	ds_read_b128 v[162:165], v227 offset:49152
	ds_read_b128 v[166:169], v227 offset:50176
	ds_read_b128 v[170:173], v227 offset:51200
	ds_read_b128 v[174:177], v227 offset:52224
	ds_read_b128 v[178:181], v227 offset:53248
	ds_read_b128 v[182:185], v227 offset:54272
	ds_read_b128 v[186:189], v227 offset:55296
	ds_read_b128 v[190:193], v227 offset:56320
	global_load_lds_dwordx4 v0, s[98:99]
	s_add_i32 m0, s45, 0x2000
	s_add_u32 s56, s62, 0x80080
	s_addc_u32 s57, s63, 0
	s_add_i32 s45, s55, s35
	global_load_lds_dwordx4 v208, s[98:99]
	s_mov_b32 m0, s45
	s_nop 0
	global_load_lds_dwordx4 v0, s[56:57]
	s_add_i32 m0, s45, 0x2000
	s_nop 0
	global_load_lds_dwordx4 v208, s[56:57]
	s_mov_b32 m0, s71
	s_nop 0
	global_load_lds_dwordx4 v204, s[100:101]
	s_mov_b32 m0, s74
	s_nop 0
	global_load_lds_dwordx4 v206, s[100:101]
	s_waitcnt vmcnt(8)
	s_waitcnt lgkmcnt(0)
	s_barrier
	s_setprio 1
	s_waitcnt lgkmcnt(0)
	v_mfma_f32_16x16x32_bf16 v[102:105], v[82:85], v[162:165], v[102:105]
	v_mfma_f32_16x16x32_bf16 v[30:33], v[106:109], v[162:165], v[30:33]
	v_mfma_f32_16x16x32_bf16 v[94:97], v[82:85], v[170:173], v[94:97]
	v_mfma_f32_16x16x32_bf16 v[22:25], v[106:109], v[170:173], v[22:25]
	v_mfma_f32_16x16x32_bf16 v[86:89], v[82:85], v[178:181], v[86:89]
	v_mfma_f32_16x16x32_bf16 v[14:17], v[106:109], v[178:181], v[14:17]
	v_mfma_f32_16x16x32_bf16 v[62:65], v[82:85], v[186:189], v[62:65]
	v_mfma_f32_16x16x32_bf16 v[10:13], v[106:109], v[186:189], v[10:13]
	v_mfma_f32_16x16x32_bf16 v[102:105], v[98:101], v[166:169], v[102:105]
	v_mfma_f32_16x16x32_bf16 v[30:33], v[110:113], v[166:169], v[30:33]
	v_mfma_f32_16x16x32_bf16 v[94:97], v[98:101], v[174:177], v[94:97]
	v_mfma_f32_16x16x32_bf16 v[22:25], v[110:113], v[174:177], v[22:25]
	v_mfma_f32_16x16x32_bf16 v[86:89], v[98:101], v[182:185], v[86:89]
	v_mfma_f32_16x16x32_bf16 v[14:17], v[110:113], v[182:185], v[14:17]
	v_mfma_f32_16x16x32_bf16 v[82:85], v[98:101], v[190:193], v[62:65]
	v_mfma_f32_16x16x32_bf16 v[10:13], v[110:113], v[190:193], v[10:13]
	s_setprio 0
	s_setprio 1
	v_mfma_f32_16x16x32_bf16 v[62:65], v[138:141], v[162:165], v[66:69]
	v_mfma_f32_16x16x32_bf16 v[98:101], v[150:153], v[166:169], v[62:65]
	v_mfma_f32_16x16x32_bf16 v[62:65], v[138:141], v[170:173], v[90:93]
	v_mfma_f32_16x16x32_bf16 v[90:93], v[150:153], v[174:177], v[62:65]
	v_mfma_f32_16x16x32_bf16 v[62:65], v[138:141], v[178:181], v[78:81]
	v_mfma_f32_16x16x32_bf16 v[26:29], v[154:157], v[162:165], v[26:29]
	v_mfma_f32_16x16x32_bf16 v[18:21], v[154:157], v[170:173], v[18:21]
	v_mfma_f32_16x16x32_bf16 v[78:81], v[150:153], v[182:185], v[62:65]
	v_mfma_f32_16x16x32_bf16 v[6:9], v[154:157], v[178:181], v[6:9]
	v_mfma_f32_16x16x32_bf16 v[62:65], v[138:141], v[186:189], v[74:77]
	v_mfma_f32_16x16x32_bf16 v[2:5], v[154:157], v[186:189], v[2:5]
	v_mfma_f32_16x16x32_bf16 v[26:29], v[158:161], v[166:169], v[26:29]
	v_mfma_f32_16x16x32_bf16 v[18:21], v[158:161], v[174:177], v[18:21]
	v_mfma_f32_16x16x32_bf16 v[6:9], v[158:161], v[182:185], v[6:9]
	v_mfma_f32_16x16x32_bf16 v[74:77], v[150:153], v[190:193], v[62:65]
	v_mfma_f32_16x16x32_bf16 v[2:5], v[158:161], v[190:193], v[2:5]
	s_setprio 0
	s_barrier
	s_add_i32 s44, s44, 2
	s_add_u32 s41, s41, 0x100
	s_addc_u32 s43, s43, 0
	s_cmp_gt_u32 s44, 29
	s_mov_b64 s[56:57], s[60:61]
	s_cbranch_scc0 .LBB0_1080

.LBB0_1185:
	s_add_i32 s13, s55, -2
	s_add_u32 s33, s24, 0x100
	s_addc_u32 s40, s25, 0
	s_mov_b32 s26, 0
	v_add_u32_e32 v253, 0x10000, v190
	s_add_i32 s41, s26, 2
	s_add_u32 s24, s22, 0x100
	s_addc_u32 s25, s23, 0
	s_add_i32 s44, 0, 0x10000
	s_cmp_eq_u32 s13, s26
	s_cselect_b32 s31, s15, s25
	s_cselect_b32 s30, s14, s24
	s_cselect_b32 s27, s17, s40
	s_cselect_b32 s26, s16, s33
	s_add_i32 s45, 0, 0x14000
	ds_read_b128 v[102:105], v253
	ds_read_b128 v[106:109], v253 offset:1024
	ds_read_b128 v[110:113], v253 offset:2048
	ds_read_b128 v[118:121], v253 offset:3072
	ds_read_b128 v[146:149], v253 offset:16384
	ds_read_b128 v[150:153], v253 offset:17408
	ds_read_b128 v[154:157], v253 offset:18432
	ds_read_b128 v[158:161], v253 offset:19456
	s_add_i32 m0, s34, 0xc000
	ds_read_b128 v[162:165], v192
	ds_read_b128 v[176:179], v192 offset:1024
	ds_read_b128 v[180:183], v192 offset:2048
	ds_read_b128 v[184:187], v192 offset:3072
	ds_read_b128 v[204:207], v192 offset:4096
	ds_read_b128 v[208:211], v192 offset:5120
	ds_read_b128 v[212:215], v192 offset:6144
	ds_read_b128 v[216:219], v192 offset:7168
	global_load_lds_dwordx4 v172, s[22:23]
	s_add_i32 m0, s34, 0xe000
	s_nop 0
	global_load_lds_dwordx4 v174, s[22:23]
	s_waitcnt vmcnt(8)
	s_waitcnt lgkmcnt(0)
	s_barrier
	s_setprio 1
	s_waitcnt lgkmcnt(0)
	v_mfma_f32_16x16x32_bf16 v[142:145], v[102:105], v[162:165], 0
	v_mfma_f32_16x16x32_bf16 v[138:141], v[110:113], v[162:165], 0
	v_mfma_f32_16x16x32_bf16 v[134:137], v[102:105], v[180:183], 0
	v_mfma_f32_16x16x32_bf16 v[126:129], v[110:113], v[180:183], 0
	v_mfma_f32_16x16x32_bf16 v[98:101], v[102:105], v[204:207], 0
	v_mfma_f32_16x16x32_bf16 v[90:93], v[110:113], v[204:207], 0
	v_mfma_f32_16x16x32_bf16 v[86:89], v[102:105], v[212:215], 0
	v_mfma_f32_16x16x32_bf16 v[78:81], v[110:113], v[212:215], 0
	v_mfma_f32_16x16x32_bf16 v[142:145], v[106:109], v[176:179], v[142:145]
	v_mfma_f32_16x16x32_bf16 v[138:141], v[118:121], v[176:179], v[138:141]
	v_mfma_f32_16x16x32_bf16 v[134:137], v[106:109], v[184:187], v[134:137]
	v_mfma_f32_16x16x32_bf16 v[126:129], v[118:121], v[184:187], v[126:129]
	v_mfma_f32_16x16x32_bf16 v[98:101], v[106:109], v[208:211], v[98:101]
	v_mfma_f32_16x16x32_bf16 v[90:93], v[118:121], v[208:211], v[90:93]
	v_mfma_f32_16x16x32_bf16 v[86:89], v[106:109], v[216:219], v[86:89]
	v_mfma_f32_16x16x32_bf16 v[78:81], v[118:121], v[216:219], v[78:81]
	s_setprio 0
	s_setprio 1
	v_mfma_f32_16x16x32_bf16 v[130:133], v[146:149], v[162:165], 0
	v_mfma_f32_16x16x32_bf16 v[122:125], v[154:157], v[162:165], 0
	v_mfma_f32_16x16x32_bf16 v[114:117], v[146:149], v[180:183], 0
	v_mfma_f32_16x16x32_bf16 v[94:97], v[154:157], v[180:183], 0
	v_mfma_f32_16x16x32_bf16 v[82:85], v[146:149], v[204:207], 0
	v_mfma_f32_16x16x32_bf16 v[74:77], v[154:157], v[204:207], 0
	v_mfma_f32_16x16x32_bf16 v[70:73], v[146:149], v[212:215], 0
	v_mfma_f32_16x16x32_bf16 v[66:69], v[154:157], v[212:215], 0
	v_mfma_f32_16x16x32_bf16 v[130:133], v[150:153], v[176:179], v[130:133]
	v_mfma_f32_16x16x32_bf16 v[122:125], v[158:161], v[176:179], v[122:125]
	v_mfma_f32_16x16x32_bf16 v[114:117], v[150:153], v[184:187], v[114:117]
	v_mfma_f32_16x16x32_bf16 v[94:97], v[158:161], v[184:187], v[94:97]
	v_mfma_f32_16x16x32_bf16 v[82:85], v[150:153], v[208:211], v[82:85]
	v_mfma_f32_16x16x32_bf16 v[74:77], v[158:161], v[208:211], v[74:77]
	v_mfma_f32_16x16x32_bf16 v[70:73], v[150:153], v[216:219], v[70:73]
	v_mfma_f32_16x16x32_bf16 v[66:69], v[158:161], v[216:219], v[66:69]
	s_setprio 0
	s_barrier
	s_add_i32 s22, s44, s29
	s_mov_b32 m0, s22
	ds_read_b128 v[162:165], v192 offset:16384
	ds_read_b128 v[176:179], v192 offset:17408
	ds_read_b128 v[180:183], v192 offset:18432
	ds_read_b128 v[184:187], v192 offset:19456
	ds_read_b128 v[204:207], v192 offset:20480
	ds_read_b128 v[208:211], v192 offset:21504
	ds_read_b128 v[212:215], v192 offset:22528
	ds_read_b128 v[216:219], v192 offset:23552
	global_load_lds_dwordx4 v0, s[26:27]
	s_add_i32 m0, s22, 0x2000
	s_add_u32 s22, s26, 0x160000
	s_addc_u32 s23, s27, 0
	s_add_i32 s44, s45, s29
	global_load_lds_dwordx4 v170, s[26:27]
	s_mov_b32 m0, s44
	s_nop 0
	global_load_lds_dwordx4 v0, s[22:23]
	s_add_i32 m0, s44, 0x2000
	s_nop 0
	global_load_lds_dwordx4 v170, s[22:23]
	s_mov_b32 m0, s34
	s_nop 0
	global_load_lds_dwordx4 v166, s[30:31]
	s_mov_b32 m0, s35
	s_nop 0
	global_load_lds_dwordx4 v168, s[30:31]
	s_waitcnt vmcnt(8)
	s_waitcnt lgkmcnt(0)
	s_barrier
	s_setprio 1
	s_waitcnt lgkmcnt(0)
	v_mfma_f32_16x16x32_bf16 v[62:65], v[102:105], v[162:165], 0
	v_mfma_f32_16x16x32_bf16 v[58:61], v[110:113], v[162:165], 0
	v_mfma_f32_16x16x32_bf16 v[50:53], v[102:105], v[180:183], 0
	v_mfma_f32_16x16x32_bf16 v[42:45], v[110:113], v[180:183], 0
	v_mfma_f32_16x16x32_bf16 v[34:37], v[102:105], v[204:207], 0
	v_mfma_f32_16x16x32_bf16 v[26:29], v[110:113], v[204:207], 0
	v_mfma_f32_16x16x32_bf16 v[18:21], v[102:105], v[212:215], 0
	v_mfma_f32_16x16x32_bf16 v[10:13], v[110:113], v[212:215], 0
	v_mfma_f32_16x16x32_bf16 v[62:65], v[106:109], v[176:179], v[62:65]
	v_mfma_f32_16x16x32_bf16 v[58:61], v[118:121], v[176:179], v[58:61]
	v_mfma_f32_16x16x32_bf16 v[50:53], v[106:109], v[184:187], v[50:53]
	v_mfma_f32_16x16x32_bf16 v[42:45], v[118:121], v[184:187], v[42:45]
	v_mfma_f32_16x16x32_bf16 v[34:37], v[106:109], v[208:211], v[34:37]
	v_mfma_f32_16x16x32_bf16 v[26:29], v[118:121], v[208:211], v[26:29]
	v_mfma_f32_16x16x32_bf16 v[18:21], v[106:109], v[216:219], v[18:21]
	v_mfma_f32_16x16x32_bf16 v[10:13], v[118:121], v[216:219], v[10:13]
	s_setprio 0
	s_setprio 1
	v_mfma_f32_16x16x32_bf16 v[54:57], v[146:149], v[162:165], 0
	v_mfma_f32_16x16x32_bf16 v[46:49], v[154:157], v[162:165], 0
	v_mfma_f32_16x16x32_bf16 v[38:41], v[146:149], v[180:183], 0
	v_mfma_f32_16x16x32_bf16 v[30:33], v[154:157], v[180:183], 0
	v_mfma_f32_16x16x32_bf16 v[22:25], v[146:149], v[204:207], 0
	v_mfma_f32_16x16x32_bf16 v[14:17], v[154:157], v[204:207], 0
	v_mfma_f32_16x16x32_bf16 v[6:9], v[146:149], v[212:215], 0
	v_mfma_f32_16x16x32_bf16 v[2:5], v[154:157], v[212:215], 0
	v_mfma_f32_16x16x32_bf16 v[54:57], v[150:153], v[176:179], v[54:57]
	v_mfma_f32_16x16x32_bf16 v[46:49], v[158:161], v[176:179], v[46:49]
	v_mfma_f32_16x16x32_bf16 v[38:41], v[150:153], v[184:187], v[38:41]
	v_mfma_f32_16x16x32_bf16 v[30:33], v[158:161], v[184:187], v[30:33]
	v_mfma_f32_16x16x32_bf16 v[22:25], v[150:153], v[208:211], v[22:25]
	v_mfma_f32_16x16x32_bf16 v[14:17], v[158:161], v[208:211], v[14:17]
	v_mfma_f32_16x16x32_bf16 v[6:9], v[150:153], v[216:219], v[6:9]
	v_mfma_f32_16x16x32_bf16 v[2:5], v[158:161], v[216:219], v[2:5]
	s_setprio 0
	s_barrier
	s_nop 0
	s_add_i32 s44, 0, 0x18000
	s_add_i32 s45, 0, 0x1c000
	ds_read_b128 v[102:105], v253 offset:32768
	ds_read_b128 v[106:109], v253 offset:33792
	ds_read_b128 v[110:113], v253 offset:34816
	ds_read_b128 v[118:121], v253 offset:35840
	ds_read_b128 v[146:149], v253 offset:49152
	ds_read_b128 v[150:153], v253 offset:50176
	ds_read_b128 v[154:157], v253 offset:51200
	ds_read_b128 v[158:161], v253 offset:52224
	s_add_u32 s22, s30, 0x160000
	s_addc_u32 s23, s31, 0
	s_mov_b32 m0, s36
	ds_read_b128 v[162:165], v192 offset:32768
	ds_read_b128 v[176:179], v192 offset:33792
	ds_read_b128 v[180:183], v192 offset:34816
	ds_read_b128 v[184:187], v192 offset:35840
	ds_read_b128 v[204:207], v192 offset:36864
	ds_read_b128 v[208:211], v192 offset:37888
	ds_read_b128 v[212:215], v192 offset:38912
	ds_read_b128 v[216:219], v192 offset:39936
	global_load_lds_dwordx4 v166, s[22:23]
	s_mov_b32 m0, s37
	s_nop 0
	global_load_lds_dwordx4 v168, s[22:23]
	s_waitcnt vmcnt(8)
	s_waitcnt lgkmcnt(0)
	s_barrier
	s_setprio 1
	s_waitcnt lgkmcnt(0)
	v_mfma_f32_16x16x32_bf16 v[142:145], v[102:105], v[162:165], v[142:145]
	v_mfma_f32_16x16x32_bf16 v[138:141], v[110:113], v[162:165], v[138:141]
	v_mfma_f32_16x16x32_bf16 v[134:137], v[102:105], v[180:183], v[134:137]
	v_mfma_f32_16x16x32_bf16 v[126:129], v[110:113], v[180:183], v[126:129]
	v_mfma_f32_16x16x32_bf16 v[98:101], v[102:105], v[204:207], v[98:101]
	v_mfma_f32_16x16x32_bf16 v[90:93], v[110:113], v[204:207], v[90:93]
	v_mfma_f32_16x16x32_bf16 v[86:89], v[102:105], v[212:215], v[86:89]
	v_mfma_f32_16x16x32_bf16 v[78:81], v[110:113], v[212:215], v[78:81]
	v_mfma_f32_16x16x32_bf16 v[142:145], v[106:109], v[176:179], v[142:145]
	v_mfma_f32_16x16x32_bf16 v[138:141], v[118:121], v[176:179], v[138:141]
	v_mfma_f32_16x16x32_bf16 v[134:137], v[106:109], v[184:187], v[134:137]
	v_mfma_f32_16x16x32_bf16 v[126:129], v[118:121], v[184:187], v[126:129]
	v_mfma_f32_16x16x32_bf16 v[98:101], v[106:109], v[208:211], v[98:101]
	v_mfma_f32_16x16x32_bf16 v[90:93], v[118:121], v[208:211], v[90:93]
	v_mfma_f32_16x16x32_bf16 v[86:89], v[106:109], v[216:219], v[86:89]
	v_mfma_f32_16x16x32_bf16 v[78:81], v[118:121], v[216:219], v[78:81]
	s_setprio 0
	s_setprio 1
	v_mfma_f32_16x16x32_bf16 v[130:133], v[146:149], v[162:165], v[130:133]
	v_mfma_f32_16x16x32_bf16 v[122:125], v[154:157], v[162:165], v[122:125]
	v_mfma_f32_16x16x32_bf16 v[114:117], v[146:149], v[180:183], v[114:117]
	v_mfma_f32_16x16x32_bf16 v[94:97], v[154:157], v[180:183], v[94:97]
	v_mfma_f32_16x16x32_bf16 v[82:85], v[146:149], v[204:207], v[82:85]
	v_mfma_f32_16x16x32_bf16 v[74:77], v[154:157], v[204:207], v[74:77]
	v_mfma_f32_16x16x32_bf16 v[70:73], v[146:149], v[212:215], v[70:73]
	v_mfma_f32_16x16x32_bf16 v[66:69], v[154:157], v[212:215], v[66:69]
	v_mfma_f32_16x16x32_bf16 v[130:133], v[150:153], v[176:179], v[130:133]
	v_mfma_f32_16x16x32_bf16 v[122:125], v[158:161], v[176:179], v[122:125]
	v_mfma_f32_16x16x32_bf16 v[114:117], v[150:153], v[184:187], v[114:117]
	v_mfma_f32_16x16x32_bf16 v[94:97], v[158:161], v[184:187], v[94:97]
	v_mfma_f32_16x16x32_bf16 v[82:85], v[150:153], v[208:211], v[82:85]
	v_mfma_f32_16x16x32_bf16 v[74:77], v[158:161], v[208:211], v[74:77]
	v_mfma_f32_16x16x32_bf16 v[70:73], v[150:153], v[216:219], v[70:73]
	v_mfma_f32_16x16x32_bf16 v[66:69], v[158:161], v[216:219], v[66:69]
	s_setprio 0
	s_barrier
	s_add_u32 s100, s22, 0xffea0080
	s_addc_u32 s101, s23, -1
	s_add_u32 s98, s26, 0x80
	s_addc_u32 s99, s27, 0
	s_add_i32 s22, s44, s29
	s_mov_b32 m0, s22
	ds_read_b128 v[162:165], v192 offset:49152
	ds_read_b128 v[176:179], v192 offset:50176
	ds_read_b128 v[180:183], v192 offset:51200
	ds_read_b128 v[184:187], v192 offset:52224
	ds_read_b128 v[204:207], v192 offset:53248
	ds_read_b128 v[208:211], v192 offset:54272
	ds_read_b128 v[212:215], v192 offset:55296
	ds_read_b128 v[216:219], v192 offset:56320
	global_load_lds_dwordx4 v0, s[98:99]
	s_add_i32 m0, s22, 0x2000
	s_add_u32 s22, s26, 0x160080
	s_addc_u32 s23, s27, 0
	s_add_i32 s26, s45, s29
	global_load_lds_dwordx4 v170, s[98:99]
	s_mov_b32 m0, s26
	s_nop 0
	global_load_lds_dwordx4 v0, s[22:23]
	s_add_i32 m0, s26, 0x2000
	s_nop 0
	global_load_lds_dwordx4 v170, s[22:23]
	s_mov_b32 m0, s42
	s_nop 0
	global_load_lds_dwordx4 v166, s[100:101]
	s_mov_b32 m0, s43
	s_nop 0
	global_load_lds_dwordx4 v168, s[100:101]
	s_waitcnt vmcnt(8)
	s_waitcnt lgkmcnt(0)
	s_barrier
	s_setprio 1
	s_waitcnt lgkmcnt(0)
	v_mfma_f32_16x16x32_bf16 v[62:65], v[102:105], v[162:165], v[62:65]
	v_mfma_f32_16x16x32_bf16 v[58:61], v[110:113], v[162:165], v[58:61]
	v_mfma_f32_16x16x32_bf16 v[50:53], v[102:105], v[180:183], v[50:53]
	v_mfma_f32_16x16x32_bf16 v[42:45], v[110:113], v[180:183], v[42:45]
	v_mfma_f32_16x16x32_bf16 v[34:37], v[102:105], v[204:207], v[34:37]
	v_mfma_f32_16x16x32_bf16 v[26:29], v[110:113], v[204:207], v[26:29]
	v_mfma_f32_16x16x32_bf16 v[18:21], v[102:105], v[212:215], v[18:21]
	v_mfma_f32_16x16x32_bf16 v[10:13], v[110:113], v[212:215], v[10:13]
	v_mfma_f32_16x16x32_bf16 v[62:65], v[106:109], v[176:179], v[62:65]
	v_mfma_f32_16x16x32_bf16 v[58:61], v[118:121], v[176:179], v[58:61]
	v_mfma_f32_16x16x32_bf16 v[50:53], v[106:109], v[184:187], v[50:53]
	v_mfma_f32_16x16x32_bf16 v[42:45], v[118:121], v[184:187], v[42:45]
	v_mfma_f32_16x16x32_bf16 v[34:37], v[106:109], v[208:211], v[34:37]
	v_mfma_f32_16x16x32_bf16 v[26:29], v[118:121], v[208:211], v[26:29]
	v_mfma_f32_16x16x32_bf16 v[18:21], v[106:109], v[216:219], v[18:21]
	v_mfma_f32_16x16x32_bf16 v[10:13], v[118:121], v[216:219], v[10:13]
	s_setprio 0
	s_setprio 1
	v_mfma_f32_16x16x32_bf16 v[54:57], v[146:149], v[162:165], v[54:57]
	v_mfma_f32_16x16x32_bf16 v[46:49], v[154:157], v[162:165], v[46:49]
	v_mfma_f32_16x16x32_bf16 v[38:41], v[146:149], v[180:183], v[38:41]
	v_mfma_f32_16x16x32_bf16 v[30:33], v[154:157], v[180:183], v[30:33]
	v_mfma_f32_16x16x32_bf16 v[22:25], v[146:149], v[204:207], v[22:25]
	v_mfma_f32_16x16x32_bf16 v[14:17], v[154:157], v[204:207], v[14:17]
	v_mfma_f32_16x16x32_bf16 v[6:9], v[146:149], v[212:215], v[6:9]
	v_mfma_f32_16x16x32_bf16 v[2:5], v[154:157], v[212:215], v[2:5]
	v_mfma_f32_16x16x32_bf16 v[54:57], v[150:153], v[176:179], v[54:57]
	v_mfma_f32_16x16x32_bf16 v[46:49], v[158:161], v[176:179], v[46:49]
	v_mfma_f32_16x16x32_bf16 v[38:41], v[150:153], v[184:187], v[38:41]
	v_mfma_f32_16x16x32_bf16 v[30:33], v[158:161], v[184:187], v[30:33]
	v_mfma_f32_16x16x32_bf16 v[22:25], v[150:153], v[208:211], v[22:25]
	v_mfma_f32_16x16x32_bf16 v[14:17], v[158:161], v[208:211], v[14:17]
	v_mfma_f32_16x16x32_bf16 v[6:9], v[150:153], v[216:219], v[6:9]
	v_mfma_f32_16x16x32_bf16 v[2:5], v[158:161], v[216:219], v[2:5]
	s_setprio 0
	s_barrier
	s_add_u32 s33, s33, 0x100
	s_addc_u32 s40, s40, 0
	s_cmp_ge_u32 s41, s55
	s_mov_b64 s[22:23], s[24:25]
	s_mov_b32 s26, s41
	s_cbranch_scc0 .LBB0_1186
	s_branch .Lpeel_exit_5
.LBB0_1186:
	s_nop 0
	s_add_i32 s41, s26, 2
	s_add_u32 s24, s22, 0x100
	s_addc_u32 s25, s23, 0
	s_add_i32 s44, 0, 0x10000
	s_cmp_eq_u32 s13, s26
	s_cselect_b32 s31, s15, s25
	s_cselect_b32 s30, s14, s24
	s_cselect_b32 s27, s17, s40
	s_cselect_b32 s26, s16, s33
	s_add_i32 s45, 0, 0x14000
	ds_read_b128 v[102:105], v253
	ds_read_b128 v[106:109], v253 offset:1024
	ds_read_b128 v[110:113], v253 offset:2048
	ds_read_b128 v[118:121], v253 offset:3072
	ds_read_b128 v[146:149], v253 offset:16384
	ds_read_b128 v[150:153], v253 offset:17408
	ds_read_b128 v[154:157], v253 offset:18432
	ds_read_b128 v[158:161], v253 offset:19456
	s_add_i32 m0, s34, 0xc000
	ds_read_b128 v[162:165], v192
	ds_read_b128 v[176:179], v192 offset:1024
	ds_read_b128 v[180:183], v192 offset:2048
	ds_read_b128 v[184:187], v192 offset:3072
	ds_read_b128 v[204:207], v192 offset:4096
	ds_read_b128 v[208:211], v192 offset:5120
	ds_read_b128 v[212:215], v192 offset:6144
	ds_read_b128 v[216:219], v192 offset:7168
	global_load_lds_dwordx4 v172, s[22:23]
	s_add_i32 m0, s34, 0xe000
	s_nop 0
	global_load_lds_dwordx4 v174, s[22:23]
	s_waitcnt vmcnt(8)
	s_waitcnt lgkmcnt(0)
	s_barrier
	s_setprio 1
	s_waitcnt lgkmcnt(0)
	v_mfma_f32_16x16x32_bf16 v[142:145], v[102:105], v[162:165], v[142:145]
	v_mfma_f32_16x16x32_bf16 v[138:141], v[110:113], v[162:165], v[138:141]
	v_mfma_f32_16x16x32_bf16 v[134:137], v[102:105], v[180:183], v[134:137]
	v_mfma_f32_16x16x32_bf16 v[126:129], v[110:113], v[180:183], v[126:129]
	v_mfma_f32_16x16x32_bf16 v[98:101], v[102:105], v[204:207], v[98:101]
	v_mfma_f32_16x16x32_bf16 v[90:93], v[110:113], v[204:207], v[90:93]
	v_mfma_f32_16x16x32_bf16 v[86:89], v[102:105], v[212:215], v[86:89]
	v_mfma_f32_16x16x32_bf16 v[78:81], v[110:113], v[212:215], v[78:81]
	v_mfma_f32_16x16x32_bf16 v[142:145], v[106:109], v[176:179], v[142:145]
	v_mfma_f32_16x16x32_bf16 v[138:141], v[118:121], v[176:179], v[138:141]
	v_mfma_f32_16x16x32_bf16 v[134:137], v[106:109], v[184:187], v[134:137]
	v_mfma_f32_16x16x32_bf16 v[126:129], v[118:121], v[184:187], v[126:129]
	v_mfma_f32_16x16x32_bf16 v[98:101], v[106:109], v[208:211], v[98:101]
	v_mfma_f32_16x16x32_bf16 v[90:93], v[118:121], v[208:211], v[90:93]
	v_mfma_f32_16x16x32_bf16 v[86:89], v[106:109], v[216:219], v[86:89]
	v_mfma_f32_16x16x32_bf16 v[78:81], v[118:121], v[216:219], v[78:81]
	s_setprio 0
	s_setprio 1
	v_mfma_f32_16x16x32_bf16 v[130:133], v[146:149], v[162:165], v[130:133]
	v_mfma_f32_16x16x32_bf16 v[122:125], v[154:157], v[162:165], v[122:125]
	v_mfma_f32_16x16x32_bf16 v[114:117], v[146:149], v[180:183], v[114:117]
	v_mfma_f32_16x16x32_bf16 v[94:97], v[154:157], v[180:183], v[94:97]
	v_mfma_f32_16x16x32_bf16 v[82:85], v[146:149], v[204:207], v[82:85]
	v_mfma_f32_16x16x32_bf16 v[74:77], v[154:157], v[204:207], v[74:77]
	v_mfma_f32_16x16x32_bf16 v[70:73], v[146:149], v[212:215], v[70:73]
	v_mfma_f32_16x16x32_bf16 v[66:69], v[154:157], v[212:215], v[66:69]
	v_mfma_f32_16x16x32_bf16 v[130:133], v[150:153], v[176:179], v[130:133]
	v_mfma_f32_16x16x32_bf16 v[122:125], v[158:161], v[176:179], v[122:125]
	v_mfma_f32_16x16x32_bf16 v[114:117], v[150:153], v[184:187], v[114:117]
	v_mfma_f32_16x16x32_bf16 v[94:97], v[158:161], v[184:187], v[94:97]
	v_mfma_f32_16x16x32_bf16 v[82:85], v[150:153], v[208:211], v[82:85]
	v_mfma_f32_16x16x32_bf16 v[74:77], v[158:161], v[208:211], v[74:77]
	v_mfma_f32_16x16x32_bf16 v[70:73], v[150:153], v[216:219], v[70:73]
	v_mfma_f32_16x16x32_bf16 v[66:69], v[158:161], v[216:219], v[66:69]
	s_setprio 0
	s_barrier
	s_add_i32 s22, s44, s29
	s_mov_b32 m0, s22
	ds_read_b128 v[162:165], v192 offset:16384
	ds_read_b128 v[176:179], v192 offset:17408
	ds_read_b128 v[180:183], v192 offset:18432
	ds_read_b128 v[184:187], v192 offset:19456
	ds_read_b128 v[204:207], v192 offset:20480
	ds_read_b128 v[208:211], v192 offset:21504
	ds_read_b128 v[212:215], v192 offset:22528
	ds_read_b128 v[216:219], v192 offset:23552
	global_load_lds_dwordx4 v0, s[26:27]
	s_add_i32 m0, s22, 0x2000
	s_add_u32 s22, s26, 0x160000
	s_addc_u32 s23, s27, 0
	s_add_i32 s44, s45, s29
	global_load_lds_dwordx4 v170, s[26:27]
	s_mov_b32 m0, s44
	s_nop 0
	global_load_lds_dwordx4 v0, s[22:23]
	s_add_i32 m0, s44, 0x2000
	s_nop 0
	global_load_lds_dwordx4 v170, s[22:23]
	s_mov_b32 m0, s34
	s_nop 0
	global_load_lds_dwordx4 v166, s[30:31]
	s_mov_b32 m0, s35
	s_nop 0
	global_load_lds_dwordx4 v168, s[30:31]
	s_waitcnt vmcnt(8)
	s_waitcnt lgkmcnt(0)
	s_barrier
	s_setprio 1
	s_waitcnt lgkmcnt(0)
	v_mfma_f32_16x16x32_bf16 v[62:65], v[102:105], v[162:165], v[62:65]
	v_mfma_f32_16x16x32_bf16 v[58:61], v[110:113], v[162:165], v[58:61]
	v_mfma_f32_16x16x32_bf16 v[50:53], v[102:105], v[180:183], v[50:53]
	v_mfma_f32_16x16x32_bf16 v[42:45], v[110:113], v[180:183], v[42:45]
	v_mfma_f32_16x16x32_bf16 v[34:37], v[102:105], v[204:207], v[34:37]
	v_mfma_f32_16x16x32_bf16 v[26:29], v[110:113], v[204:207], v[26:29]
	v_mfma_f32_16x16x32_bf16 v[18:21], v[102:105], v[212:215], v[18:21]
	v_mfma_f32_16x16x32_bf16 v[10:13], v[110:113], v[212:215], v[10:13]
	v_mfma_f32_16x16x32_bf16 v[62:65], v[106:109], v[176:179], v[62:65]
	v_mfma_f32_16x16x32_bf16 v[58:61], v[118:121], v[176:179], v[58:61]
	v_mfma_f32_16x16x32_bf16 v[50:53], v[106:109], v[184:187], v[50:53]
	v_mfma_f32_16x16x32_bf16 v[42:45], v[118:121], v[184:187], v[42:45]
	v_mfma_f32_16x16x32_bf16 v[34:37], v[106:109], v[208:211], v[34:37]
	v_mfma_f32_16x16x32_bf16 v[26:29], v[118:121], v[208:211], v[26:29]
	v_mfma_f32_16x16x32_bf16 v[18:21], v[106:109], v[216:219], v[18:21]
	v_mfma_f32_16x16x32_bf16 v[10:13], v[118:121], v[216:219], v[10:13]
	s_setprio 0
	s_setprio 1
	v_mfma_f32_16x16x32_bf16 v[54:57], v[146:149], v[162:165], v[54:57]
	v_mfma_f32_16x16x32_bf16 v[46:49], v[154:157], v[162:165], v[46:49]
	v_mfma_f32_16x16x32_bf16 v[38:41], v[146:149], v[180:183], v[38:41]
	v_mfma_f32_16x16x32_bf16 v[30:33], v[154:157], v[180:183], v[30:33]
	v_mfma_f32_16x16x32_bf16 v[22:25], v[146:149], v[204:207], v[22:25]
	v_mfma_f32_16x16x32_bf16 v[14:17], v[154:157], v[204:207], v[14:17]
	v_mfma_f32_16x16x32_bf16 v[6:9], v[146:149], v[212:215], v[6:9]
	v_mfma_f32_16x16x32_bf16 v[2:5], v[154:157], v[212:215], v[2:5]
	v_mfma_f32_16x16x32_bf16 v[54:57], v[150:153], v[176:179], v[54:57]
	v_mfma_f32_16x16x32_bf16 v[46:49], v[158:161], v[176:179], v[46:49]
	v_mfma_f32_16x16x32_bf16 v[38:41], v[150:153], v[184:187], v[38:41]
	v_mfma_f32_16x16x32_bf16 v[30:33], v[158:161], v[184:187], v[30:33]
	v_mfma_f32_16x16x32_bf16 v[22:25], v[150:153], v[208:211], v[22:25]
	v_mfma_f32_16x16x32_bf16 v[14:17], v[158:161], v[208:211], v[14:17]
	v_mfma_f32_16x16x32_bf16 v[6:9], v[150:153], v[216:219], v[6:9]
	v_mfma_f32_16x16x32_bf16 v[2:5], v[158:161], v[216:219], v[2:5]
	s_setprio 0
	s_barrier
	s_nop 0
	s_add_i32 s44, 0, 0x18000
	s_add_i32 s45, 0, 0x1c000
	ds_read_b128 v[102:105], v253 offset:32768
	ds_read_b128 v[106:109], v253 offset:33792
	ds_read_b128 v[110:113], v253 offset:34816
	ds_read_b128 v[118:121], v253 offset:35840
	ds_read_b128 v[146:149], v253 offset:49152
	ds_read_b128 v[150:153], v253 offset:50176
	ds_read_b128 v[154:157], v253 offset:51200
	ds_read_b128 v[158:161], v253 offset:52224
	s_add_u32 s22, s30, 0x160000
	s_addc_u32 s23, s31, 0
	s_mov_b32 m0, s36
	ds_read_b128 v[162:165], v192 offset:32768
	ds_read_b128 v[176:179], v192 offset:33792
	ds_read_b128 v[180:183], v192 offset:34816
	ds_read_b128 v[184:187], v192 offset:35840
	ds_read_b128 v[204:207], v192 offset:36864
	ds_read_b128 v[208:211], v192 offset:37888
	ds_read_b128 v[212:215], v192 offset:38912
	ds_read_b128 v[216:219], v192 offset:39936
	global_load_lds_dwordx4 v166, s[22:23]
	s_mov_b32 m0, s37
	s_nop 0
	global_load_lds_dwordx4 v168, s[22:23]
	s_waitcnt vmcnt(8)
	s_waitcnt lgkmcnt(0)
	s_barrier
	s_setprio 1
	s_waitcnt lgkmcnt(0)
	v_mfma_f32_16x16x32_bf16 v[142:145], v[102:105], v[162:165], v[142:145]
	v_mfma_f32_16x16x32_bf16 v[138:141], v[110:113], v[162:165], v[138:141]
	v_mfma_f32_16x16x32_bf16 v[134:137], v[102:105], v[180:183], v[134:137]
	v_mfma_f32_16x16x32_bf16 v[126:129], v[110:113], v[180:183], v[126:129]
	v_mfma_f32_16x16x32_bf16 v[98:101], v[102:105], v[204:207], v[98:101]
	v_mfma_f32_16x16x32_bf16 v[90:93], v[110:113], v[204:207], v[90:93]
	v_mfma_f32_16x16x32_bf16 v[86:89], v[102:105], v[212:215], v[86:89]
	v_mfma_f32_16x16x32_bf16 v[78:81], v[110:113], v[212:215], v[78:81]
	v_mfma_f32_16x16x32_bf16 v[142:145], v[106:109], v[176:179], v[142:145]
	v_mfma_f32_16x16x32_bf16 v[138:141], v[118:121], v[176:179], v[138:141]
	v_mfma_f32_16x16x32_bf16 v[134:137], v[106:109], v[184:187], v[134:137]
	v_mfma_f32_16x16x32_bf16 v[126:129], v[118:121], v[184:187], v[126:129]
	v_mfma_f32_16x16x32_bf16 v[98:101], v[106:109], v[208:211], v[98:101]
	v_mfma_f32_16x16x32_bf16 v[90:93], v[118:121], v[208:211], v[90:93]
	v_mfma_f32_16x16x32_bf16 v[86:89], v[106:109], v[216:219], v[86:89]
	v_mfma_f32_16x16x32_bf16 v[78:81], v[118:121], v[216:219], v[78:81]
	s_setprio 0
	s_setprio 1
	v_mfma_f32_16x16x32_bf16 v[130:133], v[146:149], v[162:165], v[130:133]
	v_mfma_f32_16x16x32_bf16 v[122:125], v[154:157], v[162:165], v[122:125]
	v_mfma_f32_16x16x32_bf16 v[114:117], v[146:149], v[180:183], v[114:117]
	v_mfma_f32_16x16x32_bf16 v[94:97], v[154:157], v[180:183], v[94:97]
	v_mfma_f32_16x16x32_bf16 v[82:85], v[146:149], v[204:207], v[82:85]
	v_mfma_f32_16x16x32_bf16 v[74:77], v[154:157], v[204:207], v[74:77]
	v_mfma_f32_16x16x32_bf16 v[70:73], v[146:149], v[212:215], v[70:73]
	v_mfma_f32_16x16x32_bf16 v[66:69], v[154:157], v[212:215], v[66:69]
	v_mfma_f32_16x16x32_bf16 v[130:133], v[150:153], v[176:179], v[130:133]
	v_mfma_f32_16x16x32_bf16 v[122:125], v[158:161], v[176:179], v[122:125]
	v_mfma_f32_16x16x32_bf16 v[114:117], v[150:153], v[184:187], v[114:117]
	v_mfma_f32_16x16x32_bf16 v[94:97], v[158:161], v[184:187], v[94:97]
	v_mfma_f32_16x16x32_bf16 v[82:85], v[150:153], v[208:211], v[82:85]
	v_mfma_f32_16x16x32_bf16 v[74:77], v[158:161], v[208:211], v[74:77]
	v_mfma_f32_16x16x32_bf16 v[70:73], v[150:153], v[216:219], v[70:73]
	v_mfma_f32_16x16x32_bf16 v[66:69], v[158:161], v[216:219], v[66:69]
	s_setprio 0
	s_barrier
	s_add_u32 s100, s22, 0xffea0080
	s_addc_u32 s101, s23, -1
	s_add_u32 s98, s26, 0x80
	s_addc_u32 s99, s27, 0
	s_add_i32 s22, s44, s29
	s_mov_b32 m0, s22
	ds_read_b128 v[162:165], v192 offset:49152
	ds_read_b128 v[176:179], v192 offset:50176
	ds_read_b128 v[180:183], v192 offset:51200
	ds_read_b128 v[184:187], v192 offset:52224
	ds_read_b128 v[204:207], v192 offset:53248
	ds_read_b128 v[208:211], v192 offset:54272
	ds_read_b128 v[212:215], v192 offset:55296
	ds_read_b128 v[216:219], v192 offset:56320
	global_load_lds_dwordx4 v0, s[98:99]
	s_add_i32 m0, s22, 0x2000
	s_add_u32 s22, s26, 0x160080
	s_addc_u32 s23, s27, 0
	s_add_i32 s26, s45, s29
	global_load_lds_dwordx4 v170, s[98:99]
	s_mov_b32 m0, s26
	s_nop 0
	global_load_lds_dwordx4 v0, s[22:23]
	s_add_i32 m0, s26, 0x2000
	s_nop 0
	global_load_lds_dwordx4 v170, s[22:23]
	s_mov_b32 m0, s42
	s_nop 0
	global_load_lds_dwordx4 v166, s[100:101]
	s_mov_b32 m0, s43
	s_nop 0
	global_load_lds_dwordx4 v168, s[100:101]
	s_waitcnt vmcnt(8)
	s_waitcnt lgkmcnt(0)
	s_barrier
	s_setprio 1
	s_waitcnt lgkmcnt(0)
	v_mfma_f32_16x16x32_bf16 v[62:65], v[102:105], v[162:165], v[62:65]
	v_mfma_f32_16x16x32_bf16 v[58:61], v[110:113], v[162:165], v[58:61]
	v_mfma_f32_16x16x32_bf16 v[50:53], v[102:105], v[180:183], v[50:53]
	v_mfma_f32_16x16x32_bf16 v[42:45], v[110:113], v[180:183], v[42:45]
	v_mfma_f32_16x16x32_bf16 v[34:37], v[102:105], v[204:207], v[34:37]
	v_mfma_f32_16x16x32_bf16 v[26:29], v[110:113], v[204:207], v[26:29]
	v_mfma_f32_16x16x32_bf16 v[18:21], v[102:105], v[212:215], v[18:21]
	v_mfma_f32_16x16x32_bf16 v[10:13], v[110:113], v[212:215], v[10:13]
	v_mfma_f32_16x16x32_bf16 v[62:65], v[106:109], v[176:179], v[62:65]
	v_mfma_f32_16x16x32_bf16 v[58:61], v[118:121], v[176:179], v[58:61]
	v_mfma_f32_16x16x32_bf16 v[50:53], v[106:109], v[184:187], v[50:53]
	v_mfma_f32_16x16x32_bf16 v[42:45], v[118:121], v[184:187], v[42:45]
	v_mfma_f32_16x16x32_bf16 v[34:37], v[106:109], v[208:211], v[34:37]
	v_mfma_f32_16x16x32_bf16 v[26:29], v[118:121], v[208:211], v[26:29]
	v_mfma_f32_16x16x32_bf16 v[18:21], v[106:109], v[216:219], v[18:21]
	v_mfma_f32_16x16x32_bf16 v[10:13], v[118:121], v[216:219], v[10:13]
	s_setprio 0
	s_setprio 1
	v_mfma_f32_16x16x32_bf16 v[54:57], v[146:149], v[162:165], v[54:57]
	v_mfma_f32_16x16x32_bf16 v[46:49], v[154:157], v[162:165], v[46:49]
	v_mfma_f32_16x16x32_bf16 v[38:41], v[146:149], v[180:183], v[38:41]
	v_mfma_f32_16x16x32_bf16 v[30:33], v[154:157], v[180:183], v[30:33]
	v_mfma_f32_16x16x32_bf16 v[22:25], v[146:149], v[204:207], v[22:25]
	v_mfma_f32_16x16x32_bf16 v[14:17], v[154:157], v[204:207], v[14:17]
	v_mfma_f32_16x16x32_bf16 v[6:9], v[146:149], v[212:215], v[6:9]
	v_mfma_f32_16x16x32_bf16 v[2:5], v[154:157], v[212:215], v[2:5]
	v_mfma_f32_16x16x32_bf16 v[54:57], v[150:153], v[176:179], v[54:57]
	v_mfma_f32_16x16x32_bf16 v[46:49], v[158:161], v[176:179], v[46:49]
	v_mfma_f32_16x16x32_bf16 v[38:41], v[150:153], v[184:187], v[38:41]
	v_mfma_f32_16x16x32_bf16 v[30:33], v[158:161], v[184:187], v[30:33]
	v_mfma_f32_16x16x32_bf16 v[22:25], v[150:153], v[208:211], v[22:25]
	v_mfma_f32_16x16x32_bf16 v[14:17], v[158:161], v[208:211], v[14:17]
	v_mfma_f32_16x16x32_bf16 v[6:9], v[150:153], v[216:219], v[6:9]
	v_mfma_f32_16x16x32_bf16 v[2:5], v[158:161], v[216:219], v[2:5]
	s_setprio 0
	s_barrier
	s_add_u32 s33, s33, 0x100
	s_addc_u32 s40, s40, 0
	s_cmp_ge_u32 s41, s55
	s_mov_b64 s[22:23], s[24:25]
	s_mov_b32 s26, s41
	s_cbranch_scc0 .LBB0_1186
